# fft pass loops: 8-byte LDS reads/writes (ds_read_b64/ds_write_b64) instead of read2/write2 pairs
# speedup vs baseline: 1.0160x; 1.0021x over previous
; #define LAS __attribute__((address_space(3)))
; __device__ __forceinline__ f32x2 cmul(f32x2 a, f32x2 b) { return (f32x2){a.x * b.x - a.y * b.y, a.x * b.y + a.y * b.x}; }
; __device__ __forceinline__ f32x2 tw32k(const LAS f32x2* TH, const LAS f32x2* TL, int n) { return cmul(TH[n >> 7], TL[n & 127]); }
; template <bool INV> __device__ __forceinline__ void dft16(f32x2 (&x)[16]) {
; #pragma unroll
;     for (int b = 0; b < 4; ++b) r4<INV>(x[b], x[4 + b], x[8 + b], x[12 + b]);
;     const float sg = INV ? -1.f : 1.f;
;     const f32x2 W1 = {0.92387953251f, -0.38268343236f * sg}, W2 = {0.70710678118f, -0.70710678118f * sg}, W3 = {0.38268343236f, -0.92387953251f * sg},
;                 W4 = {0.f, -1.f * sg}, W6 = {-0.70710678118f, -0.70710678118f * sg}, W9 = {-0.92387953251f, 0.38268343236f * sg};
;     x[5] = cmul(x[5], W1); x[9] = cmul(x[9], W2); x[13] = cmul(x[13], W3);
;     x[6] = cmul(x[6], W2); x[10] = cmul(x[10], W4); x[14] = cmul(x[14], W6);
;     x[7] = cmul(x[7], W3); x[11] = cmul(x[11], W6); x[15] = cmul(x[15], W9);
; #pragma unroll
;     for (int c = 0; c < 4; ++c) r4<INV>(x[4 * c], x[4 * c + 1], x[4 * c + 2], x[4 * c + 3]);
; }
; template <bool INV> __device__ __forceinline__ void bfly16(f32x2 (&x)[16], const LAS f32x2* TH, const LAS f32x2* TL, int tw) {
;     f32x2 W = tw32k(TH, TL, tw); if (INV) W.y = -W.y;
;     if (INV) { f32x2 p = W;
; #pragma unroll
;         for (int q = 1; q < 16; ++q) { x[q] = cmul(x[q], p); if (q < 15) p = cmul(p, W); } }
;     dft16<INV>(x);
;     if (!INV) { f32x2 p = W;
; #pragma unroll
;         for (int r = 1; r < 16; ++r) { x[4 * (r & 3) + (r >> 2)] = cmul(x[4 * (r & 3) + (r >> 2)], p); if (r < 15) p = cmul(p, W); } }
; }
; template <bool INV> __device__ __forceinline__ void pass16(LAS f32x2* X, const LAS f32x2* TH, const LAS f32x2* TL, int base, int stride, int tw) {
;     f32x2 x[16];
; #pragma unroll
;     for (int q = 0; q < 16; ++q) x[q] = X[base + q * stride];
;     bfly16<INV>(x, TH, TL, tw);
; #pragma unroll
;     for (int c = 0; c < 4; ++c)
; #pragma unroll
;         for (int d = 0; d < 4; ++d) X[base + (c + 4 * d) * stride] = x[4 * c + d];
; }
.LBB0_696:
	v_add_u32_e32 v128, s0, v140
	v_lshrrev_b32_e32 v147, 6, v128
	v_and_b32_e32 v157, 63, v128
	v_lshlrev_b32_e32 v151, 5, v147
	v_lshlrev_b32_e32 v155, 3, v147
	v_lshlrev_b32_e32 v157, 4, v157
	v_lshl_add_u32 v151, v128, 3, v151
	v_add_u32_e32 v155, 0x26000, v155
	v_add_u32_e32 v157, 0x26400, v157
	v_add_u32_e32 v176, 0x11000, v151
	ds_read_b64 v[0:1], v155
	ds_read_b64 v[2:3], v157
	ds_read_b64 v[4:5], v151 offset:0
	ds_read_b64 v[6:7], v176 offset:0
	ds_read_b64 v[8:9], v151 offset:8704
	ds_read_b64 v[10:11], v176 offset:8704
	ds_read_b64 v[12:13], v151 offset:17408
	ds_read_b64 v[14:15], v176 offset:17408
	ds_read_b64 v[16:17], v151 offset:26112
	ds_read_b64 v[18:19], v176 offset:26112
	ds_read_b64 v[20:21], v151 offset:34816
	ds_read_b64 v[22:23], v176 offset:34816
	ds_read_b64 v[24:25], v151 offset:43520
	ds_read_b64 v[26:27], v176 offset:43520
	ds_read_b64 v[28:29], v151 offset:52224
	ds_read_b64 v[30:31], v176 offset:52224
	ds_read_b64 v[32:33], v151 offset:60928
	ds_read_b64 v[34:35], v176 offset:60928
	s_cmp_eq_u32 s0, 0
	s_movk_i32 s0, 0x200
	s_mov_b64 s[36:37], 0
	s_waitcnt lgkmcnt(15)
	v_pk_mul_f32 v[36:37], v[0:1], v[2:3] op_sel:[0,1] op_sel_hi:[1,1]
	s_nop 0
	v_pk_fma_f32 v[0:1], v[0:1], v[2:3], v[36:37] op_sel:[0,0,1] op_sel_hi:[1,0,0] neg_lo:[0,0,1]
	s_nop 0
	v_pk_mul_f32 v[36:37], v[0:1], v[0:1] op_sel:[0,1] op_sel_hi:[1,1]
	s_nop 0
	v_pk_fma_f32 v[36:37], v[0:1], v[0:1], v[36:37] op_sel:[0,0,1] op_sel_hi:[1,0,0] neg_lo:[0,0,1]
	s_nop 0
	v_pk_mul_f32 v[2:3], v[36:37], v[0:1] op_sel:[0,1] op_sel_hi:[1,1]
	v_pk_mul_f32 v[38:39], v[36:37], v[36:37] op_sel:[0,1] op_sel_hi:[1,1]
	v_pk_fma_f32 v[2:3], v[36:37], v[0:1], v[2:3] op_sel:[0,0,1] op_sel_hi:[1,0,0] neg_lo:[0,0,1]
	v_pk_fma_f32 v[38:39], v[36:37], v[36:37], v[38:39] op_sel:[0,0,1] op_sel_hi:[1,0,0] neg_lo:[0,0,1]
	s_nop 0
	v_pk_mul_f32 v[40:41], v[38:39], v[0:1] op_sel:[0,1] op_sel_hi:[1,1]
	v_pk_mul_f32 v[42:43], v[38:39], v[36:37] op_sel:[0,1] op_sel_hi:[1,1]
	v_pk_mul_f32 v[44:45], v[38:39], v[2:3] op_sel:[0,1] op_sel_hi:[1,1]
	v_pk_fma_f32 v[40:41], v[38:39], v[0:1], v[40:41] op_sel:[0,0,1] op_sel_hi:[1,0,0] neg_lo:[0,0,1]
	v_pk_fma_f32 v[42:43], v[38:39], v[36:37], v[42:43] op_sel:[0,0,1] op_sel_hi:[1,0,0] neg_lo:[0,0,1]
	v_pk_fma_f32 v[44:45], v[38:39], v[2:3], v[44:45] op_sel:[0,0,1] op_sel_hi:[1,0,0] neg_lo:[0,0,1]
	v_pk_mul_f32 v[46:47], v[38:39], v[38:39] op_sel:[0,1] op_sel_hi:[1,1]
	s_nop 0
	v_pk_fma_f32 v[46:47], v[38:39], v[38:39], v[46:47] op_sel:[0,0,1] op_sel_hi:[1,0,0] neg_lo:[0,0,1]
	s_nop 0
	v_pk_mul_f32 v[48:49], v[46:47], v[0:1] op_sel:[0,1] op_sel_hi:[1,1]
	v_pk_mul_f32 v[50:51], v[46:47], v[36:37] op_sel:[0,1] op_sel_hi:[1,1]
	v_pk_mul_f32 v[52:53], v[46:47], v[2:3] op_sel:[0,1] op_sel_hi:[1,1]
	v_pk_fma_f32 v[48:49], v[46:47], v[0:1], v[48:49] op_sel:[0,0,1] op_sel_hi:[1,0,0] neg_lo:[0,0,1]
	v_pk_fma_f32 v[50:51], v[46:47], v[36:37], v[50:51] op_sel:[0,0,1] op_sel_hi:[1,0,0] neg_lo:[0,0,1]
	v_pk_fma_f32 v[52:53], v[46:47], v[2:3], v[52:53] op_sel:[0,0,1] op_sel_hi:[1,0,0] neg_lo:[0,0,1]
	v_pk_mul_f32 v[54:55], v[46:47], v[38:39] op_sel:[0,1] op_sel_hi:[1,1]
	v_pk_mul_f32 v[56:57], v[46:47], v[40:41] op_sel:[0,1] op_sel_hi:[1,1]
	v_pk_mul_f32 v[58:59], v[46:47], v[42:43] op_sel:[0,1] op_sel_hi:[1,1]
	v_pk_fma_f32 v[54:55], v[46:47], v[38:39], v[54:55] op_sel:[0,0,1] op_sel_hi:[1,0,0] neg_lo:[0,0,1]
	v_pk_fma_f32 v[56:57], v[46:47], v[40:41], v[56:57] op_sel:[0,0,1] op_sel_hi:[1,0,0] neg_lo:[0,0,1]
	v_pk_fma_f32 v[58:59], v[46:47], v[42:43], v[58:59] op_sel:[0,0,1] op_sel_hi:[1,0,0] neg_lo:[0,0,1]
	v_pk_mul_f32 v[60:61], v[46:47], v[44:45] op_sel:[0,1] op_sel_hi:[1,1]
	s_nop 0
	v_pk_fma_f32 v[60:61], v[46:47], v[44:45], v[60:61] op_sel:[0,0,1] op_sel_hi:[1,0,0] neg_lo:[0,0,1]
	s_waitcnt lgkmcnt(14)
	v_pk_add_f32 v[62:63], v[4:5], v[6:7]
	s_waitcnt lgkmcnt(12)
	v_pk_add_f32 v[170:171], v[8:9], v[10:11]
	s_waitcnt lgkmcnt(10)
	v_pk_add_f32 v[172:173], v[12:13], v[14:15]
	s_waitcnt lgkmcnt(8)
	v_pk_add_f32 v[174:175], v[16:17], v[18:19]
	v_pk_add_f32 v[6:7], v[4:5], v[6:7] neg_lo:[0,1] neg_hi:[0,1]
	v_pk_add_f32 v[8:9], v[8:9], v[10:11] neg_lo:[0,1] neg_hi:[0,1]
	v_pk_add_f32 v[14:15], v[12:13], v[14:15] neg_lo:[0,1] neg_hi:[0,1]
	v_pk_add_f32 v[18:19], v[16:17], v[18:19] neg_lo:[0,1] neg_hi:[0,1]
	s_waitcnt lgkmcnt(6)
	v_pk_add_f32 v[16:17], v[20:21], v[22:23]
	s_waitcnt lgkmcnt(4)
	v_pk_add_f32 v[12:13], v[24:25], v[26:27]
	s_waitcnt lgkmcnt(2)
	v_pk_add_f32 v[10:11], v[28:29], v[30:31]
	s_waitcnt lgkmcnt(0)
; #define LAS __attribute__((address_space(3)))
; __device__ __forceinline__ f32x2 cmul(f32x2 a, f32x2 b) { return (f32x2){a.x * b.x - a.y * b.y, a.x * b.y + a.y * b.x}; }
; __device__ __forceinline__ f32x2 tw32k(const LAS f32x2* TH, const LAS f32x2* TL, int n) { return cmul(TH[n >> 7], TL[n & 127]); }
; template <bool INV> __device__ __forceinline__ void dft16(f32x2 (&x)[16]) {
; #pragma unroll
;     for (int b = 0; b < 4; ++b) r4<INV>(x[b], x[4 + b], x[8 + b], x[12 + b]);
;     const float sg = INV ? -1.f : 1.f;
;     const f32x2 W1 = {0.92387953251f, -0.38268343236f * sg}, W2 = {0.70710678118f, -0.70710678118f * sg}, W3 = {0.38268343236f, -0.92387953251f * sg},
;                 W4 = {0.f, -1.f * sg}, W6 = {-0.70710678118f, -0.70710678118f * sg}, W9 = {-0.92387953251f, 0.38268343236f * sg};
;     x[5] = cmul(x[5], W1); x[9] = cmul(x[9], W2); x[13] = cmul(x[13], W3);
;     x[6] = cmul(x[6], W2); x[10] = cmul(x[10], W4); x[14] = cmul(x[14], W6);
;     x[7] = cmul(x[7], W3); x[11] = cmul(x[11], W6); x[15] = cmul(x[15], W9);
; #pragma unroll
;     for (int c = 0; c < 4; ++c) r4<INV>(x[4 * c], x[4 * c + 1], x[4 * c + 2], x[4 * c + 3]);
; }
; template <bool INV> __device__ __forceinline__ void bfly16(f32x2 (&x)[16], const LAS f32x2* TH, const LAS f32x2* TL, int tw) {
;     f32x2 W = tw32k(TH, TL, tw); if (INV) W.y = -W.y;
;     if (INV) { f32x2 p = W;
; #pragma unroll
;         for (int q = 1; q < 16; ++q) { x[q] = cmul(x[q], p); if (q < 15) p = cmul(p, W); } }
;     dft16<INV>(x);
;     if (!INV) { f32x2 p = W;
; #pragma unroll
;         for (int r = 1; r < 16; ++r) { x[4 * (r & 3) + (r >> 2)] = cmul(x[4 * (r & 3) + (r >> 2)], p); if (r < 15) p = cmul(p, W); } }
; }
	v_pk_add_f32 v[4:5], v[32:33], v[34:35]
	v_pk_add_f32 v[22:23], v[20:21], v[22:23] neg_lo:[0,1] neg_hi:[0,1]
	v_pk_add_f32 v[24:25], v[24:25], v[26:27] neg_lo:[0,1] neg_hi:[0,1]
	v_pk_add_f32 v[30:31], v[28:29], v[30:31] neg_lo:[0,1] neg_hi:[0,1]
	v_pk_add_f32 v[34:35], v[32:33], v[34:35] neg_lo:[0,1] neg_hi:[0,1]
	v_pk_add_f32 v[32:33], v[62:63], v[16:17]
	v_pk_add_f32 v[28:29], v[170:171], v[12:13]
	v_pk_add_f32 v[26:27], v[172:173], v[10:11]
	v_pk_add_f32 v[20:21], v[174:175], v[4:5]
	v_pk_add_f32 v[62:63], v[62:63], v[16:17] neg_lo:[0,1] neg_hi:[0,1]
	v_pk_add_f32 v[170:171], v[170:171], v[12:13] neg_lo:[0,1] neg_hi:[0,1]
	v_pk_add_f32 v[10:11], v[172:173], v[10:11] neg_lo:[0,1] neg_hi:[0,1]
	v_pk_add_f32 v[174:175], v[174:175], v[4:5] neg_lo:[0,1] neg_hi:[0,1]
	v_pk_add_f32 v[4:5], v[6:7], v[22:23] op_sel:[0,1] op_sel_hi:[1,0] neg_hi:[0,1]
	v_pk_add_f32 v[172:173], v[8:9], v[24:25] op_sel:[0,1] op_sel_hi:[1,0] neg_hi:[0,1]
	v_pk_add_f32 v[12:13], v[14:15], v[30:31] op_sel:[0,1] op_sel_hi:[1,0] neg_hi:[0,1]
	v_pk_add_f32 v[16:17], v[18:19], v[34:35] op_sel:[0,1] op_sel_hi:[1,0] neg_hi:[0,1]
	v_pk_add_f32 v[22:23], v[6:7], v[22:23] op_sel:[0,1] op_sel_hi:[1,0] neg_lo:[0,1]
	v_pk_add_f32 v[8:9], v[8:9], v[24:25] op_sel:[0,1] op_sel_hi:[1,0] neg_lo:[0,1]
	v_pk_add_f32 v[14:15], v[14:15], v[30:31] op_sel:[0,1] op_sel_hi:[1,0] neg_lo:[0,1]
	v_pk_add_f32 v[18:19], v[18:19], v[34:35] op_sel:[0,1] op_sel_hi:[1,0] neg_lo:[0,1]
	v_pk_mul_f32 v[34:35], v[172:173], s[70:71] op_sel_hi:[1,0]
	v_pk_mul_f32 v[30:31], v[170:171], s[72:73] op_sel_hi:[1,0]
	v_pk_mul_f32 v[24:25], v[8:9], s[64:65] op_sel_hi:[1,0]
	v_pk_mul_f32 v[6:7], v[12:13], s[72:73] op_sel_hi:[1,0]
	v_pk_mul_f32 v[178:179], v[14:15], s[72:73] op_sel_hi:[1,0]
	v_pk_mul_f32 v[180:181], v[16:17], s[64:65] op_sel_hi:[1,0]
	v_pk_mul_f32 v[182:183], v[174:175], s[72:73] op_sel_hi:[1,0]
	v_pk_mul_f32 v[184:185], v[18:19], s[82:83] op_sel_hi:[1,0]
	v_pk_fma_f32 v[172:173], v[172:173], s[44:45], v[34:35] op_sel:[0,0,1] op_sel_hi:[1,0,0] neg_lo:[0,0,1]
	v_pk_fma_f32 v[30:31], v[170:171], s[76:77], v[30:31] op_sel:[0,0,1] op_sel_hi:[1,0,0] neg_lo:[0,0,1]
	v_pk_fma_f32 v[24:25], v[8:9], s[82:83], v[24:25] op_sel:[0,0,1] op_sel_hi:[1,0,0] neg_lo:[0,0,1]
	v_pk_fma_f32 v[6:7], v[12:13], s[76:77], v[6:7] op_sel:[0,0,1] op_sel_hi:[1,0,0] neg_lo:[0,0,1]
	v_pk_fma_f32 v[178:179], v[14:15], s[72:73], v[178:179] op_sel:[0,0,1] op_sel_hi:[1,0,0] neg_lo:[0,0,1]
	v_pk_fma_f32 v[180:181], v[16:17], s[82:83], v[180:181] op_sel:[0,0,1] op_sel_hi:[1,0,0] neg_lo:[0,0,1]
	v_pk_fma_f32 v[182:183], v[174:175], s[72:73], v[182:183] op_sel:[0,0,1] op_sel_hi:[1,0,0] neg_lo:[0,0,1]
	v_pk_fma_f32 v[184:185], v[18:19], s[64:65], v[184:185] op_sel:[0,0,1] op_sel_hi:[1,0,0] neg_lo:[0,0,1]
	v_pk_add_f32 v[18:19], v[32:33], v[26:27]
	v_pk_add_f32 v[174:175], v[4:5], v[6:7]
	v_pk_add_f32 v[16:17], v[62:63], v[10:11] op_sel:[0,1] op_sel_hi:[1,0] neg_hi:[0,1]
	v_pk_add_f32 v[14:15], v[22:23], v[178:179]
	v_pk_add_f32 v[26:27], v[32:33], v[26:27] neg_lo:[0,1] neg_hi:[0,1]
	v_pk_add_f32 v[6:7], v[4:5], v[6:7] neg_lo:[0,1] neg_hi:[0,1]
	v_pk_add_f32 v[10:11], v[62:63], v[10:11] op_sel:[0,1] op_sel_hi:[1,0] neg_lo:[0,1]
	v_pk_add_f32 v[22:23], v[22:23], v[178:179] neg_lo:[0,1] neg_hi:[0,1]
	v_pk_add_f32 v[178:179], v[28:29], v[20:21]
	v_pk_add_f32 v[62:63], v[172:173], v[180:181]
	v_pk_add_f32 v[4:5], v[30:31], v[182:183]
	v_pk_add_f32 v[32:33], v[24:25], v[184:185]
	v_pk_add_f32 v[20:21], v[28:29], v[20:21] neg_lo:[0,1] neg_hi:[0,1]
	v_pk_add_f32 v[172:173], v[172:173], v[180:181] neg_lo:[0,1] neg_hi:[0,1]
	v_pk_add_f32 v[182:183], v[30:31], v[182:183] neg_lo:[0,1] neg_hi:[0,1]
	v_pk_add_f32 v[24:25], v[24:25], v[184:185] neg_lo:[0,1] neg_hi:[0,1]
	v_pk_add_f32 v[184:185], v[18:19], v[178:179]
	v_pk_add_f32 v[30:31], v[174:175], v[62:63]
	v_pk_add_f32 v[180:181], v[16:17], v[4:5]
	v_pk_add_f32 v[28:29], v[14:15], v[32:33]
	v_pk_add_f32 v[18:19], v[18:19], v[178:179] neg_lo:[0,1] neg_hi:[0,1]
	v_pk_add_f32 v[174:175], v[174:175], v[62:63] neg_lo:[0,1] neg_hi:[0,1]
	v_pk_add_f32 v[4:5], v[16:17], v[4:5] neg_lo:[0,1] neg_hi:[0,1]
	v_pk_add_f32 v[32:33], v[14:15], v[32:33] neg_lo:[0,1] neg_hi:[0,1]
	v_pk_add_f32 v[14:15], v[26:27], v[20:21] op_sel:[0,1] op_sel_hi:[1,0] neg_hi:[0,1]
	v_pk_add_f32 v[16:17], v[6:7], v[172:173] op_sel:[0,1] op_sel_hi:[1,0] neg_hi:[0,1]
	v_pk_add_f32 v[62:63], v[10:11], v[182:183] op_sel:[0,1] op_sel_hi:[1,0] neg_hi:[0,1]
	v_pk_add_f32 v[178:179], v[22:23], v[24:25] op_sel:[0,1] op_sel_hi:[1,0] neg_hi:[0,1]
	v_pk_add_f32 v[26:27], v[26:27], v[20:21] op_sel:[0,1] op_sel_hi:[1,0] neg_lo:[0,1]
	v_pk_add_f32 v[172:173], v[6:7], v[172:173] op_sel:[0,1] op_sel_hi:[1,0] neg_lo:[0,1]
	v_pk_add_f32 v[182:183], v[10:11], v[182:183] op_sel:[0,1] op_sel_hi:[1,0] neg_lo:[0,1]
	v_pk_add_f32 v[24:25], v[22:23], v[24:25] op_sel:[0,1] op_sel_hi:[1,0] neg_lo:[0,1]
	v_pk_mul_f32 v[22:23], v[30:31], v[0:1] op_sel:[0,1] op_sel_hi:[1,1]
	v_pk_mul_f32 v[10:11], v[180:181], v[36:37] op_sel:[0,1] op_sel_hi:[1,1]
	v_pk_fma_f32 v[22:23], v[30:31], v[0:1], v[22:23] op_sel:[0,0,1] op_sel_hi:[1,0,0] neg_lo:[0,0,1]
	v_pk_mul_f32 v[0:1], v[28:29], v[2:3] op_sel:[0,1] op_sel_hi:[1,1]
	v_pk_fma_f32 v[36:37], v[180:181], v[36:37], v[10:11] op_sel:[0,0,1] op_sel_hi:[1,0,0] neg_lo:[0,0,1]
	v_pk_mul_f32 v[10:11], v[14:15], v[38:39] op_sel:[0,1] op_sel_hi:[1,1]
	v_pk_fma_f32 v[0:1], v[28:29], v[2:3], v[0:1] op_sel:[0,0,1] op_sel_hi:[1,0,0] neg_lo:[0,0,1]
	v_pk_mul_f32 v[28:29], v[16:17], v[40:41] op_sel:[0,1] op_sel_hi:[1,1]
	v_pk_fma_f32 v[38:39], v[14:15], v[38:39], v[10:11] op_sel:[0,0,1] op_sel_hi:[1,0,0] neg_lo:[0,0,1]
; #define LAS __attribute__((address_space(3)))
; template <bool INV> __device__ __forceinline__ void pass16_s64(LAS f32x2* X, const LAS f32x2* TH, int base, int j) {
;     f32x2 x[16];
; #pragma unroll
;     for (int q = 0; q < 16; ++q) x[q] = X[base + q * 68];
;     bfly16_tab<INV>(x, TH - 2048, 64, j);
; #pragma unroll
;     for (int c = 0; c < 4; ++c)
; #pragma unroll
;         for (int d = 0; d < 4; ++d) X[base + (c + 4 * d) * 68] = x[4 * c + d];
; }
; template <bool INV> __device__ __forceinline__ void pass16(LAS f32x2* X, const LAS f32x2* TH, const LAS f32x2* TL, int base, int stride, int tw) {
;     f32x2 x[16];
; #pragma unroll
;     for (int q = 0; q < 16; ++q) x[q] = X[base + q * stride];
;     bfly16<INV>(x, TH, TL, tw);
; #pragma unroll
;     for (int c = 0; c < 4; ++c)
; #pragma unroll
;         for (int d = 0; d < 4; ++d) X[base + (c + 4 * d) * stride] = x[4 * c + d];
	v_pk_mul_f32 v[10:11], v[62:63], v[42:43] op_sel:[0,1] op_sel_hi:[1,1]
	v_pk_fma_f32 v[40:41], v[16:17], v[40:41], v[28:29] op_sel:[0,0,1] op_sel_hi:[1,0,0] neg_lo:[0,0,1]
	v_pk_mul_f32 v[16:17], v[178:179], v[44:45] op_sel:[0,1] op_sel_hi:[1,1]
	v_pk_fma_f32 v[62:63], v[62:63], v[42:43], v[10:11] op_sel:[0,0,1] op_sel_hi:[1,0,0] neg_lo:[0,0,1]
	v_pk_mul_f32 v[42:43], v[18:19], v[46:47] op_sel:[0,1] op_sel_hi:[1,1]
	v_pk_fma_f32 v[178:179], v[178:179], v[44:45], v[16:17] op_sel:[0,0,1] op_sel_hi:[1,0,0] neg_lo:[0,0,1]
	v_pk_mul_f32 v[16:17], v[174:175], v[48:49] op_sel:[0,1] op_sel_hi:[1,1]
	v_pk_fma_f32 v[46:47], v[18:19], v[46:47], v[42:43] op_sel:[0,0,1] op_sel_hi:[1,0,0] neg_lo:[0,0,1]
	v_pk_mul_f32 v[18:19], v[4:5], v[50:51] op_sel:[0,1] op_sel_hi:[1,1]
	v_pk_fma_f32 v[48:49], v[174:175], v[48:49], v[16:17] op_sel:[0,0,1] op_sel_hi:[1,0,0] neg_lo:[0,0,1]
	v_pk_mul_f32 v[16:17], v[32:33], v[52:53] op_sel:[0,1] op_sel_hi:[1,1]
	v_pk_fma_f32 v[50:51], v[4:5], v[50:51], v[18:19] op_sel:[0,0,1] op_sel_hi:[1,0,0] neg_lo:[0,0,1]
	v_pk_mul_f32 v[18:19], v[26:27], v[54:55] op_sel:[0,1] op_sel_hi:[1,1]
	v_pk_fma_f32 v[16:17], v[32:33], v[52:53], v[16:17] op_sel:[0,0,1] op_sel_hi:[1,0,0] neg_lo:[0,0,1]
	v_pk_mul_f32 v[52:53], v[172:173], v[56:57] op_sel:[0,1] op_sel_hi:[1,1]
	v_pk_fma_f32 v[54:55], v[26:27], v[54:55], v[18:19] op_sel:[0,0,1] op_sel_hi:[1,0,0] neg_lo:[0,0,1]
	v_pk_mul_f32 v[18:19], v[182:183], v[58:59] op_sel:[0,1] op_sel_hi:[1,1]
	v_pk_fma_f32 v[52:53], v[172:173], v[56:57], v[52:53] op_sel:[0,0,1] op_sel_hi:[1,0,0] neg_lo:[0,0,1]
	v_pk_mul_f32 v[172:173], v[24:25], v[60:61] op_sel:[0,1] op_sel_hi:[1,1]
	v_pk_fma_f32 v[58:59], v[182:183], v[58:59], v[18:19] op_sel:[0,0,1] op_sel_hi:[1,0,0] neg_lo:[0,0,1]
	v_pk_fma_f32 v[24:25], v[24:25], v[60:61], v[172:173] op_sel:[0,0,1] op_sel_hi:[1,0,0] neg_lo:[0,0,1]
	ds_write_b64 v151, v[184:185] offset:0
	ds_write_b64 v151, v[22:23] offset:8704
	ds_write_b64 v151, v[36:37] offset:17408
	ds_write_b64 v151, v[0:1] offset:26112
	ds_write_b64 v151, v[38:39] offset:34816
	ds_write_b64 v151, v[40:41] offset:43520
	ds_write_b64 v151, v[62:63] offset:52224
	ds_write_b64 v151, v[178:179] offset:60928
	ds_write_b64 v176, v[46:47] offset:0
	ds_write_b64 v176, v[48:49] offset:8704
	ds_write_b64 v176, v[50:51] offset:17408
	ds_write_b64 v176, v[16:17] offset:26112
	ds_write_b64 v176, v[54:55] offset:34816
	ds_write_b64 v176, v[52:53] offset:43520
	ds_write_b64 v176, v[58:59] offset:52224
	ds_write_b64 v176, v[24:25] offset:60928
	s_cbranch_scc1 .LBB0_696
	s_waitcnt lgkmcnt(0)
	s_barrier
	s_mov_b32 s0, 0
	s_mov_b64 s[36:37], -1
	ds_read2st64_b64 v[232:235], v139 offset0:1 offset1:2
	ds_read2st64_b64 v[208:211], v139 offset0:3 offset1:4
	ds_read2st64_b64 v[204:207], v139 offset0:5 offset1:6
	ds_read2st64_b64 v[200:203], v139 offset0:7 offset1:8
	ds_read2st64_b64 v[196:199], v139 offset0:9 offset1:10
	ds_read2st64_b64 v[192:195], v139 offset0:11 offset1:12
	ds_read2st64_b64 v[188:191], v139 offset0:13 offset1:14
	ds_read_b64 v[186:187], v139 offset:7680
.LBB0_698:
	v_add_u32_e32 v128, s0, v140
	v_lshrrev_b32_e32 v147, 6, v128
	v_mad_u32_u24 v151, v147, s77, v142
	ds_read_b64 v[0:1], v151 offset:0
	ds_read_b64 v[2:3], v151 offset:4352
	ds_read_b64 v[4:5], v151 offset:544
	ds_read_b64 v[6:7], v151 offset:4896
	ds_read_b64 v[8:9], v151 offset:1088
	ds_read_b64 v[10:11], v151 offset:5440
	ds_read_b64 v[12:13], v151 offset:1632
	ds_read_b64 v[14:15], v151 offset:5984
	ds_read_b64 v[16:17], v151 offset:2176
	ds_read_b64 v[18:19], v151 offset:6528
	ds_read_b64 v[20:21], v151 offset:2720
	ds_read_b64 v[22:23], v151 offset:7072
	ds_read_b64 v[24:25], v151 offset:3264
	ds_read_b64 v[26:27], v151 offset:7616
	ds_read_b64 v[28:29], v151 offset:3808
	ds_read_b64 v[30:31], v151 offset:8160
	s_cmp_eq_u32 s0, 0
	s_movk_i32 s0, 0x200
	s_mov_b64 s[36:37], 0
	s_waitcnt lgkmcnt(14)
	v_pk_add_f32 v[32:33], v[0:1], v[2:3]
	s_waitcnt lgkmcnt(12)
	v_pk_add_f32 v[34:35], v[4:5], v[6:7]
	s_waitcnt lgkmcnt(10)
	v_pk_add_f32 v[36:37], v[8:9], v[10:11]
	s_waitcnt lgkmcnt(8)
	v_pk_add_f32 v[38:39], v[12:13], v[14:15]
	v_pk_add_f32 v[0:1], v[0:1], v[2:3] neg_lo:[0,1] neg_hi:[0,1]
	v_pk_add_f32 v[4:5], v[4:5], v[6:7] neg_lo:[0,1] neg_hi:[0,1]
	v_pk_add_f32 v[10:11], v[8:9], v[10:11] neg_lo:[0,1] neg_hi:[0,1]
	v_pk_add_f32 v[14:15], v[12:13], v[14:15] neg_lo:[0,1] neg_hi:[0,1]
	s_waitcnt lgkmcnt(6)
	v_pk_add_f32 v[12:13], v[16:17], v[18:19]
	s_waitcnt lgkmcnt(4)
	v_pk_add_f32 v[8:9], v[20:21], v[22:23]
	s_waitcnt lgkmcnt(2)
	v_pk_add_f32 v[6:7], v[24:25], v[26:27]
	s_waitcnt lgkmcnt(0)
; #define LAS __attribute__((address_space(3)))
; __device__ __forceinline__ f32x2 cmul(f32x2 a, f32x2 b) { return (f32x2){a.x * b.x - a.y * b.y, a.x * b.y + a.y * b.x}; }
; __device__ __forceinline__ f32x2 tw32k(const LAS f32x2* TH, const LAS f32x2* TL, int n) { return cmul(TH[n >> 7], TL[n & 127]); }
; template <bool INV> __device__ __forceinline__ void dft16(f32x2 (&x)[16]) {
; #pragma unroll
;     for (int b = 0; b < 4; ++b) r4<INV>(x[b], x[4 + b], x[8 + b], x[12 + b]);
;     const float sg = INV ? -1.f : 1.f;
;     const f32x2 W1 = {0.92387953251f, -0.38268343236f * sg}, W2 = {0.70710678118f, -0.70710678118f * sg}, W3 = {0.38268343236f, -0.92387953251f * sg},
;                 W4 = {0.f, -1.f * sg}, W6 = {-0.70710678118f, -0.70710678118f * sg}, W9 = {-0.92387953251f, 0.38268343236f * sg};
;     x[5] = cmul(x[5], W1); x[9] = cmul(x[9], W2); x[13] = cmul(x[13], W3);
;     x[6] = cmul(x[6], W2); x[10] = cmul(x[10], W4); x[14] = cmul(x[14], W6);
;     x[7] = cmul(x[7], W3); x[11] = cmul(x[11], W6); x[15] = cmul(x[15], W9);
; #pragma unroll
;     for (int c = 0; c < 4; ++c) r4<INV>(x[4 * c], x[4 * c + 1], x[4 * c + 2], x[4 * c + 3]);
; }
; template <bool INV> __device__ __forceinline__ void bfly16(f32x2 (&x)[16], const LAS f32x2* TH, const LAS f32x2* TL, int tw) {
;     f32x2 W = tw32k(TH, TL, tw); if (INV) W.y = -W.y;
;     if (INV) { f32x2 p = W;
; #pragma unroll
;         for (int q = 1; q < 16; ++q) { x[q] = cmul(x[q], p); if (q < 15) p = cmul(p, W); } }
;     dft16<INV>(x);
;     if (!INV) { f32x2 p = W;
; #pragma unroll
;         for (int r = 1; r < 16; ++r) { x[4 * (r & 3) + (r >> 2)] = cmul(x[4 * (r & 3) + (r >> 2)], p); if (r < 15) p = cmul(p, W); } }
; }
; template <bool INV> __device__ __forceinline__ void bfly16_tab(f32x2 (&x)[16], const LAS f32x2* T, int tstride, int j) {
;     if (INV) {
; #pragma unroll
;         for (int q = 1; q < 16; ++q) { f32x2 p = T[q * tstride + j]; p.y = -p.y; x[q] = cmul(x[q], p); } }
;     dft16<INV>(x);
;     if (!INV) {
; #pragma unroll
;         for (int r = 1; r < 16; ++r) { const f32x2 p = T[r * tstride + j]; x[4 * (r & 3) + (r >> 2)] = cmul(x[4 * (r & 3) + (r >> 2)], p); } }
; }
	v_pk_add_f32 v[2:3], v[28:29], v[30:31]
	v_pk_add_f32 v[18:19], v[16:17], v[18:19] neg_lo:[0,1] neg_hi:[0,1]
	v_pk_add_f32 v[22:23], v[20:21], v[22:23] neg_lo:[0,1] neg_hi:[0,1]
	v_pk_add_f32 v[26:27], v[24:25], v[26:27] neg_lo:[0,1] neg_hi:[0,1]
	v_pk_add_f32 v[30:31], v[28:29], v[30:31] neg_lo:[0,1] neg_hi:[0,1]
	v_pk_add_f32 v[28:29], v[32:33], v[12:13]
	v_pk_add_f32 v[24:25], v[34:35], v[8:9]
	v_pk_add_f32 v[20:21], v[36:37], v[6:7]
	v_pk_add_f32 v[16:17], v[38:39], v[2:3]
	v_pk_add_f32 v[12:13], v[32:33], v[12:13] neg_lo:[0,1] neg_hi:[0,1]
	v_pk_add_f32 v[8:9], v[34:35], v[8:9] neg_lo:[0,1] neg_hi:[0,1]
	v_pk_add_f32 v[6:7], v[36:37], v[6:7] neg_lo:[0,1] neg_hi:[0,1]
	v_pk_add_f32 v[2:3], v[38:39], v[2:3] neg_lo:[0,1] neg_hi:[0,1]
	v_pk_add_f32 v[38:39], v[0:1], v[18:19] op_sel:[0,1] op_sel_hi:[1,0] neg_hi:[0,1]
	v_pk_add_f32 v[36:37], v[4:5], v[22:23] op_sel:[0,1] op_sel_hi:[1,0] neg_hi:[0,1]
	v_pk_add_f32 v[34:35], v[10:11], v[26:27] op_sel:[0,1] op_sel_hi:[1,0] neg_hi:[0,1]
	v_pk_add_f32 v[32:33], v[14:15], v[30:31] op_sel:[0,1] op_sel_hi:[1,0] neg_hi:[0,1]
	v_pk_add_f32 v[18:19], v[0:1], v[18:19] op_sel:[0,1] op_sel_hi:[1,0] neg_lo:[0,1]
	v_pk_add_f32 v[22:23], v[4:5], v[22:23] op_sel:[0,1] op_sel_hi:[1,0] neg_lo:[0,1]
	v_pk_add_f32 v[26:27], v[10:11], v[26:27] op_sel:[0,1] op_sel_hi:[1,0] neg_lo:[0,1]
	v_pk_add_f32 v[30:31], v[14:15], v[30:31] op_sel:[0,1] op_sel_hi:[1,0] neg_lo:[0,1]
	v_pk_mul_f32 v[14:15], v[36:37], s[70:71] op_sel_hi:[1,0]
	v_pk_mul_f32 v[10:11], v[8:9], s[72:73] op_sel_hi:[1,0]
	v_pk_mul_f32 v[4:5], v[22:23], s[64:65] op_sel_hi:[1,0]
	v_pk_mul_f32 v[0:1], v[34:35], s[72:73] op_sel_hi:[1,0]
	v_pk_mul_f32 v[40:41], v[26:27], s[72:73] op_sel_hi:[1,0]
	v_pk_mul_f32 v[42:43], v[32:33], s[64:65] op_sel_hi:[1,0]
	v_pk_mul_f32 v[44:45], v[2:3], s[72:73] op_sel_hi:[1,0]
	v_pk_mul_f32 v[46:47], v[30:31], s[82:83] op_sel_hi:[1,0]
	v_pk_fma_f32 v[36:37], v[36:37], s[44:45], v[14:15] op_sel:[0,0,1] op_sel_hi:[1,0,0] neg_lo:[0,0,1]
	v_pk_fma_f32 v[10:11], v[8:9], s[76:77], v[10:11] op_sel:[0,0,1] op_sel_hi:[1,0,0] neg_lo:[0,0,1]
	v_pk_fma_f32 v[22:23], v[22:23], s[82:83], v[4:5] op_sel:[0,0,1] op_sel_hi:[1,0,0] neg_lo:[0,0,1]
	v_pk_fma_f32 v[34:35], v[34:35], s[76:77], v[0:1] op_sel:[0,0,1] op_sel_hi:[1,0,0] neg_lo:[0,0,1]
	v_pk_fma_f32 v[26:27], v[26:27], s[72:73], v[40:41] op_sel:[0,0,1] op_sel_hi:[1,0,0] neg_lo:[0,0,1]
	v_pk_fma_f32 v[42:43], v[32:33], s[82:83], v[42:43] op_sel:[0,0,1] op_sel_hi:[1,0,0] neg_lo:[0,0,1]
	v_pk_fma_f32 v[2:3], v[2:3], s[72:73], v[44:45] op_sel:[0,0,1] op_sel_hi:[1,0,0] neg_lo:[0,0,1]
	v_pk_fma_f32 v[46:47], v[30:31], s[64:65], v[46:47] op_sel:[0,0,1] op_sel_hi:[1,0,0] neg_lo:[0,0,1]
	v_pk_add_f32 v[30:31], v[28:29], v[20:21]
	v_pk_add_f32 v[44:45], v[38:39], v[34:35]
	v_pk_add_f32 v[32:33], v[12:13], v[6:7] op_sel:[0,1] op_sel_hi:[1,0] neg_hi:[0,1]
	v_pk_add_f32 v[40:41], v[18:19], v[26:27]
	v_pk_add_f32 v[28:29], v[28:29], v[20:21] neg_lo:[0,1] neg_hi:[0,1]
	v_pk_add_f32 v[38:39], v[38:39], v[34:35] neg_lo:[0,1] neg_hi:[0,1]
	v_pk_add_f32 v[6:7], v[12:13], v[6:7] op_sel:[0,1] op_sel_hi:[1,0] neg_lo:[0,1]
	v_pk_add_f32 v[26:27], v[18:19], v[26:27] neg_lo:[0,1] neg_hi:[0,1]
	v_pk_add_f32 v[18:19], v[24:25], v[16:17]
	v_pk_add_f32 v[12:13], v[36:37], v[42:43]
	v_pk_add_f32 v[34:35], v[10:11], v[2:3]
	v_pk_add_f32 v[20:21], v[22:23], v[46:47]
	v_pk_add_f32 v[24:25], v[24:25], v[16:17] neg_lo:[0,1] neg_hi:[0,1]
	v_pk_add_f32 v[36:37], v[36:37], v[42:43] neg_lo:[0,1] neg_hi:[0,1]
	v_pk_add_f32 v[2:3], v[10:11], v[2:3] neg_lo:[0,1] neg_hi:[0,1]
	v_pk_add_f32 v[22:23], v[22:23], v[46:47] neg_lo:[0,1] neg_hi:[0,1]
	v_pk_add_f32 v[46:47], v[30:31], v[18:19]
	v_pk_add_f32 v[10:11], v[44:45], v[12:13]
	v_pk_add_f32 v[42:43], v[32:33], v[34:35]
	v_pk_add_f32 v[16:17], v[40:41], v[20:21]
	v_pk_add_f32 v[18:19], v[30:31], v[18:19] neg_lo:[0,1] neg_hi:[0,1]
	v_pk_add_f32 v[12:13], v[44:45], v[12:13] neg_lo:[0,1] neg_hi:[0,1]
	v_pk_add_f32 v[34:35], v[32:33], v[34:35] neg_lo:[0,1] neg_hi:[0,1]
	v_pk_add_f32 v[40:41], v[40:41], v[20:21] neg_lo:[0,1] neg_hi:[0,1]
	v_pk_add_f32 v[20:21], v[28:29], v[24:25] op_sel:[0,1] op_sel_hi:[1,0] neg_hi:[0,1]
	v_pk_add_f32 v[32:33], v[38:39], v[36:37] op_sel:[0,1] op_sel_hi:[1,0] neg_hi:[0,1]
	v_pk_add_f32 v[44:45], v[6:7], v[2:3] op_sel:[0,1] op_sel_hi:[1,0] neg_hi:[0,1]
	v_pk_add_f32 v[30:31], v[26:27], v[22:23] op_sel:[0,1] op_sel_hi:[1,0] neg_hi:[0,1]
	v_pk_add_f32 v[28:29], v[28:29], v[24:25] op_sel:[0,1] op_sel_hi:[1,0] neg_lo:[0,1]
	v_pk_add_f32 v[38:39], v[38:39], v[36:37] op_sel:[0,1] op_sel_hi:[1,0] neg_lo:[0,1]
	v_pk_add_f32 v[6:7], v[6:7], v[2:3] op_sel:[0,1] op_sel_hi:[1,0] neg_lo:[0,1]
	v_pk_add_f32 v[22:23], v[26:27], v[22:23] op_sel:[0,1] op_sel_hi:[1,0] neg_lo:[0,1]
	v_pk_mul_f32 v[26:27], v[10:11], v[232:233] op_sel:[0,1] op_sel_hi:[1,1]
	v_pk_mul_f32 v[2:3], v[42:43], v[234:235] op_sel:[0,1] op_sel_hi:[1,1]
	v_pk_fma_f32 v[26:27], v[10:11], v[232:233], v[26:27] op_sel:[0,0,1] op_sel_hi:[1,0,0] neg_lo:[0,0,1]
	v_pk_mul_f32 v[10:11], v[16:17], v[208:209] op_sel:[0,1] op_sel_hi:[1,1]
	v_pk_fma_f32 v[2:3], v[42:43], v[234:235], v[2:3] op_sel:[0,0,1] op_sel_hi:[1,0,0] neg_lo:[0,0,1]
	v_pk_mul_f32 v[42:43], v[20:21], v[210:211] op_sel:[0,1] op_sel_hi:[1,1]
	v_pk_fma_f32 v[10:11], v[16:17], v[208:209], v[10:11] op_sel:[0,0,1] op_sel_hi:[1,0,0] neg_lo:[0,0,1]
	v_pk_mul_f32 v[16:17], v[32:33], v[204:205] op_sel:[0,1] op_sel_hi:[1,1]
	v_pk_fma_f32 v[42:43], v[20:21], v[210:211], v[42:43] op_sel:[0,0,1] op_sel_hi:[1,0,0] neg_lo:[0,0,1]
	v_pk_mul_f32 v[20:21], v[44:45], v[206:207] op_sel:[0,1] op_sel_hi:[1,1]
; #define LAS __attribute__((address_space(3)))
; template <bool INV> __device__ __forceinline__ void pass16_s64(LAS f32x2* X, const LAS f32x2* TH, int base, int j) {
;     ...
; #pragma unroll
;     for (int c = 0; c < 4; ++c)
; #pragma unroll
;         for (int d = 0; d < 4; ++d) X[base + (c + 4 * d) * 68] = x[4 * c + d];
; }
; template <bool INV> __device__ __forceinline__ void pass16(LAS f32x2* X, const LAS f32x2* TH, const LAS f32x2* TL, int base, int stride, int tw) {
;     f32x2 x[16];
; #pragma unroll
;     for (int q = 0; q < 16; ++q) x[q] = X[base + q * stride];
;     bfly16<INV>(x, TH, TL, tw);
; #pragma unroll
;     for (int c = 0; c < 4; ++c)
; #pragma unroll
;         for (int d = 0; d < 4; ++d) X[base + (c + 4 * d) * stride] = x[4 * c + d];
; }
; template <bool INV> __device__ __forceinline__ void pass16_s4(LAS f32x2* X, const LAS f32x2* TH, const LAS f32x2* TL, int tid) {
; #pragma unroll 1
;     for (int s = 0; s < 2; ++s) {
;         const int b = tid + NTHR * s, blk = b >> 2, jj = b & 3;
;         LAS f32x2* P = X + blk * 68 + jj;
;         f32x2 x[16];
; #pragma unroll
;         for (int q = 0; q < 16; ++q) x[q] = P[4 * q];
;         bfly16_tab<INV>(x, TH - 1024, 4, jj);
	v_pk_fma_f32 v[32:33], v[32:33], v[204:205], v[16:17] op_sel:[0,0,1] op_sel_hi:[1,0,0] neg_lo:[0,0,1]
	v_pk_mul_f32 v[16:17], v[30:31], v[200:201] op_sel:[0,1] op_sel_hi:[1,1]
	v_pk_fma_f32 v[44:45], v[44:45], v[206:207], v[20:21] op_sel:[0,0,1] op_sel_hi:[1,0,0] neg_lo:[0,0,1]
	v_pk_mul_f32 v[20:21], v[18:19], v[202:203] op_sel:[0,1] op_sel_hi:[1,1]
	v_pk_fma_f32 v[16:17], v[30:31], v[200:201], v[16:17] op_sel:[0,0,1] op_sel_hi:[1,0,0] neg_lo:[0,0,1]
	v_pk_mul_f32 v[30:31], v[12:13], v[196:197] op_sel:[0,1] op_sel_hi:[1,1]
	v_pk_fma_f32 v[18:19], v[18:19], v[202:203], v[20:21] op_sel:[0,0,1] op_sel_hi:[1,0,0] neg_lo:[0,0,1]
	v_pk_mul_f32 v[20:21], v[34:35], v[198:199] op_sel:[0,1] op_sel_hi:[1,1]
	v_pk_fma_f32 v[12:13], v[12:13], v[196:197], v[30:31] op_sel:[0,0,1] op_sel_hi:[1,0,0] neg_lo:[0,0,1]
	v_pk_mul_f32 v[30:31], v[40:41], v[192:193] op_sel:[0,1] op_sel_hi:[1,1]
	v_pk_fma_f32 v[34:35], v[34:35], v[198:199], v[20:21] op_sel:[0,0,1] op_sel_hi:[1,0,0] neg_lo:[0,0,1]
	v_pk_mul_f32 v[20:21], v[28:29], v[194:195] op_sel:[0,1] op_sel_hi:[1,1]
	v_pk_fma_f32 v[40:41], v[40:41], v[192:193], v[30:31] op_sel:[0,0,1] op_sel_hi:[1,0,0] neg_lo:[0,0,1]
	v_pk_mul_f32 v[30:31], v[38:39], v[188:189] op_sel:[0,1] op_sel_hi:[1,1]
	v_pk_fma_f32 v[20:21], v[28:29], v[194:195], v[20:21] op_sel:[0,0,1] op_sel_hi:[1,0,0] neg_lo:[0,0,1]
	v_pk_mul_f32 v[28:29], v[6:7], v[190:191] op_sel:[0,1] op_sel_hi:[1,1]
	v_pk_fma_f32 v[30:31], v[38:39], v[188:189], v[30:31] op_sel:[0,0,1] op_sel_hi:[1,0,0] neg_lo:[0,0,1]
	v_pk_mul_f32 v[38:39], v[22:23], v[186:187] op_sel:[0,1] op_sel_hi:[1,1]
	v_pk_fma_f32 v[6:7], v[6:7], v[190:191], v[28:29] op_sel:[0,0,1] op_sel_hi:[1,0,0] neg_lo:[0,0,1]
	v_pk_fma_f32 v[22:23], v[22:23], v[186:187], v[38:39] op_sel:[0,0,1] op_sel_hi:[1,0,0] neg_lo:[0,0,1]
	ds_write_b64 v151, v[46:47] offset:0
	ds_write_b64 v151, v[26:27] offset:544
	ds_write_b64 v151, v[2:3] offset:1088
	ds_write_b64 v151, v[10:11] offset:1632
	ds_write_b64 v151, v[42:43] offset:2176
	ds_write_b64 v151, v[32:33] offset:2720
	ds_write_b64 v151, v[44:45] offset:3264
	ds_write_b64 v151, v[16:17] offset:3808
	ds_write_b64 v151, v[18:19] offset:4352
	ds_write_b64 v151, v[12:13] offset:4896
	ds_write_b64 v151, v[34:35] offset:5440
	ds_write_b64 v151, v[40:41] offset:5984
	ds_write_b64 v151, v[20:21] offset:6528
	ds_write_b64 v151, v[30:31] offset:7072
	ds_write_b64 v151, v[6:7] offset:7616
	ds_write_b64 v151, v[22:23] offset:8160
	s_cbranch_scc1 .LBB0_698
	s_waitcnt lgkmcnt(0)
	s_barrier
	s_mov_b32 s0, 0
	s_mov_b64 s[36:37], -1
	ds_read2_b64 v[232:235], v141 offset0:4 offset1:8
	ds_read2_b64 v[208:211], v141 offset0:12 offset1:16
	ds_read2_b64 v[204:207], v141 offset0:20 offset1:24
	ds_read2_b64 v[200:203], v141 offset0:28 offset1:32
	ds_read2_b64 v[196:199], v141 offset0:36 offset1:40
	ds_read2_b64 v[192:195], v141 offset0:44 offset1:48
	ds_read2_b64 v[188:191], v141 offset0:52 offset1:56
	ds_read_b64 v[186:187], v141 offset:480
.LBB0_700:
	v_add_u32_e32 v128, s0, v140
	v_lshrrev_b32_e32 v147, 2, v128
	v_mad_u32_u24 v151, v147, s43, v144
	ds_read_b64 v[0:1], v151 offset:0
	ds_read_b64 v[2:3], v151 offset:256
	ds_read_b64 v[4:5], v151 offset:32
	ds_read_b64 v[6:7], v151 offset:288
	ds_read_b64 v[8:9], v151 offset:64
	ds_read_b64 v[10:11], v151 offset:320
	ds_read_b64 v[12:13], v151 offset:96
	ds_read_b64 v[14:15], v151 offset:352
	ds_read_b64 v[16:17], v151 offset:128
	ds_read_b64 v[18:19], v151 offset:384
	ds_read_b64 v[20:21], v151 offset:160
	ds_read_b64 v[22:23], v151 offset:416
	ds_read_b64 v[24:25], v151 offset:192
	ds_read_b64 v[26:27], v151 offset:448
	ds_read_b64 v[28:29], v151 offset:224
	ds_read_b64 v[30:31], v151 offset:480
	s_cmp_eq_u32 s0, 0
	s_movk_i32 s0, 0x200
	s_mov_b64 s[36:37], 0
	s_waitcnt lgkmcnt(14)
	v_pk_add_f32 v[32:33], v[0:1], v[2:3]
	s_waitcnt lgkmcnt(12)
	v_pk_add_f32 v[34:35], v[4:5], v[6:7]
	s_waitcnt lgkmcnt(10)
	v_pk_add_f32 v[36:37], v[8:9], v[10:11]
	s_waitcnt lgkmcnt(8)
	v_pk_add_f32 v[38:39], v[12:13], v[14:15]
	v_pk_add_f32 v[2:3], v[0:1], v[2:3] neg_lo:[0,1] neg_hi:[0,1]
	v_pk_add_f32 v[4:5], v[4:5], v[6:7] neg_lo:[0,1] neg_hi:[0,1]
	v_pk_add_f32 v[10:11], v[8:9], v[10:11] neg_lo:[0,1] neg_hi:[0,1]
	v_pk_add_f32 v[12:13], v[12:13], v[14:15] neg_lo:[0,1] neg_hi:[0,1]
	s_waitcnt lgkmcnt(6)
	v_pk_add_f32 v[14:15], v[16:17], v[18:19]
	s_waitcnt lgkmcnt(4)
	v_pk_add_f32 v[8:9], v[20:21], v[22:23]
	s_waitcnt lgkmcnt(2)
	v_pk_add_f32 v[6:7], v[24:25], v[26:27]
	s_waitcnt lgkmcnt(0)
; #define LAS __attribute__((address_space(3)))
; __device__ __forceinline__ f32x2 cmul(f32x2 a, f32x2 b) { return (f32x2){a.x * b.x - a.y * b.y, a.x * b.y + a.y * b.x}; }
; __device__ __forceinline__ f32x2 tw32k(const LAS f32x2* TH, const LAS f32x2* TL, int n) { return cmul(TH[n >> 7], TL[n & 127]); }
; template <bool INV> __device__ __forceinline__ void dft16(f32x2 (&x)[16]) {
; #pragma unroll
;     for (int b = 0; b < 4; ++b) r4<INV>(x[b], x[4 + b], x[8 + b], x[12 + b]);
;     const float sg = INV ? -1.f : 1.f;
;     const f32x2 W1 = {0.92387953251f, -0.38268343236f * sg}, W2 = {0.70710678118f, -0.70710678118f * sg}, W3 = {0.38268343236f, -0.92387953251f * sg},
;                 W4 = {0.f, -1.f * sg}, W6 = {-0.70710678118f, -0.70710678118f * sg}, W9 = {-0.92387953251f, 0.38268343236f * sg};
;     x[5] = cmul(x[5], W1); x[9] = cmul(x[9], W2); x[13] = cmul(x[13], W3);
;     x[6] = cmul(x[6], W2); x[10] = cmul(x[10], W4); x[14] = cmul(x[14], W6);
;     x[7] = cmul(x[7], W3); x[11] = cmul(x[11], W6); x[15] = cmul(x[15], W9);
; #pragma unroll
;     for (int c = 0; c < 4; ++c) r4<INV>(x[4 * c], x[4 * c + 1], x[4 * c + 2], x[4 * c + 3]);
; }
; template <bool INV> __device__ __forceinline__ void bfly16(f32x2 (&x)[16], const LAS f32x2* TH, const LAS f32x2* TL, int tw) {
;     f32x2 W = tw32k(TH, TL, tw); if (INV) W.y = -W.y;
;     if (INV) { f32x2 p = W;
; #pragma unroll
;         for (int q = 1; q < 16; ++q) { x[q] = cmul(x[q], p); if (q < 15) p = cmul(p, W); } }
;     dft16<INV>(x);
;     if (!INV) { f32x2 p = W;
; #pragma unroll
;         for (int r = 1; r < 16; ++r) { x[4 * (r & 3) + (r >> 2)] = cmul(x[4 * (r & 3) + (r >> 2)], p); if (r < 15) p = cmul(p, W); } }
; }
; template <bool INV> __device__ __forceinline__ void bfly16_tab(f32x2 (&x)[16], const LAS f32x2* T, int tstride, int j) {
;     if (INV) {
; #pragma unroll
;         for (int q = 1; q < 16; ++q) { f32x2 p = T[q * tstride + j]; p.y = -p.y; x[q] = cmul(x[q], p); } }
;     dft16<INV>(x);
;     if (!INV) {
; #pragma unroll
;         for (int r = 1; r < 16; ++r) { const f32x2 p = T[r * tstride + j]; x[4 * (r & 3) + (r >> 2)] = cmul(x[4 * (r & 3) + (r >> 2)], p); } }
; }
	v_pk_add_f32 v[0:1], v[28:29], v[30:31]
	v_pk_add_f32 v[16:17], v[16:17], v[18:19] neg_lo:[0,1] neg_hi:[0,1]
	v_pk_add_f32 v[22:23], v[20:21], v[22:23] neg_lo:[0,1] neg_hi:[0,1]
	v_pk_add_f32 v[26:27], v[24:25], v[26:27] neg_lo:[0,1] neg_hi:[0,1]
	v_pk_add_f32 v[30:31], v[28:29], v[30:31] neg_lo:[0,1] neg_hi:[0,1]
	v_pk_add_f32 v[28:29], v[32:33], v[14:15]
	v_pk_add_f32 v[24:25], v[34:35], v[8:9]
	v_pk_add_f32 v[20:21], v[36:37], v[6:7]
	v_pk_add_f32 v[18:19], v[38:39], v[0:1]
	v_pk_add_f32 v[32:33], v[32:33], v[14:15] neg_lo:[0,1] neg_hi:[0,1]
	v_pk_add_f32 v[34:35], v[34:35], v[8:9] neg_lo:[0,1] neg_hi:[0,1]
	v_pk_add_f32 v[6:7], v[36:37], v[6:7] neg_lo:[0,1] neg_hi:[0,1]
	v_pk_add_f32 v[0:1], v[38:39], v[0:1] neg_lo:[0,1] neg_hi:[0,1]
	v_pk_add_f32 v[38:39], v[2:3], v[16:17] op_sel:[0,1] op_sel_hi:[1,0] neg_hi:[0,1]
	v_pk_add_f32 v[36:37], v[4:5], v[22:23] op_sel:[0,1] op_sel_hi:[1,0] neg_hi:[0,1]
	v_pk_add_f32 v[8:9], v[10:11], v[26:27] op_sel:[0,1] op_sel_hi:[1,0] neg_hi:[0,1]
	v_pk_add_f32 v[14:15], v[12:13], v[30:31] op_sel:[0,1] op_sel_hi:[1,0] neg_hi:[0,1]
	v_pk_add_f32 v[16:17], v[2:3], v[16:17] op_sel:[0,1] op_sel_hi:[1,0] neg_lo:[0,1]
	v_pk_add_f32 v[4:5], v[4:5], v[22:23] op_sel:[0,1] op_sel_hi:[1,0] neg_lo:[0,1]
	v_pk_add_f32 v[26:27], v[10:11], v[26:27] op_sel:[0,1] op_sel_hi:[1,0] neg_lo:[0,1]
	v_pk_add_f32 v[30:31], v[12:13], v[30:31] op_sel:[0,1] op_sel_hi:[1,0] neg_lo:[0,1]
	v_pk_mul_f32 v[12:13], v[36:37], s[70:71] op_sel_hi:[1,0]
	v_pk_mul_f32 v[10:11], v[34:35], s[72:73] op_sel_hi:[1,0]
	v_pk_mul_f32 v[22:23], v[4:5], s[64:65] op_sel_hi:[1,0]
	v_pk_mul_f32 v[2:3], v[8:9], s[72:73] op_sel_hi:[1,0]
	v_pk_mul_f32 v[40:41], v[26:27], s[72:73] op_sel_hi:[1,0]
	v_pk_mul_f32 v[42:43], v[14:15], s[64:65] op_sel_hi:[1,0]
	v_pk_mul_f32 v[44:45], v[0:1], s[72:73] op_sel_hi:[1,0]
	v_pk_mul_f32 v[46:47], v[30:31], s[82:83] op_sel_hi:[1,0]
	v_pk_fma_f32 v[36:37], v[36:37], s[44:45], v[12:13] op_sel:[0,0,1] op_sel_hi:[1,0,0] neg_lo:[0,0,1]
	v_pk_fma_f32 v[34:35], v[34:35], s[76:77], v[10:11] op_sel:[0,0,1] op_sel_hi:[1,0,0] neg_lo:[0,0,1]
	v_pk_fma_f32 v[4:5], v[4:5], s[82:83], v[22:23] op_sel:[0,0,1] op_sel_hi:[1,0,0] neg_lo:[0,0,1]
	v_pk_fma_f32 v[2:3], v[8:9], s[76:77], v[2:3] op_sel:[0,0,1] op_sel_hi:[1,0,0] neg_lo:[0,0,1]
	v_pk_fma_f32 v[26:27], v[26:27], s[72:73], v[40:41] op_sel:[0,0,1] op_sel_hi:[1,0,0] neg_lo:[0,0,1]
	v_pk_fma_f32 v[42:43], v[14:15], s[82:83], v[42:43] op_sel:[0,0,1] op_sel_hi:[1,0,0] neg_lo:[0,0,1]
	v_pk_fma_f32 v[44:45], v[0:1], s[72:73], v[44:45] op_sel:[0,0,1] op_sel_hi:[1,0,0] neg_lo:[0,0,1]
	v_pk_fma_f32 v[46:47], v[30:31], s[64:65], v[46:47] op_sel:[0,0,1] op_sel_hi:[1,0,0] neg_lo:[0,0,1]
	v_pk_add_f32 v[30:31], v[28:29], v[20:21]
	v_pk_add_f32 v[0:1], v[38:39], v[2:3]
	v_pk_add_f32 v[14:15], v[32:33], v[6:7] op_sel:[0,1] op_sel_hi:[1,0] neg_hi:[0,1]
	v_pk_add_f32 v[40:41], v[16:17], v[26:27]
	v_pk_add_f32 v[20:21], v[28:29], v[20:21] neg_lo:[0,1] neg_hi:[0,1]
	v_pk_add_f32 v[38:39], v[38:39], v[2:3] neg_lo:[0,1] neg_hi:[0,1]
	v_pk_add_f32 v[6:7], v[32:33], v[6:7] op_sel:[0,1] op_sel_hi:[1,0] neg_lo:[0,1]
	v_pk_add_f32 v[26:27], v[16:17], v[26:27] neg_lo:[0,1] neg_hi:[0,1]
	v_pk_add_f32 v[16:17], v[24:25], v[18:19]
	v_pk_add_f32 v[32:33], v[36:37], v[42:43]
	v_pk_add_f32 v[2:3], v[34:35], v[44:45]
	v_pk_add_f32 v[28:29], v[4:5], v[46:47]
	v_pk_add_f32 v[18:19], v[24:25], v[18:19] neg_lo:[0,1] neg_hi:[0,1]
	v_pk_add_f32 v[36:37], v[36:37], v[42:43] neg_lo:[0,1] neg_hi:[0,1]
	v_pk_add_f32 v[34:35], v[34:35], v[44:45] neg_lo:[0,1] neg_hi:[0,1]
	v_pk_add_f32 v[4:5], v[4:5], v[46:47] neg_lo:[0,1] neg_hi:[0,1]
	v_pk_add_f32 v[46:47], v[30:31], v[16:17]
	v_pk_add_f32 v[44:45], v[0:1], v[32:33]
	v_pk_add_f32 v[42:43], v[14:15], v[2:3]
	v_pk_add_f32 v[24:25], v[40:41], v[28:29]
	v_pk_add_f32 v[16:17], v[30:31], v[16:17] neg_lo:[0,1] neg_hi:[0,1]
	v_pk_add_f32 v[32:33], v[0:1], v[32:33] neg_lo:[0,1] neg_hi:[0,1]
	v_pk_add_f32 v[2:3], v[14:15], v[2:3] neg_lo:[0,1] neg_hi:[0,1]
	v_pk_add_f32 v[28:29], v[40:41], v[28:29] neg_lo:[0,1] neg_hi:[0,1]
	v_pk_add_f32 v[40:41], v[20:21], v[18:19] op_sel:[0,1] op_sel_hi:[1,0] neg_hi:[0,1]
	v_pk_add_f32 v[14:15], v[38:39], v[36:37] op_sel:[0,1] op_sel_hi:[1,0] neg_hi:[0,1]
	v_pk_add_f32 v[0:1], v[6:7], v[34:35] op_sel:[0,1] op_sel_hi:[1,0] neg_hi:[0,1]
	v_pk_add_f32 v[30:31], v[26:27], v[4:5] op_sel:[0,1] op_sel_hi:[1,0] neg_hi:[0,1]
	v_pk_add_f32 v[20:21], v[20:21], v[18:19] op_sel:[0,1] op_sel_hi:[1,0] neg_lo:[0,1]
	v_pk_add_f32 v[38:39], v[38:39], v[36:37] op_sel:[0,1] op_sel_hi:[1,0] neg_lo:[0,1]
	v_pk_add_f32 v[6:7], v[6:7], v[34:35] op_sel:[0,1] op_sel_hi:[1,0] neg_lo:[0,1]
	v_pk_add_f32 v[26:27], v[26:27], v[4:5] op_sel:[0,1] op_sel_hi:[1,0] neg_lo:[0,1]
	v_pk_mul_f32 v[4:5], v[44:45], v[232:233] op_sel:[0,1] op_sel_hi:[1,1]
	v_pk_mul_f32 v[34:35], v[42:43], v[234:235] op_sel:[0,1] op_sel_hi:[1,1]
	v_pk_fma_f32 v[4:5], v[44:45], v[232:233], v[4:5] op_sel:[0,0,1] op_sel_hi:[1,0,0] neg_lo:[0,0,1]
	v_pk_mul_f32 v[44:45], v[24:25], v[208:209] op_sel:[0,1] op_sel_hi:[1,1]
	v_pk_fma_f32 v[34:35], v[42:43], v[234:235], v[34:35] op_sel:[0,0,1] op_sel_hi:[1,0,0] neg_lo:[0,0,1]
	v_pk_mul_f32 v[42:43], v[40:41], v[210:211] op_sel:[0,1] op_sel_hi:[1,1]
	v_pk_fma_f32 v[44:45], v[24:25], v[208:209], v[44:45] op_sel:[0,0,1] op_sel_hi:[1,0,0] neg_lo:[0,0,1]
; #define LAS __attribute__((address_space(3)))
; __device__ __forceinline__ float lane_read(float v, int src_lane) { return __builtin_bit_cast(float, __builtin_amdgcn_ds_bpermute(src_lane << 2, __builtin_bit_cast(int, v))); }
; #define LDS_BARRIER() do { asm volatile("s_waitcnt lgkmcnt(0)" ::: "memory"); __builtin_amdgcn_s_barrier(); asm volatile("" ::: "memory"); } while (0)
; #define HP_BEGIN(id) unsigned long long hp0_ = 0; if ((id) == PROBE_TIME_PHASE) { __syncthreads(); hp0_ = __builtin_amdgcn_s_memrealtime(); }
; #define LT() ({ int lt_ = tid; asm volatile("" : "+v"(lt_)); lt_; })
; template <bool INV> __device__ __forceinline__ void pass16_s4(LAS f32x2* X, const LAS f32x2* TH, const LAS f32x2* TL, int tid) {
;     ...
; #pragma unroll
;         for (int c = 0; c < 4; ++c)
; #pragma unroll
;             for (int d = 0; d < 4; ++d) P[4 * (c + 4 * d)] = x[4 * c + d];
;     }
; }
; __device__ __forceinline__ void hyena_latent(Frame& F, int l, int ch, LAS f32x2* X, const LAS f32x2* TH, const LAS f32x2* TL, GAS f32x2* KS, const LAS float* CT  , bool wr = true) {
;     ...
; #pragma unroll
;             for (int i = 0; i < 8; ++i) { const int b = LT() + NTHR * i; const LAS f32x4* P = (const LAS f32x4*)(X + 4 * b + ((b >> 4) << 2)); const f32x4 u = P[0], v = P[1];
;                 f32x2 x0 = {u.x, u.y}, x1 = {u.z, u.w}, x2 = {v.x, v.y}, x3 = {v.z, v.w}; r4<false>(x0, x1, x2, x3);
;                 kreg[2 * i] = (f32x4){x0.x, x0.y, x1.x, x1.y}; kreg[2 * i + 1] = (f32x4){x2.x, x2.y, x3.x, x3.y}; }
;             LDS_BARRIER();
;             HP_END(31) }
;             { HP_BEGIN(32)
; #pragma unroll
;             for (int i = 0; i < 8; ++i) { const int g = LT() + NTHR * i, n0 = 4 * g;
;                 f32x4 z0 = pc0[i], z1 = pc1[i];
;                 if (o == 0) { const f32x4 c = pc0[i], d = pc1[i]; const int ln = F.lane;
;                     float l0 = lane_read(c.w, ln - 1), r0 = lane_read(c.x, ln + 1), l1 = lane_read(d.w, ln - 1), r1 = lane_read(d.x, ln + 1);
;                     if (ln == 0) { l0 = n0 > 0 ? hv[n0 - 1] : 0.f; l1 = n0 > 0 ? hv[SEQ + n0 - 1] : 0.f; }
;                     if (ln == 63) { r0 = n0 + 4 < SEQ ? hv[n0 + 4] : 0.f; r1 = n0 + 4 < SEQ ? hv[SEQ + n0 + 4] : 0.f; }
	v_pk_mul_f32 v[24:25], v[14:15], v[204:205] op_sel:[0,1] op_sel_hi:[1,1]
	v_pk_fma_f32 v[40:41], v[40:41], v[210:211], v[42:43] op_sel:[0,0,1] op_sel_hi:[1,0,0] neg_lo:[0,0,1]
	v_pk_mul_f32 v[42:43], v[0:1], v[206:207] op_sel:[0,1] op_sel_hi:[1,1]
	v_pk_fma_f32 v[14:15], v[14:15], v[204:205], v[24:25] op_sel:[0,0,1] op_sel_hi:[1,0,0] neg_lo:[0,0,1]
	v_pk_mul_f32 v[24:25], v[30:31], v[200:201] op_sel:[0,1] op_sel_hi:[1,1]
	v_pk_fma_f32 v[42:43], v[0:1], v[206:207], v[42:43] op_sel:[0,0,1] op_sel_hi:[1,0,0] neg_lo:[0,0,1]
	v_pk_mul_f32 v[0:1], v[16:17], v[202:203] op_sel:[0,1] op_sel_hi:[1,1]
	v_pk_fma_f32 v[30:31], v[30:31], v[200:201], v[24:25] op_sel:[0,0,1] op_sel_hi:[1,0,0] neg_lo:[0,0,1]
	v_pk_mul_f32 v[24:25], v[32:33], v[196:197] op_sel:[0,1] op_sel_hi:[1,1]
	v_pk_fma_f32 v[16:17], v[16:17], v[202:203], v[0:1] op_sel:[0,0,1] op_sel_hi:[1,0,0] neg_lo:[0,0,1]
	v_pk_mul_f32 v[0:1], v[2:3], v[198:199] op_sel:[0,1] op_sel_hi:[1,1]
	v_pk_fma_f32 v[32:33], v[32:33], v[196:197], v[24:25] op_sel:[0,0,1] op_sel_hi:[1,0,0] neg_lo:[0,0,1]
	v_pk_mul_f32 v[24:25], v[28:29], v[192:193] op_sel:[0,1] op_sel_hi:[1,1]
	v_pk_fma_f32 v[2:3], v[2:3], v[198:199], v[0:1] op_sel:[0,0,1] op_sel_hi:[1,0,0] neg_lo:[0,0,1]
	v_pk_mul_f32 v[0:1], v[20:21], v[194:195] op_sel:[0,1] op_sel_hi:[1,1]
	v_pk_fma_f32 v[28:29], v[28:29], v[192:193], v[24:25] op_sel:[0,0,1] op_sel_hi:[1,0,0] neg_lo:[0,0,1]
	v_pk_mul_f32 v[24:25], v[38:39], v[188:189] op_sel:[0,1] op_sel_hi:[1,1]
	v_pk_fma_f32 v[0:1], v[20:21], v[194:195], v[0:1] op_sel:[0,0,1] op_sel_hi:[1,0,0] neg_lo:[0,0,1]
	v_pk_mul_f32 v[20:21], v[6:7], v[190:191] op_sel:[0,1] op_sel_hi:[1,1]
	v_pk_fma_f32 v[38:39], v[38:39], v[188:189], v[24:25] op_sel:[0,0,1] op_sel_hi:[1,0,0] neg_lo:[0,0,1]
	v_pk_mul_f32 v[24:25], v[26:27], v[186:187] op_sel:[0,1] op_sel_hi:[1,1]
	v_pk_fma_f32 v[20:21], v[6:7], v[190:191], v[20:21] op_sel:[0,0,1] op_sel_hi:[1,0,0] neg_lo:[0,0,1]
	v_pk_fma_f32 v[26:27], v[26:27], v[186:187], v[24:25] op_sel:[0,0,1] op_sel_hi:[1,0,0] neg_lo:[0,0,1]
	ds_write_b64 v151, v[46:47] offset:0
	ds_write_b64 v151, v[4:5] offset:32
	ds_write_b64 v151, v[34:35] offset:64
	ds_write_b64 v151, v[44:45] offset:96
	ds_write_b64 v151, v[40:41] offset:128
	ds_write_b64 v151, v[14:15] offset:160
	ds_write_b64 v151, v[42:43] offset:192
	ds_write_b64 v151, v[30:31] offset:224
	ds_write_b64 v151, v[16:17] offset:256
	ds_write_b64 v151, v[32:33] offset:288
	ds_write_b64 v151, v[2:3] offset:320
	ds_write_b64 v151, v[28:29] offset:352
	ds_write_b64 v151, v[0:1] offset:384
	ds_write_b64 v151, v[38:39] offset:416
	ds_write_b64 v151, v[20:21] offset:448
	ds_write_b64 v151, v[26:27] offset:480
	s_cbranch_scc1 .LBB0_700
	v_mov_b32_e32 v0, v140
	s_waitcnt lgkmcnt(0)
	s_barrier
	v_mov_b32_e32 v128, v140
	v_lshlrev_b32_e32 v1, 5, v0
	v_lshlrev_b32_e32 v0, 1, v0
	v_and_b32_e32 v0, 0xffffffe0, v0
	v_add3_u32 v0, 0, v1, v0
	ds_read_b128 v[56:59], v0
	ds_read_b128 v[60:63], v0 offset:16
	v_mov_b32_e32 v0, v140
	s_and_b64 vcc, s[26:27], exec
	v_add_u32_e32 v0, 0x200, v0
	v_lshlrev_b32_e32 v1, 5, v0
	v_lshlrev_b32_e32 v0, 1, v0
	v_and_b32_e32 v0, 0xffffffe0, v0
	v_add3_u32 v0, 0, v1, v0
	ds_read_b128 v[48:51], v0
	ds_read_b128 v[52:55], v0 offset:16
	v_mov_b32_e32 v0, v140
	s_nop 0
	v_add_u32_e32 v0, 0x400, v0
	v_lshlrev_b32_e32 v1, 5, v0
	v_lshlrev_b32_e32 v0, 1, v0
	v_and_b32_e32 v0, 0xffffffe0, v0
	v_add3_u32 v0, 0, v1, v0
	ds_read_b128 v[40:43], v0
	ds_read_b128 v[44:47], v0 offset:16
	v_mov_b32_e32 v0, v140
	s_nop 0
	v_add_u32_e32 v0, 0x600, v0
	v_lshlrev_b32_e32 v1, 5, v0
	v_lshlrev_b32_e32 v0, 1, v0
	v_and_b32_e32 v0, 0xffffffe0, v0
	v_add3_u32 v0, 0, v1, v0
	ds_read_b128 v[32:35], v0
	ds_read_b128 v[36:39], v0 offset:16
	v_mov_b32_e32 v0, v140
	s_nop 0
	v_add_u32_e32 v0, 0x800, v0
	v_lshlrev_b32_e32 v1, 5, v0
	v_lshlrev_b32_e32 v0, 1, v0
	v_and_b32_e32 v0, 0xffffffe0, v0
	v_add3_u32 v0, 0, v1, v0
	ds_read_b128 v[24:27], v0
	ds_read_b128 v[28:31], v0 offset:16
	v_mov_b32_e32 v0, v140
	s_nop 0
	v_add_u32_e32 v0, 0xa00, v0
	v_lshlrev_b32_e32 v1, 5, v0
	v_lshlrev_b32_e32 v0, 1, v0
	v_and_b32_e32 v0, 0xffffffe0, v0
	v_add3_u32 v0, 0, v1, v0
	ds_read_b128 v[12:15], v0
	ds_read_b128 v[20:23], v0 offset:16
	v_mov_b32_e32 v0, v140
	s_nop 0
	v_add_u32_e32 v0, 0xc00, v0
	v_lshlrev_b32_e32 v1, 5, v0
	v_lshlrev_b32_e32 v0, 1, v0
	v_and_b32_e32 v0, 0xffffffe0, v0
	v_add3_u32 v0, 0, v1, v0
	ds_read_b128 v[4:7], v0
	ds_read_b128 v[16:19], v0 offset:16
	v_mov_b32_e32 v0, v140
	s_nop 0
	v_add_u32_e32 v0, 0xe00, v0
	v_lshlrev_b32_e32 v1, 5, v0
	v_lshlrev_b32_e32 v0, 1, v0
	v_and_b32_e32 v0, 0xffffffe0, v0
	v_add3_u32 v8, 0, v1, v0
	ds_read_b128 v[0:3], v8
	ds_read_b128 v[8:11], v8 offset:16
	s_waitcnt lgkmcnt(0)
	s_barrier
	s_nop 0
	v_lshlrev_b32_e32 v176, 2, v128
	s_cbranch_vccz .LBB0_715
	s_waitcnt vmcnt(15)
	ds_bpermute_b32 v134, v143, v127
	ds_bpermute_b32 v133, v145, v124
	s_waitcnt vmcnt(14)
	ds_bpermute_b32 v130, v143, v123
	ds_bpermute_b32 v129, v145, v120
	s_and_saveexec_b64 s[36:37], s[8:9]
	s_cbranch_execz .LBB0_708
	v_cmp_lt_i32_e32 vcc, 0, v176
	s_waitcnt lgkmcnt(1)
	v_mov_b32_e32 v130, 0
	v_mov_b32_e32 v134, 0
	s_and_saveexec_b64 s[38:39], vcc
	s_cbranch_execz .LBB0_705
	v_lshl_add_u64 v[134:135], v[176:177], 2, s[20:21]
	global_load_dword v134, v[134:135], off offset:-4

; #define LAS __attribute__((address_space(3)))
; __device__ __forceinline__ f32x2 cmul(f32x2 a, f32x2 b) { return (f32x2){a.x * b.x - a.y * b.y, a.x * b.y + a.y * b.x}; }
; __device__ __forceinline__ f32x2 tw32k(const LAS f32x2* TH, const LAS f32x2* TL, int n) { return cmul(TH[n >> 7], TL[n & 127]); }
; template <bool INV> __device__ __forceinline__ void dft16(f32x2 (&x)[16]) {
; #pragma unroll
;     for (int b = 0; b < 4; ++b) r4<INV>(x[b], x[4 + b], x[8 + b], x[12 + b]);
;     const float sg = INV ? -1.f : 1.f;
;     const f32x2 W1 = {0.92387953251f, -0.38268343236f * sg}, W2 = {0.70710678118f, -0.70710678118f * sg}, W3 = {0.38268343236f, -0.92387953251f * sg},
;                 W4 = {0.f, -1.f * sg}, W6 = {-0.70710678118f, -0.70710678118f * sg}, W9 = {-0.92387953251f, 0.38268343236f * sg};
;     x[5] = cmul(x[5], W1); x[9] = cmul(x[9], W2); x[13] = cmul(x[13], W3);
;     x[6] = cmul(x[6], W2); x[10] = cmul(x[10], W4); x[14] = cmul(x[14], W6);
;     x[7] = cmul(x[7], W3); x[11] = cmul(x[11], W6); x[15] = cmul(x[15], W9);
; #pragma unroll
;     for (int c = 0; c < 4; ++c) r4<INV>(x[4 * c], x[4 * c + 1], x[4 * c + 2], x[4 * c + 3]);
; }
; template <bool INV> __device__ __forceinline__ void bfly16(f32x2 (&x)[16], const LAS f32x2* TH, const LAS f32x2* TL, int tw) {
;     f32x2 W = tw32k(TH, TL, tw); if (INV) W.y = -W.y;
;     if (INV) { f32x2 p = W;
; #pragma unroll
;         for (int q = 1; q < 16; ++q) { x[q] = cmul(x[q], p); if (q < 15) p = cmul(p, W); } }
;     dft16<INV>(x);
;     if (!INV) { f32x2 p = W;
; #pragma unroll
;         for (int r = 1; r < 16; ++r) { x[4 * (r & 3) + (r >> 2)] = cmul(x[4 * (r & 3) + (r >> 2)], p); if (r < 15) p = cmul(p, W); } }
; }
; template <bool INV> __device__ __forceinline__ void pass16(LAS f32x2* X, const LAS f32x2* TH, const LAS f32x2* TL, int base, int stride, int tw) {
;     f32x2 x[16];
; #pragma unroll
;     for (int q = 0; q < 16; ++q) x[q] = X[base + q * stride];
;     bfly16<INV>(x, TH, TL, tw);
; #pragma unroll
;     for (int c = 0; c < 4; ++c)
; #pragma unroll
;         for (int d = 0; d < 4; ++d) X[base + (c + 4 * d) * stride] = x[4 * c + d];
; }
.LBB0_846:
	v_add_u32_e32 v128, s0, v140
	v_lshrrev_b32_e32 v147, 6, v128
	v_and_b32_e32 v157, 63, v128
	v_lshlrev_b32_e32 v151, 5, v147
	v_lshlrev_b32_e32 v155, 3, v147
	v_lshlrev_b32_e32 v157, 4, v157
	v_lshl_add_u32 v151, v128, 3, v151
	v_add_u32_e32 v155, 0x26000, v155
	v_add_u32_e32 v157, 0x26400, v157
	v_add_u32_e32 v176, 0x11000, v151
	ds_read_b64 v[64:65], v155
	ds_read_b64 v[66:67], v157
	ds_read_b64 v[68:69], v151 offset:0
	ds_read_b64 v[70:71], v176 offset:0
	ds_read_b64 v[72:73], v151 offset:8704
	ds_read_b64 v[74:75], v176 offset:8704
	ds_read_b64 v[76:77], v151 offset:17408
	ds_read_b64 v[78:79], v176 offset:17408
	ds_read_b64 v[80:81], v151 offset:26112
	ds_read_b64 v[82:83], v176 offset:26112
	ds_read_b64 v[84:85], v151 offset:34816
	ds_read_b64 v[86:87], v176 offset:34816
	ds_read_b64 v[88:89], v151 offset:43520
	ds_read_b64 v[90:91], v176 offset:43520
	ds_read_b64 v[92:93], v151 offset:52224
	ds_read_b64 v[94:95], v176 offset:52224
	ds_read_b64 v[96:97], v151 offset:60928
	ds_read_b64 v[98:99], v176 offset:60928
	s_cmp_eq_u32 s0, 0
	s_movk_i32 s0, 0x200
	s_mov_b64 s[12:13], 0
	s_waitcnt lgkmcnt(15)
	v_pk_mul_f32 v[100:101], v[64:65], v[66:67] op_sel:[0,1] op_sel_hi:[1,1]
	s_nop 0
	v_pk_fma_f32 v[100:101], v[64:65], v[66:67], v[100:101] op_sel:[0,0,1] op_sel_hi:[1,0,0] neg_lo:[0,0,1]
	s_nop 0
	v_pk_mul_f32 v[66:67], v[100:101], v[100:101] op_sel:[0,1] op_sel_hi:[1,1]
	s_nop 0
	v_pk_fma_f32 v[66:67], v[100:101], v[100:101], v[66:67] op_sel:[0,0,1] op_sel_hi:[1,0,0] neg_lo:[0,0,1]
	s_nop 0
	v_pk_mul_f32 v[64:65], v[66:67], v[100:101] op_sel:[0,1] op_sel_hi:[1,1]
	v_pk_mul_f32 v[102:103], v[66:67], v[66:67] op_sel:[0,1] op_sel_hi:[1,1]
	v_pk_fma_f32 v[64:65], v[66:67], v[100:101], v[64:65] op_sel:[0,0,1] op_sel_hi:[1,0,0] neg_lo:[0,0,1]
	v_pk_fma_f32 v[102:103], v[66:67], v[66:67], v[102:103] op_sel:[0,0,1] op_sel_hi:[1,0,0] neg_lo:[0,0,1]
	s_nop 0
	v_pk_mul_f32 v[104:105], v[102:103], v[100:101] op_sel:[0,1] op_sel_hi:[1,1]
	v_pk_mul_f32 v[106:107], v[102:103], v[66:67] op_sel:[0,1] op_sel_hi:[1,1]
	v_pk_mul_f32 v[108:109], v[102:103], v[64:65] op_sel:[0,1] op_sel_hi:[1,1]
	v_pk_fma_f32 v[104:105], v[102:103], v[100:101], v[104:105] op_sel:[0,0,1] op_sel_hi:[1,0,0] neg_lo:[0,0,1]
	v_pk_fma_f32 v[106:107], v[102:103], v[66:67], v[106:107] op_sel:[0,0,1] op_sel_hi:[1,0,0] neg_lo:[0,0,1]
	v_pk_fma_f32 v[108:109], v[102:103], v[64:65], v[108:109] op_sel:[0,0,1] op_sel_hi:[1,0,0] neg_lo:[0,0,1]
	v_pk_mul_f32 v[110:111], v[102:103], v[102:103] op_sel:[0,1] op_sel_hi:[1,1]
	s_nop 0
	v_pk_fma_f32 v[110:111], v[102:103], v[102:103], v[110:111] op_sel:[0,0,1] op_sel_hi:[1,0,0] neg_lo:[0,0,1]
	s_nop 0
	v_pk_mul_f32 v[112:113], v[110:111], v[100:101] op_sel:[0,1] op_sel_hi:[1,1]
	v_pk_mul_f32 v[114:115], v[110:111], v[66:67] op_sel:[0,1] op_sel_hi:[1,1]
	v_pk_mul_f32 v[116:117], v[110:111], v[64:65] op_sel:[0,1] op_sel_hi:[1,1]
	v_pk_fma_f32 v[112:113], v[110:111], v[100:101], v[112:113] op_sel:[0,0,1] op_sel_hi:[1,0,0] neg_lo:[0,0,1]
	v_pk_fma_f32 v[114:115], v[110:111], v[66:67], v[114:115] op_sel:[0,0,1] op_sel_hi:[1,0,0] neg_lo:[0,0,1]
	v_pk_fma_f32 v[116:117], v[110:111], v[64:65], v[116:117] op_sel:[0,0,1] op_sel_hi:[1,0,0] neg_lo:[0,0,1]
	v_pk_mul_f32 v[118:119], v[110:111], v[102:103] op_sel:[0,1] op_sel_hi:[1,1]
	v_pk_mul_f32 v[120:121], v[110:111], v[104:105] op_sel:[0,1] op_sel_hi:[1,1]
	v_pk_mul_f32 v[122:123], v[110:111], v[106:107] op_sel:[0,1] op_sel_hi:[1,1]
	v_pk_fma_f32 v[118:119], v[110:111], v[102:103], v[118:119] op_sel:[0,0,1] op_sel_hi:[1,0,0] neg_lo:[0,0,1]
	v_pk_fma_f32 v[120:121], v[110:111], v[104:105], v[120:121] op_sel:[0,0,1] op_sel_hi:[1,0,0] neg_lo:[0,0,1]
	v_pk_fma_f32 v[122:123], v[110:111], v[106:107], v[122:123] op_sel:[0,0,1] op_sel_hi:[1,0,0] neg_lo:[0,0,1]
	v_pk_mul_f32 v[124:125], v[110:111], v[108:109] op_sel:[0,1] op_sel_hi:[1,1]
	s_nop 0
	v_pk_fma_f32 v[124:125], v[110:111], v[108:109], v[124:125] op_sel:[0,0,1] op_sel_hi:[1,0,0] neg_lo:[0,0,1]
	s_waitcnt lgkmcnt(14)
	v_pk_add_f32 v[126:127], v[68:69], v[70:71]
	s_waitcnt lgkmcnt(12)
	v_pk_add_f32 v[170:171], v[72:73], v[74:75]
	s_waitcnt lgkmcnt(10)
	v_pk_add_f32 v[172:173], v[76:77], v[78:79]
	s_waitcnt lgkmcnt(8)
	v_pk_add_f32 v[174:175], v[80:81], v[82:83]
	v_pk_add_f32 v[68:69], v[68:69], v[70:71] neg_lo:[0,1] neg_hi:[0,1]
	v_pk_add_f32 v[74:75], v[72:73], v[74:75] neg_lo:[0,1] neg_hi:[0,1]
	v_pk_add_f32 v[78:79], v[76:77], v[78:79] neg_lo:[0,1] neg_hi:[0,1]
	v_pk_add_f32 v[82:83], v[80:81], v[82:83] neg_lo:[0,1] neg_hi:[0,1]
	s_waitcnt lgkmcnt(6)
	v_pk_add_f32 v[80:81], v[84:85], v[86:87]
	s_waitcnt lgkmcnt(4)
	v_pk_add_f32 v[76:77], v[88:89], v[90:91]
	s_waitcnt lgkmcnt(2)
	v_pk_add_f32 v[72:73], v[92:93], v[94:95]
	s_waitcnt lgkmcnt(0)
; #define LAS __attribute__((address_space(3)))
; __device__ __forceinline__ f32x2 cmul(f32x2 a, f32x2 b) { return (f32x2){a.x * b.x - a.y * b.y, a.x * b.y + a.y * b.x}; }
; __device__ __forceinline__ f32x2 tw32k(const LAS f32x2* TH, const LAS f32x2* TL, int n) { return cmul(TH[n >> 7], TL[n & 127]); }
; template <bool INV> __device__ __forceinline__ void dft16(f32x2 (&x)[16]) {
; #pragma unroll
;     for (int b = 0; b < 4; ++b) r4<INV>(x[b], x[4 + b], x[8 + b], x[12 + b]);
;     const float sg = INV ? -1.f : 1.f;
;     const f32x2 W1 = {0.92387953251f, -0.38268343236f * sg}, W2 = {0.70710678118f, -0.70710678118f * sg}, W3 = {0.38268343236f, -0.92387953251f * sg},
;                 W4 = {0.f, -1.f * sg}, W6 = {-0.70710678118f, -0.70710678118f * sg}, W9 = {-0.92387953251f, 0.38268343236f * sg};
;     x[5] = cmul(x[5], W1); x[9] = cmul(x[9], W2); x[13] = cmul(x[13], W3);
;     x[6] = cmul(x[6], W2); x[10] = cmul(x[10], W4); x[14] = cmul(x[14], W6);
;     x[7] = cmul(x[7], W3); x[11] = cmul(x[11], W6); x[15] = cmul(x[15], W9);
; #pragma unroll
;     for (int c = 0; c < 4; ++c) r4<INV>(x[4 * c], x[4 * c + 1], x[4 * c + 2], x[4 * c + 3]);
; }
; template <bool INV> __device__ __forceinline__ void bfly16(f32x2 (&x)[16], const LAS f32x2* TH, const LAS f32x2* TL, int tw) {
;     f32x2 W = tw32k(TH, TL, tw); if (INV) W.y = -W.y;
;     if (INV) { f32x2 p = W;
; #pragma unroll
;         for (int q = 1; q < 16; ++q) { x[q] = cmul(x[q], p); if (q < 15) p = cmul(p, W); } }
;     dft16<INV>(x);
;     if (!INV) { f32x2 p = W;
; #pragma unroll
;         for (int r = 1; r < 16; ++r) { x[4 * (r & 3) + (r >> 2)] = cmul(x[4 * (r & 3) + (r >> 2)], p); if (r < 15) p = cmul(p, W); } }
; }
	v_pk_add_f32 v[70:71], v[96:97], v[98:99]
	v_pk_add_f32 v[84:85], v[84:85], v[86:87] neg_lo:[0,1] neg_hi:[0,1]
	v_pk_add_f32 v[88:89], v[88:89], v[90:91] neg_lo:[0,1] neg_hi:[0,1]
	v_pk_add_f32 v[92:93], v[92:93], v[94:95] neg_lo:[0,1] neg_hi:[0,1]
	v_pk_add_f32 v[96:97], v[96:97], v[98:99] neg_lo:[0,1] neg_hi:[0,1]
	v_pk_add_f32 v[98:99], v[126:127], v[80:81]
	v_pk_add_f32 v[94:95], v[170:171], v[76:77]
	v_pk_add_f32 v[90:91], v[172:173], v[72:73]
	v_pk_add_f32 v[86:87], v[174:175], v[70:71]
	v_pk_add_f32 v[80:81], v[126:127], v[80:81] neg_lo:[0,1] neg_hi:[0,1]
	v_pk_add_f32 v[170:171], v[170:171], v[76:77] neg_lo:[0,1] neg_hi:[0,1]
	v_pk_add_f32 v[172:173], v[172:173], v[72:73] neg_lo:[0,1] neg_hi:[0,1]
	v_pk_add_f32 v[174:175], v[174:175], v[70:71] neg_lo:[0,1] neg_hi:[0,1]
	v_pk_add_f32 v[70:71], v[68:69], v[84:85] op_sel:[0,1] op_sel_hi:[1,0] neg_hi:[0,1]
	v_pk_add_f32 v[72:73], v[74:75], v[88:89] op_sel:[0,1] op_sel_hi:[1,0] neg_hi:[0,1]
	v_pk_add_f32 v[76:77], v[78:79], v[92:93] op_sel:[0,1] op_sel_hi:[1,0] neg_hi:[0,1]
	v_pk_add_f32 v[126:127], v[82:83], v[96:97] op_sel:[0,1] op_sel_hi:[1,0] neg_hi:[0,1]
	v_pk_add_f32 v[84:85], v[68:69], v[84:85] op_sel:[0,1] op_sel_hi:[1,0] neg_lo:[0,1]
	v_pk_add_f32 v[74:75], v[74:75], v[88:89] op_sel:[0,1] op_sel_hi:[1,0] neg_lo:[0,1]
	v_pk_add_f32 v[78:79], v[78:79], v[92:93] op_sel:[0,1] op_sel_hi:[1,0] neg_lo:[0,1]
	v_pk_add_f32 v[82:83], v[82:83], v[96:97] op_sel:[0,1] op_sel_hi:[1,0] neg_lo:[0,1]
	v_pk_mul_f32 v[96:97], v[72:73], s[70:71] op_sel_hi:[1,0]
	v_pk_mul_f32 v[92:93], v[170:171], s[72:73] op_sel_hi:[1,0]
	v_pk_mul_f32 v[88:89], v[74:75], s[64:65] op_sel_hi:[1,0]
	v_pk_mul_f32 v[68:69], v[76:77], s[72:73] op_sel_hi:[1,0]
	v_pk_mul_f32 v[178:179], v[78:79], s[72:73] op_sel_hi:[1,0]
	v_pk_mul_f32 v[180:181], v[126:127], s[64:65] op_sel_hi:[1,0]
	v_pk_mul_f32 v[182:183], v[174:175], s[72:73] op_sel_hi:[1,0]
	v_pk_mul_f32 v[184:185], v[82:83], s[82:83] op_sel_hi:[1,0]
	v_pk_fma_f32 v[72:73], v[72:73], s[44:45], v[96:97] op_sel:[0,0,1] op_sel_hi:[1,0,0] neg_lo:[0,0,1]
	v_pk_fma_f32 v[170:171], v[170:171], s[76:77], v[92:93] op_sel:[0,0,1] op_sel_hi:[1,0,0] neg_lo:[0,0,1]
	v_pk_fma_f32 v[74:75], v[74:75], s[82:83], v[88:89] op_sel:[0,0,1] op_sel_hi:[1,0,0] neg_lo:[0,0,1]
	v_pk_fma_f32 v[68:69], v[76:77], s[76:77], v[68:69] op_sel:[0,0,1] op_sel_hi:[1,0,0] neg_lo:[0,0,1]
	v_pk_fma_f32 v[78:79], v[78:79], s[72:73], v[178:179] op_sel:[0,0,1] op_sel_hi:[1,0,0] neg_lo:[0,0,1]
	v_pk_fma_f32 v[180:181], v[126:127], s[82:83], v[180:181] op_sel:[0,0,1] op_sel_hi:[1,0,0] neg_lo:[0,0,1]
	v_pk_fma_f32 v[174:175], v[174:175], s[72:73], v[182:183] op_sel:[0,0,1] op_sel_hi:[1,0,0] neg_lo:[0,0,1]
	v_pk_fma_f32 v[82:83], v[82:83], s[64:65], v[184:185] op_sel:[0,0,1] op_sel_hi:[1,0,0] neg_lo:[0,0,1]
	v_pk_add_f32 v[184:185], v[98:99], v[90:91]
	v_pk_add_f32 v[182:183], v[70:71], v[68:69]
	v_pk_add_f32 v[126:127], v[80:81], v[172:173] op_sel:[0,1] op_sel_hi:[1,0] neg_hi:[0,1]
	v_pk_add_f32 v[178:179], v[84:85], v[78:79]
	v_pk_add_f32 v[90:91], v[98:99], v[90:91] neg_lo:[0,1] neg_hi:[0,1]
	v_pk_add_f32 v[68:69], v[70:71], v[68:69] neg_lo:[0,1] neg_hi:[0,1]
	v_pk_add_f32 v[172:173], v[80:81], v[172:173] op_sel:[0,1] op_sel_hi:[1,0] neg_lo:[0,1]
	v_pk_add_f32 v[78:79], v[84:85], v[78:79] neg_lo:[0,1] neg_hi:[0,1]
	v_pk_add_f32 v[84:85], v[94:95], v[86:87]
	v_pk_add_f32 v[80:81], v[72:73], v[180:181]
	v_pk_add_f32 v[70:71], v[170:171], v[174:175]
	v_pk_add_f32 v[98:99], v[74:75], v[82:83]
	v_pk_add_f32 v[94:95], v[94:95], v[86:87] neg_lo:[0,1] neg_hi:[0,1]
	v_pk_add_f32 v[180:181], v[72:73], v[180:181] neg_lo:[0,1] neg_hi:[0,1]
	v_pk_add_f32 v[174:175], v[170:171], v[174:175] neg_lo:[0,1] neg_hi:[0,1]
	v_pk_add_f32 v[82:83], v[74:75], v[82:83] neg_lo:[0,1] neg_hi:[0,1]
	v_pk_add_f32 v[74:75], v[184:185], v[84:85]
	v_pk_add_f32 v[170:171], v[182:183], v[80:81]
	v_pk_add_f32 v[72:73], v[126:127], v[70:71]
	v_pk_add_f32 v[86:87], v[178:179], v[98:99]
	v_pk_add_f32 v[84:85], v[184:185], v[84:85] neg_lo:[0,1] neg_hi:[0,1]
	v_pk_add_f32 v[182:183], v[182:183], v[80:81] neg_lo:[0,1] neg_hi:[0,1]
	v_pk_add_f32 v[126:127], v[126:127], v[70:71] neg_lo:[0,1] neg_hi:[0,1]
	v_pk_add_f32 v[98:99], v[178:179], v[98:99] neg_lo:[0,1] neg_hi:[0,1]
	v_pk_add_f32 v[178:179], v[90:91], v[94:95] op_sel:[0,1] op_sel_hi:[1,0] neg_hi:[0,1]
	v_pk_add_f32 v[70:71], v[68:69], v[180:181] op_sel:[0,1] op_sel_hi:[1,0] neg_hi:[0,1]
	v_pk_add_f32 v[80:81], v[172:173], v[174:175] op_sel:[0,1] op_sel_hi:[1,0] neg_hi:[0,1]
	v_pk_add_f32 v[184:185], v[78:79], v[82:83] op_sel:[0,1] op_sel_hi:[1,0] neg_hi:[0,1]
	v_pk_add_f32 v[90:91], v[90:91], v[94:95] op_sel:[0,1] op_sel_hi:[1,0] neg_lo:[0,1]
	v_pk_add_f32 v[68:69], v[68:69], v[180:181] op_sel:[0,1] op_sel_hi:[1,0] neg_lo:[0,1]
	v_pk_add_f32 v[172:173], v[172:173], v[174:175] op_sel:[0,1] op_sel_hi:[1,0] neg_lo:[0,1]
	v_pk_add_f32 v[82:83], v[78:79], v[82:83] op_sel:[0,1] op_sel_hi:[1,0] neg_lo:[0,1]
	v_pk_mul_f32 v[78:79], v[170:171], v[100:101] op_sel:[0,1] op_sel_hi:[1,1]
	v_pk_mul_f32 v[174:175], v[72:73], v[66:67] op_sel:[0,1] op_sel_hi:[1,1]
	v_pk_fma_f32 v[170:171], v[170:171], v[100:101], v[78:79] op_sel:[0,0,1] op_sel_hi:[1,0,0] neg_lo:[0,0,1]
	v_pk_mul_f32 v[100:101], v[86:87], v[64:65] op_sel:[0,1] op_sel_hi:[1,1]
	v_pk_fma_f32 v[72:73], v[72:73], v[66:67], v[174:175] op_sel:[0,0,1] op_sel_hi:[1,0,0] neg_lo:[0,0,1]
	v_pk_mul_f32 v[174:175], v[178:179], v[102:103] op_sel:[0,1] op_sel_hi:[1,1]
	v_pk_fma_f32 v[86:87], v[86:87], v[64:65], v[100:101] op_sel:[0,0,1] op_sel_hi:[1,0,0] neg_lo:[0,0,1]
	v_pk_mul_f32 v[100:101], v[70:71], v[104:105] op_sel:[0,1] op_sel_hi:[1,1]
; #define LAS __attribute__((address_space(3)))
; template <bool INV> __device__ __forceinline__ void pass16_s64(LAS f32x2* X, const LAS f32x2* TH, int base, int j) {
;     f32x2 x[16];
; #pragma unroll
;     for (int q = 0; q < 16; ++q) x[q] = X[base + q * 68];
;     bfly16_tab<INV>(x, TH - 2048, 64, j);
; #pragma unroll
;     for (int c = 0; c < 4; ++c)
; #pragma unroll
;         for (int d = 0; d < 4; ++d) X[base + (c + 4 * d) * 68] = x[4 * c + d];
; }
; template <bool INV> __device__ __forceinline__ void pass16(LAS f32x2* X, const LAS f32x2* TH, const LAS f32x2* TL, int base, int stride, int tw) {
;     f32x2 x[16];
; #pragma unroll
;     for (int q = 0; q < 16; ++q) x[q] = X[base + q * stride];
;     bfly16<INV>(x, TH, TL, tw);
; #pragma unroll
;     for (int c = 0; c < 4; ++c)
; #pragma unroll
;         for (int d = 0; d < 4; ++d) X[base + (c + 4 * d) * stride] = x[4 * c + d];
	v_pk_fma_f32 v[102:103], v[178:179], v[102:103], v[174:175] op_sel:[0,0,1] op_sel_hi:[1,0,0] neg_lo:[0,0,1]
	v_pk_mul_f32 v[178:179], v[80:81], v[106:107] op_sel:[0,1] op_sel_hi:[1,1]
	v_pk_fma_f32 v[100:101], v[70:71], v[104:105], v[100:101] op_sel:[0,0,1] op_sel_hi:[1,0,0] neg_lo:[0,0,1]
	v_pk_mul_f32 v[104:105], v[184:185], v[108:109] op_sel:[0,1] op_sel_hi:[1,1]
	v_pk_fma_f32 v[80:81], v[80:81], v[106:107], v[178:179] op_sel:[0,0,1] op_sel_hi:[1,0,0] neg_lo:[0,0,1]
	v_pk_mul_f32 v[106:107], v[84:85], v[110:111] op_sel:[0,1] op_sel_hi:[1,1]
	v_pk_fma_f32 v[184:185], v[184:185], v[108:109], v[104:105] op_sel:[0,0,1] op_sel_hi:[1,0,0] neg_lo:[0,0,1]
	v_pk_mul_f32 v[108:109], v[182:183], v[112:113] op_sel:[0,1] op_sel_hi:[1,1]
	v_pk_fma_f32 v[110:111], v[84:85], v[110:111], v[106:107] op_sel:[0,0,1] op_sel_hi:[1,0,0] neg_lo:[0,0,1]
	v_pk_mul_f32 v[84:85], v[126:127], v[114:115] op_sel:[0,1] op_sel_hi:[1,1]
	v_pk_fma_f32 v[108:109], v[182:183], v[112:113], v[108:109] op_sel:[0,0,1] op_sel_hi:[1,0,0] neg_lo:[0,0,1]
	v_pk_mul_f32 v[112:113], v[98:99], v[116:117] op_sel:[0,1] op_sel_hi:[1,1]
	v_pk_fma_f32 v[126:127], v[126:127], v[114:115], v[84:85] op_sel:[0,0,1] op_sel_hi:[1,0,0] neg_lo:[0,0,1]
	v_pk_mul_f32 v[114:115], v[90:91], v[118:119] op_sel:[0,1] op_sel_hi:[1,1]
	v_pk_fma_f32 v[112:113], v[98:99], v[116:117], v[112:113] op_sel:[0,0,1] op_sel_hi:[1,0,0] neg_lo:[0,0,1]
	v_pk_mul_f32 v[116:117], v[68:69], v[120:121] op_sel:[0,1] op_sel_hi:[1,1]
	v_pk_fma_f32 v[114:115], v[90:91], v[118:119], v[114:115] op_sel:[0,0,1] op_sel_hi:[1,0,0] neg_lo:[0,0,1]
	v_pk_mul_f32 v[118:119], v[172:173], v[122:123] op_sel:[0,1] op_sel_hi:[1,1]
	v_pk_fma_f32 v[116:117], v[68:69], v[120:121], v[116:117] op_sel:[0,0,1] op_sel_hi:[1,0,0] neg_lo:[0,0,1]
	v_pk_mul_f32 v[68:69], v[82:83], v[124:125] op_sel:[0,1] op_sel_hi:[1,1]
	v_pk_fma_f32 v[122:123], v[172:173], v[122:123], v[118:119] op_sel:[0,0,1] op_sel_hi:[1,0,0] neg_lo:[0,0,1]
	v_pk_fma_f32 v[68:69], v[82:83], v[124:125], v[68:69] op_sel:[0,0,1] op_sel_hi:[1,0,0] neg_lo:[0,0,1]
	ds_write_b64 v151, v[74:75] offset:0
	ds_write_b64 v151, v[170:171] offset:8704
	ds_write_b64 v151, v[72:73] offset:17408
	ds_write_b64 v151, v[86:87] offset:26112
	ds_write_b64 v151, v[102:103] offset:34816
	ds_write_b64 v151, v[100:101] offset:43520
	ds_write_b64 v151, v[80:81] offset:52224
	ds_write_b64 v151, v[184:185] offset:60928
	ds_write_b64 v176, v[110:111] offset:0
	ds_write_b64 v176, v[108:109] offset:8704
	ds_write_b64 v176, v[126:127] offset:17408
	ds_write_b64 v176, v[112:113] offset:26112
	ds_write_b64 v176, v[114:115] offset:34816
	ds_write_b64 v176, v[116:117] offset:43520
	ds_write_b64 v176, v[122:123] offset:52224
	ds_write_b64 v176, v[68:69] offset:60928
	s_cbranch_scc1 .LBB0_846
	s_waitcnt lgkmcnt(0)
	s_barrier
	s_mov_b32 s0, 0
	s_mov_b64 s[12:13], -1
	ds_read2st64_b64 v[232:235], v139 offset0:1 offset1:2
	ds_read2st64_b64 v[208:211], v139 offset0:3 offset1:4
	ds_read2st64_b64 v[204:207], v139 offset0:5 offset1:6
	ds_read2st64_b64 v[200:203], v139 offset0:7 offset1:8
	ds_read2st64_b64 v[196:199], v139 offset0:9 offset1:10
	ds_read2st64_b64 v[192:195], v139 offset0:11 offset1:12
	ds_read2st64_b64 v[188:191], v139 offset0:13 offset1:14
	ds_read_b64 v[186:187], v139 offset:7680
.LBB0_848:
	v_add_u32_e32 v128, s0, v140
	v_lshrrev_b32_e32 v147, 6, v128
	v_mad_u32_u24 v151, v147, s77, v142
	ds_read_b64 v[64:65], v151 offset:0
	ds_read_b64 v[66:67], v151 offset:4352
	ds_read_b64 v[68:69], v151 offset:544
	ds_read_b64 v[70:71], v151 offset:4896
	ds_read_b64 v[72:73], v151 offset:1088
	ds_read_b64 v[74:75], v151 offset:5440
	ds_read_b64 v[76:77], v151 offset:1632
	ds_read_b64 v[78:79], v151 offset:5984
	ds_read_b64 v[80:81], v151 offset:2176
	ds_read_b64 v[82:83], v151 offset:6528
	ds_read_b64 v[84:85], v151 offset:2720
	ds_read_b64 v[86:87], v151 offset:7072
	ds_read_b64 v[88:89], v151 offset:3264
	ds_read_b64 v[90:91], v151 offset:7616
	ds_read_b64 v[92:93], v151 offset:3808
	ds_read_b64 v[94:95], v151 offset:8160
	s_cmp_eq_u32 s0, 0
	s_movk_i32 s0, 0x200
	s_mov_b64 s[12:13], 0
	s_waitcnt lgkmcnt(14)
	v_pk_add_f32 v[96:97], v[64:65], v[66:67]
	s_waitcnt lgkmcnt(12)
	v_pk_add_f32 v[98:99], v[68:69], v[70:71]
	s_waitcnt lgkmcnt(10)
	v_pk_add_f32 v[100:101], v[72:73], v[74:75]
	s_waitcnt lgkmcnt(8)
	v_pk_add_f32 v[102:103], v[76:77], v[78:79]
	v_pk_add_f32 v[64:65], v[64:65], v[66:67] neg_lo:[0,1] neg_hi:[0,1]
	v_pk_add_f32 v[70:71], v[68:69], v[70:71] neg_lo:[0,1] neg_hi:[0,1]
	v_pk_add_f32 v[72:73], v[72:73], v[74:75] neg_lo:[0,1] neg_hi:[0,1]
	v_pk_add_f32 v[76:77], v[76:77], v[78:79] neg_lo:[0,1] neg_hi:[0,1]
	s_waitcnt lgkmcnt(6)
	v_pk_add_f32 v[78:79], v[80:81], v[82:83]
	s_waitcnt lgkmcnt(4)
	v_pk_add_f32 v[74:75], v[84:85], v[86:87]
	s_waitcnt lgkmcnt(2)
	v_pk_add_f32 v[68:69], v[88:89], v[90:91]
	s_waitcnt lgkmcnt(0)
; #define LAS __attribute__((address_space(3)))
; __device__ __forceinline__ f32x2 cmul(f32x2 a, f32x2 b) { return (f32x2){a.x * b.x - a.y * b.y, a.x * b.y + a.y * b.x}; }
; __device__ __forceinline__ f32x2 tw32k(const LAS f32x2* TH, const LAS f32x2* TL, int n) { return cmul(TH[n >> 7], TL[n & 127]); }
; template <bool INV> __device__ __forceinline__ void dft16(f32x2 (&x)[16]) {
; #pragma unroll
;     for (int b = 0; b < 4; ++b) r4<INV>(x[b], x[4 + b], x[8 + b], x[12 + b]);
;     const float sg = INV ? -1.f : 1.f;
;     const f32x2 W1 = {0.92387953251f, -0.38268343236f * sg}, W2 = {0.70710678118f, -0.70710678118f * sg}, W3 = {0.38268343236f, -0.92387953251f * sg},
;                 W4 = {0.f, -1.f * sg}, W6 = {-0.70710678118f, -0.70710678118f * sg}, W9 = {-0.92387953251f, 0.38268343236f * sg};
;     x[5] = cmul(x[5], W1); x[9] = cmul(x[9], W2); x[13] = cmul(x[13], W3);
;     x[6] = cmul(x[6], W2); x[10] = cmul(x[10], W4); x[14] = cmul(x[14], W6);
;     x[7] = cmul(x[7], W3); x[11] = cmul(x[11], W6); x[15] = cmul(x[15], W9);
; #pragma unroll
;     for (int c = 0; c < 4; ++c) r4<INV>(x[4 * c], x[4 * c + 1], x[4 * c + 2], x[4 * c + 3]);
; }
; template <bool INV> __device__ __forceinline__ void bfly16(f32x2 (&x)[16], const LAS f32x2* TH, const LAS f32x2* TL, int tw) {
;     f32x2 W = tw32k(TH, TL, tw); if (INV) W.y = -W.y;
;     if (INV) { f32x2 p = W;
; #pragma unroll
;         for (int q = 1; q < 16; ++q) { x[q] = cmul(x[q], p); if (q < 15) p = cmul(p, W); } }
;     dft16<INV>(x);
;     if (!INV) { f32x2 p = W;
; #pragma unroll
;         for (int r = 1; r < 16; ++r) { x[4 * (r & 3) + (r >> 2)] = cmul(x[4 * (r & 3) + (r >> 2)], p); if (r < 15) p = cmul(p, W); } }
; }
; template <bool INV> __device__ __forceinline__ void bfly16_tab(f32x2 (&x)[16], const LAS f32x2* T, int tstride, int j) {
;     if (INV) {
; #pragma unroll
;         for (int q = 1; q < 16; ++q) { f32x2 p = T[q * tstride + j]; p.y = -p.y; x[q] = cmul(x[q], p); } }
;     dft16<INV>(x);
;     if (!INV) {
; #pragma unroll
;         for (int r = 1; r < 16; ++r) { const f32x2 p = T[r * tstride + j]; x[4 * (r & 3) + (r >> 2)] = cmul(x[4 * (r & 3) + (r >> 2)], p); } }
; }
	v_pk_add_f32 v[66:67], v[92:93], v[94:95]
	v_pk_add_f32 v[82:83], v[80:81], v[82:83] neg_lo:[0,1] neg_hi:[0,1]
	v_pk_add_f32 v[84:85], v[84:85], v[86:87] neg_lo:[0,1] neg_hi:[0,1]
	v_pk_add_f32 v[88:89], v[88:89], v[90:91] neg_lo:[0,1] neg_hi:[0,1]
	v_pk_add_f32 v[94:95], v[92:93], v[94:95] neg_lo:[0,1] neg_hi:[0,1]
	v_pk_add_f32 v[92:93], v[96:97], v[78:79]
	v_pk_add_f32 v[90:91], v[98:99], v[74:75]
	v_pk_add_f32 v[86:87], v[100:101], v[68:69]
	v_pk_add_f32 v[80:81], v[102:103], v[66:67]
	v_pk_add_f32 v[78:79], v[96:97], v[78:79] neg_lo:[0,1] neg_hi:[0,1]
	v_pk_add_f32 v[74:75], v[98:99], v[74:75] neg_lo:[0,1] neg_hi:[0,1]
	v_pk_add_f32 v[68:69], v[100:101], v[68:69] neg_lo:[0,1] neg_hi:[0,1]
	v_pk_add_f32 v[102:103], v[102:103], v[66:67] neg_lo:[0,1] neg_hi:[0,1]
	v_pk_add_f32 v[66:67], v[64:65], v[82:83] op_sel:[0,1] op_sel_hi:[1,0] neg_hi:[0,1]
	v_pk_add_f32 v[100:101], v[70:71], v[84:85] op_sel:[0,1] op_sel_hi:[1,0] neg_hi:[0,1]
	v_pk_add_f32 v[98:99], v[72:73], v[88:89] op_sel:[0,1] op_sel_hi:[1,0] neg_hi:[0,1]
	v_pk_add_f32 v[96:97], v[76:77], v[94:95] op_sel:[0,1] op_sel_hi:[1,0] neg_hi:[0,1]
	v_pk_add_f32 v[64:65], v[64:65], v[82:83] op_sel:[0,1] op_sel_hi:[1,0] neg_lo:[0,1]
	v_pk_add_f32 v[70:71], v[70:71], v[84:85] op_sel:[0,1] op_sel_hi:[1,0] neg_lo:[0,1]
	v_pk_add_f32 v[72:73], v[72:73], v[88:89] op_sel:[0,1] op_sel_hi:[1,0] neg_lo:[0,1]
	v_pk_add_f32 v[76:77], v[76:77], v[94:95] op_sel:[0,1] op_sel_hi:[1,0] neg_lo:[0,1]
	v_pk_mul_f32 v[94:95], v[100:101], s[70:71] op_sel_hi:[1,0]
	v_pk_mul_f32 v[88:89], v[74:75], s[72:73] op_sel_hi:[1,0]
	v_pk_mul_f32 v[84:85], v[70:71], s[64:65] op_sel_hi:[1,0]
	v_pk_mul_f32 v[82:83], v[98:99], s[72:73] op_sel_hi:[1,0]
	v_pk_mul_f32 v[104:105], v[72:73], s[72:73] op_sel_hi:[1,0]
	v_pk_mul_f32 v[106:107], v[96:97], s[64:65] op_sel_hi:[1,0]
	v_pk_mul_f32 v[108:109], v[102:103], s[72:73] op_sel_hi:[1,0]
	v_pk_mul_f32 v[110:111], v[76:77], s[82:83] op_sel_hi:[1,0]
	v_pk_fma_f32 v[94:95], v[100:101], s[44:45], v[94:95] op_sel:[0,0,1] op_sel_hi:[1,0,0] neg_lo:[0,0,1]
	v_pk_fma_f32 v[74:75], v[74:75], s[76:77], v[88:89] op_sel:[0,0,1] op_sel_hi:[1,0,0] neg_lo:[0,0,1]
	v_pk_fma_f32 v[84:85], v[70:71], s[82:83], v[84:85] op_sel:[0,0,1] op_sel_hi:[1,0,0] neg_lo:[0,0,1]
	v_pk_fma_f32 v[98:99], v[98:99], s[76:77], v[82:83] op_sel:[0,0,1] op_sel_hi:[1,0,0] neg_lo:[0,0,1]
	v_pk_fma_f32 v[104:105], v[72:73], s[72:73], v[104:105] op_sel:[0,0,1] op_sel_hi:[1,0,0] neg_lo:[0,0,1]
	v_pk_fma_f32 v[96:97], v[96:97], s[82:83], v[106:107] op_sel:[0,0,1] op_sel_hi:[1,0,0] neg_lo:[0,0,1]
	v_pk_fma_f32 v[102:103], v[102:103], s[72:73], v[108:109] op_sel:[0,0,1] op_sel_hi:[1,0,0] neg_lo:[0,0,1]
	v_pk_fma_f32 v[76:77], v[76:77], s[64:65], v[110:111] op_sel:[0,0,1] op_sel_hi:[1,0,0] neg_lo:[0,0,1]
	v_pk_add_f32 v[110:111], v[92:93], v[86:87]
	v_pk_add_f32 v[108:109], v[66:67], v[98:99]
	v_pk_add_f32 v[106:107], v[78:79], v[68:69] op_sel:[0,1] op_sel_hi:[1,0] neg_hi:[0,1]
	v_pk_add_f32 v[72:73], v[64:65], v[104:105]
	v_pk_add_f32 v[92:93], v[92:93], v[86:87] neg_lo:[0,1] neg_hi:[0,1]
	v_pk_add_f32 v[66:67], v[66:67], v[98:99] neg_lo:[0,1] neg_hi:[0,1]
	v_pk_add_f32 v[68:69], v[78:79], v[68:69] op_sel:[0,1] op_sel_hi:[1,0] neg_lo:[0,1]
	v_pk_add_f32 v[64:65], v[64:65], v[104:105] neg_lo:[0,1] neg_hi:[0,1]
	v_pk_add_f32 v[104:105], v[90:91], v[80:81]
	v_pk_add_f32 v[78:79], v[94:95], v[96:97]
	v_pk_add_f32 v[98:99], v[74:75], v[102:103]
	v_pk_add_f32 v[86:87], v[84:85], v[76:77]
	v_pk_add_f32 v[80:81], v[90:91], v[80:81] neg_lo:[0,1] neg_hi:[0,1]
	v_pk_add_f32 v[96:97], v[94:95], v[96:97] neg_lo:[0,1] neg_hi:[0,1]
	v_pk_add_f32 v[74:75], v[74:75], v[102:103] neg_lo:[0,1] neg_hi:[0,1]
	v_pk_add_f32 v[76:77], v[84:85], v[76:77] neg_lo:[0,1] neg_hi:[0,1]
	v_pk_add_f32 v[84:85], v[110:111], v[104:105]
	v_pk_add_f32 v[102:103], v[108:109], v[78:79]
	v_pk_add_f32 v[94:95], v[106:107], v[98:99]
	v_pk_add_f32 v[90:91], v[72:73], v[86:87]
	v_pk_add_f32 v[110:111], v[110:111], v[104:105] neg_lo:[0,1] neg_hi:[0,1]
	v_pk_add_f32 v[108:109], v[108:109], v[78:79] neg_lo:[0,1] neg_hi:[0,1]
	v_pk_add_f32 v[98:99], v[106:107], v[98:99] neg_lo:[0,1] neg_hi:[0,1]
	v_pk_add_f32 v[72:73], v[72:73], v[86:87] neg_lo:[0,1] neg_hi:[0,1]
	v_pk_add_f32 v[86:87], v[92:93], v[80:81] op_sel:[0,1] op_sel_hi:[1,0] neg_hi:[0,1]
	v_pk_add_f32 v[106:107], v[66:67], v[96:97] op_sel:[0,1] op_sel_hi:[1,0] neg_hi:[0,1]
	v_pk_add_f32 v[78:79], v[68:69], v[74:75] op_sel:[0,1] op_sel_hi:[1,0] neg_hi:[0,1]
	v_pk_add_f32 v[104:105], v[64:65], v[76:77] op_sel:[0,1] op_sel_hi:[1,0] neg_hi:[0,1]
	v_pk_add_f32 v[80:81], v[92:93], v[80:81] op_sel:[0,1] op_sel_hi:[1,0] neg_lo:[0,1]
	v_pk_add_f32 v[96:97], v[66:67], v[96:97] op_sel:[0,1] op_sel_hi:[1,0] neg_lo:[0,1]
	v_pk_add_f32 v[68:69], v[68:69], v[74:75] op_sel:[0,1] op_sel_hi:[1,0] neg_lo:[0,1]
	v_pk_add_f32 v[76:77], v[64:65], v[76:77] op_sel:[0,1] op_sel_hi:[1,0] neg_lo:[0,1]
	v_pk_mul_f32 v[64:65], v[102:103], v[232:233] op_sel:[0,1] op_sel_hi:[1,1]
	v_pk_mul_f32 v[74:75], v[94:95], v[234:235] op_sel:[0,1] op_sel_hi:[1,1]
	v_pk_fma_f32 v[102:103], v[102:103], v[232:233], v[64:65] op_sel:[0,0,1] op_sel_hi:[1,0,0] neg_lo:[0,0,1]
	v_pk_mul_f32 v[64:65], v[90:91], v[208:209] op_sel:[0,1] op_sel_hi:[1,1]
	v_pk_fma_f32 v[94:95], v[94:95], v[234:235], v[74:75] op_sel:[0,0,1] op_sel_hi:[1,0,0] neg_lo:[0,0,1]
	v_pk_mul_f32 v[74:75], v[86:87], v[210:211] op_sel:[0,1] op_sel_hi:[1,1]
	v_pk_fma_f32 v[90:91], v[90:91], v[208:209], v[64:65] op_sel:[0,0,1] op_sel_hi:[1,0,0] neg_lo:[0,0,1]
	v_pk_mul_f32 v[64:65], v[106:107], v[204:205] op_sel:[0,1] op_sel_hi:[1,1]
	v_pk_fma_f32 v[74:75], v[86:87], v[210:211], v[74:75] op_sel:[0,0,1] op_sel_hi:[1,0,0] neg_lo:[0,0,1]
; #define LAS __attribute__((address_space(3)))
; template <bool INV> __device__ __forceinline__ void pass16_s64(LAS f32x2* X, const LAS f32x2* TH, int base, int j) {
;     ...
; #pragma unroll
;     for (int c = 0; c < 4; ++c)
; #pragma unroll
;         for (int d = 0; d < 4; ++d) X[base + (c + 4 * d) * 68] = x[4 * c + d];
; }
; template <bool INV> __device__ __forceinline__ void pass16(LAS f32x2* X, const LAS f32x2* TH, const LAS f32x2* TL, int base, int stride, int tw) {
;     f32x2 x[16];
; #pragma unroll
;     for (int q = 0; q < 16; ++q) x[q] = X[base + q * stride];
;     bfly16<INV>(x, TH, TL, tw);
; #pragma unroll
;     for (int c = 0; c < 4; ++c)
; #pragma unroll
;         for (int d = 0; d < 4; ++d) X[base + (c + 4 * d) * stride] = x[4 * c + d];
; }
; template <bool INV> __device__ __forceinline__ void pass16_s4(LAS f32x2* X, const LAS f32x2* TH, const LAS f32x2* TL, int tid) {
; #pragma unroll 1
;     for (int s = 0; s < 2; ++s) {
;         const int b = tid + NTHR * s, blk = b >> 2, jj = b & 3;
;         LAS f32x2* P = X + blk * 68 + jj;
;         f32x2 x[16];
; #pragma unroll
;         for (int q = 0; q < 16; ++q) x[q] = P[4 * q];
;         bfly16_tab<INV>(x, TH - 1024, 4, jj);
	v_pk_mul_f32 v[86:87], v[78:79], v[206:207] op_sel:[0,1] op_sel_hi:[1,1]
	v_pk_fma_f32 v[106:107], v[106:107], v[204:205], v[64:65] op_sel:[0,0,1] op_sel_hi:[1,0,0] neg_lo:[0,0,1]
	v_pk_mul_f32 v[64:65], v[104:105], v[200:201] op_sel:[0,1] op_sel_hi:[1,1]
	v_pk_fma_f32 v[78:79], v[78:79], v[206:207], v[86:87] op_sel:[0,0,1] op_sel_hi:[1,0,0] neg_lo:[0,0,1]
	v_pk_mul_f32 v[86:87], v[110:111], v[202:203] op_sel:[0,1] op_sel_hi:[1,1]
	v_pk_fma_f32 v[64:65], v[104:105], v[200:201], v[64:65] op_sel:[0,0,1] op_sel_hi:[1,0,0] neg_lo:[0,0,1]
	v_pk_mul_f32 v[104:105], v[108:109], v[196:197] op_sel:[0,1] op_sel_hi:[1,1]
	v_pk_fma_f32 v[86:87], v[110:111], v[202:203], v[86:87] op_sel:[0,0,1] op_sel_hi:[1,0,0] neg_lo:[0,0,1]
	v_pk_mul_f32 v[110:111], v[98:99], v[198:199] op_sel:[0,1] op_sel_hi:[1,1]
	v_pk_fma_f32 v[108:109], v[108:109], v[196:197], v[104:105] op_sel:[0,0,1] op_sel_hi:[1,0,0] neg_lo:[0,0,1]
	v_pk_mul_f32 v[104:105], v[72:73], v[192:193] op_sel:[0,1] op_sel_hi:[1,1]
	v_pk_fma_f32 v[98:99], v[98:99], v[198:199], v[110:111] op_sel:[0,0,1] op_sel_hi:[1,0,0] neg_lo:[0,0,1]
	v_pk_mul_f32 v[110:111], v[80:81], v[194:195] op_sel:[0,1] op_sel_hi:[1,1]
	v_pk_fma_f32 v[72:73], v[72:73], v[192:193], v[104:105] op_sel:[0,0,1] op_sel_hi:[1,0,0] neg_lo:[0,0,1]
	v_pk_mul_f32 v[104:105], v[96:97], v[188:189] op_sel:[0,1] op_sel_hi:[1,1]
	v_pk_fma_f32 v[80:81], v[80:81], v[194:195], v[110:111] op_sel:[0,0,1] op_sel_hi:[1,0,0] neg_lo:[0,0,1]
	v_pk_mul_f32 v[110:111], v[68:69], v[190:191] op_sel:[0,1] op_sel_hi:[1,1]
	v_pk_fma_f32 v[96:97], v[96:97], v[188:189], v[104:105] op_sel:[0,0,1] op_sel_hi:[1,0,0] neg_lo:[0,0,1]
	v_pk_mul_f32 v[104:105], v[76:77], v[186:187] op_sel:[0,1] op_sel_hi:[1,1]
	v_pk_fma_f32 v[68:69], v[68:69], v[190:191], v[110:111] op_sel:[0,0,1] op_sel_hi:[1,0,0] neg_lo:[0,0,1]
	v_pk_fma_f32 v[76:77], v[76:77], v[186:187], v[104:105] op_sel:[0,0,1] op_sel_hi:[1,0,0] neg_lo:[0,0,1]
	ds_write_b64 v151, v[84:85] offset:0
	ds_write_b64 v151, v[102:103] offset:544
	ds_write_b64 v151, v[94:95] offset:1088
	ds_write_b64 v151, v[90:91] offset:1632
	ds_write_b64 v151, v[74:75] offset:2176
	ds_write_b64 v151, v[106:107] offset:2720
	ds_write_b64 v151, v[78:79] offset:3264
	ds_write_b64 v151, v[64:65] offset:3808
	ds_write_b64 v151, v[86:87] offset:4352
	ds_write_b64 v151, v[108:109] offset:4896
	ds_write_b64 v151, v[98:99] offset:5440
	ds_write_b64 v151, v[72:73] offset:5984
	ds_write_b64 v151, v[80:81] offset:6528
	ds_write_b64 v151, v[96:97] offset:7072
	ds_write_b64 v151, v[68:69] offset:7616
	ds_write_b64 v151, v[76:77] offset:8160
	s_cbranch_scc1 .LBB0_848
	s_waitcnt lgkmcnt(0)
	s_barrier
	s_mov_b32 s0, 0
	s_mov_b64 s[12:13], -1
	ds_read2_b64 v[232:235], v141 offset0:4 offset1:8
	ds_read2_b64 v[208:211], v141 offset0:12 offset1:16
	ds_read2_b64 v[204:207], v141 offset0:20 offset1:24
	ds_read2_b64 v[200:203], v141 offset0:28 offset1:32
	ds_read2_b64 v[196:199], v141 offset0:36 offset1:40
	ds_read2_b64 v[192:195], v141 offset0:44 offset1:48
	ds_read2_b64 v[188:191], v141 offset0:52 offset1:56
	ds_read_b64 v[186:187], v141 offset:480
.LBB0_850:
	v_add_u32_e32 v128, s0, v140
	v_lshrrev_b32_e32 v147, 2, v128
	v_mad_u32_u24 v151, v147, s43, v144
	ds_read_b64 v[64:65], v151 offset:0
	ds_read_b64 v[66:67], v151 offset:256
	ds_read_b64 v[68:69], v151 offset:32
	ds_read_b64 v[70:71], v151 offset:288
	ds_read_b64 v[72:73], v151 offset:64
	ds_read_b64 v[74:75], v151 offset:320
	ds_read_b64 v[76:77], v151 offset:96
	ds_read_b64 v[78:79], v151 offset:352
	ds_read_b64 v[80:81], v151 offset:128
	ds_read_b64 v[82:83], v151 offset:384
	ds_read_b64 v[84:85], v151 offset:160
	ds_read_b64 v[86:87], v151 offset:416
	ds_read_b64 v[88:89], v151 offset:192
	ds_read_b64 v[90:91], v151 offset:448
	ds_read_b64 v[92:93], v151 offset:224
	ds_read_b64 v[94:95], v151 offset:480
	s_cmp_eq_u32 s0, 0
	s_movk_i32 s0, 0x200
	s_mov_b64 s[12:13], 0
	s_waitcnt lgkmcnt(14)
	v_pk_add_f32 v[96:97], v[64:65], v[66:67]
	s_waitcnt lgkmcnt(12)
	v_pk_add_f32 v[98:99], v[68:69], v[70:71]
	s_waitcnt lgkmcnt(10)
	v_pk_add_f32 v[100:101], v[72:73], v[74:75]
	s_waitcnt lgkmcnt(8)
	v_pk_add_f32 v[102:103], v[76:77], v[78:79]
	v_pk_add_f32 v[64:65], v[64:65], v[66:67] neg_lo:[0,1] neg_hi:[0,1]
	v_pk_add_f32 v[70:71], v[68:69], v[70:71] neg_lo:[0,1] neg_hi:[0,1]
	v_pk_add_f32 v[72:73], v[72:73], v[74:75] neg_lo:[0,1] neg_hi:[0,1]
	v_pk_add_f32 v[78:79], v[76:77], v[78:79] neg_lo:[0,1] neg_hi:[0,1]
	s_waitcnt lgkmcnt(6)
	v_pk_add_f32 v[76:77], v[80:81], v[82:83]
	s_waitcnt lgkmcnt(4)
	v_pk_add_f32 v[74:75], v[84:85], v[86:87]
	s_waitcnt lgkmcnt(2)
	v_pk_add_f32 v[68:69], v[88:89], v[90:91]
	s_waitcnt lgkmcnt(0)
; #define LAS __attribute__((address_space(3)))
; __device__ __forceinline__ f32x2 cmul(f32x2 a, f32x2 b) { return (f32x2){a.x * b.x - a.y * b.y, a.x * b.y + a.y * b.x}; }
; __device__ __forceinline__ f32x2 tw32k(const LAS f32x2* TH, const LAS f32x2* TL, int n) { return cmul(TH[n >> 7], TL[n & 127]); }
; template <bool INV> __device__ __forceinline__ void dft16(f32x2 (&x)[16]) {
; #pragma unroll
;     for (int b = 0; b < 4; ++b) r4<INV>(x[b], x[4 + b], x[8 + b], x[12 + b]);
;     const float sg = INV ? -1.f : 1.f;
;     const f32x2 W1 = {0.92387953251f, -0.38268343236f * sg}, W2 = {0.70710678118f, -0.70710678118f * sg}, W3 = {0.38268343236f, -0.92387953251f * sg},
;                 W4 = {0.f, -1.f * sg}, W6 = {-0.70710678118f, -0.70710678118f * sg}, W9 = {-0.92387953251f, 0.38268343236f * sg};
;     x[5] = cmul(x[5], W1); x[9] = cmul(x[9], W2); x[13] = cmul(x[13], W3);
;     x[6] = cmul(x[6], W2); x[10] = cmul(x[10], W4); x[14] = cmul(x[14], W6);
;     x[7] = cmul(x[7], W3); x[11] = cmul(x[11], W6); x[15] = cmul(x[15], W9);
; #pragma unroll
;     for (int c = 0; c < 4; ++c) r4<INV>(x[4 * c], x[4 * c + 1], x[4 * c + 2], x[4 * c + 3]);
; }
; template <bool INV> __device__ __forceinline__ void bfly16(f32x2 (&x)[16], const LAS f32x2* TH, const LAS f32x2* TL, int tw) {
;     f32x2 W = tw32k(TH, TL, tw); if (INV) W.y = -W.y;
;     if (INV) { f32x2 p = W;
; #pragma unroll
;         for (int q = 1; q < 16; ++q) { x[q] = cmul(x[q], p); if (q < 15) p = cmul(p, W); } }
;     dft16<INV>(x);
;     if (!INV) { f32x2 p = W;
; #pragma unroll
;         for (int r = 1; r < 16; ++r) { x[4 * (r & 3) + (r >> 2)] = cmul(x[4 * (r & 3) + (r >> 2)], p); if (r < 15) p = cmul(p, W); } }
; }
; template <bool INV> __device__ __forceinline__ void bfly16_tab(f32x2 (&x)[16], const LAS f32x2* T, int tstride, int j) {
;     if (INV) {
; #pragma unroll
;         for (int q = 1; q < 16; ++q) { f32x2 p = T[q * tstride + j]; p.y = -p.y; x[q] = cmul(x[q], p); } }
;     dft16<INV>(x);
;     if (!INV) {
; #pragma unroll
;         for (int r = 1; r < 16; ++r) { const f32x2 p = T[r * tstride + j]; x[4 * (r & 3) + (r >> 2)] = cmul(x[4 * (r & 3) + (r >> 2)], p); } }
; }
	v_pk_add_f32 v[66:67], v[92:93], v[94:95]
	v_pk_add_f32 v[80:81], v[80:81], v[82:83] neg_lo:[0,1] neg_hi:[0,1]
	v_pk_add_f32 v[84:85], v[84:85], v[86:87] neg_lo:[0,1] neg_hi:[0,1]
	v_pk_add_f32 v[88:89], v[88:89], v[90:91] neg_lo:[0,1] neg_hi:[0,1]
	v_pk_add_f32 v[92:93], v[92:93], v[94:95] neg_lo:[0,1] neg_hi:[0,1]
	v_pk_add_f32 v[94:95], v[96:97], v[76:77]
	v_pk_add_f32 v[90:91], v[98:99], v[74:75]
	v_pk_add_f32 v[86:87], v[100:101], v[68:69]
	v_pk_add_f32 v[82:83], v[102:103], v[66:67]
	v_pk_add_f32 v[96:97], v[96:97], v[76:77] neg_lo:[0,1] neg_hi:[0,1]
	v_pk_add_f32 v[74:75], v[98:99], v[74:75] neg_lo:[0,1] neg_hi:[0,1]
	v_pk_add_f32 v[100:101], v[100:101], v[68:69] neg_lo:[0,1] neg_hi:[0,1]
	v_pk_add_f32 v[102:103], v[102:103], v[66:67] neg_lo:[0,1] neg_hi:[0,1]
	v_pk_add_f32 v[66:67], v[64:65], v[80:81] op_sel:[0,1] op_sel_hi:[1,0] neg_hi:[0,1]
	v_pk_add_f32 v[68:69], v[70:71], v[84:85] op_sel:[0,1] op_sel_hi:[1,0] neg_hi:[0,1]
	v_pk_add_f32 v[98:99], v[72:73], v[88:89] op_sel:[0,1] op_sel_hi:[1,0] neg_hi:[0,1]
	v_pk_add_f32 v[76:77], v[78:79], v[92:93] op_sel:[0,1] op_sel_hi:[1,0] neg_hi:[0,1]
	v_pk_add_f32 v[80:81], v[64:65], v[80:81] op_sel:[0,1] op_sel_hi:[1,0] neg_lo:[0,1]
	v_pk_add_f32 v[70:71], v[70:71], v[84:85] op_sel:[0,1] op_sel_hi:[1,0] neg_lo:[0,1]
	v_pk_add_f32 v[88:89], v[72:73], v[88:89] op_sel:[0,1] op_sel_hi:[1,0] neg_lo:[0,1]
	v_pk_add_f32 v[78:79], v[78:79], v[92:93] op_sel:[0,1] op_sel_hi:[1,0] neg_lo:[0,1]
	v_pk_mul_f32 v[92:93], v[68:69], s[70:71] op_sel_hi:[1,0]
	v_pk_mul_f32 v[72:73], v[74:75], s[72:73] op_sel_hi:[1,0]
	v_pk_mul_f32 v[84:85], v[70:71], s[64:65] op_sel_hi:[1,0]
	v_pk_mul_f32 v[64:65], v[98:99], s[72:73] op_sel_hi:[1,0]
	v_pk_mul_f32 v[104:105], v[88:89], s[72:73] op_sel_hi:[1,0]
	v_pk_mul_f32 v[106:107], v[76:77], s[64:65] op_sel_hi:[1,0]
	v_pk_mul_f32 v[108:109], v[102:103], s[72:73] op_sel_hi:[1,0]
	v_pk_mul_f32 v[110:111], v[78:79], s[82:83] op_sel_hi:[1,0]
	v_pk_fma_f32 v[92:93], v[68:69], s[44:45], v[92:93] op_sel:[0,0,1] op_sel_hi:[1,0,0] neg_lo:[0,0,1]
	v_pk_fma_f32 v[72:73], v[74:75], s[76:77], v[72:73] op_sel:[0,0,1] op_sel_hi:[1,0,0] neg_lo:[0,0,1]
	v_pk_fma_f32 v[70:71], v[70:71], s[82:83], v[84:85] op_sel:[0,0,1] op_sel_hi:[1,0,0] neg_lo:[0,0,1]
	v_pk_fma_f32 v[64:65], v[98:99], s[76:77], v[64:65] op_sel:[0,0,1] op_sel_hi:[1,0,0] neg_lo:[0,0,1]
	v_pk_fma_f32 v[104:105], v[88:89], s[72:73], v[104:105] op_sel:[0,0,1] op_sel_hi:[1,0,0] neg_lo:[0,0,1]
	v_pk_fma_f32 v[106:107], v[76:77], s[82:83], v[106:107] op_sel:[0,0,1] op_sel_hi:[1,0,0] neg_lo:[0,0,1]
	v_pk_fma_f32 v[102:103], v[102:103], s[72:73], v[108:109] op_sel:[0,0,1] op_sel_hi:[1,0,0] neg_lo:[0,0,1]
	v_pk_fma_f32 v[110:111], v[78:79], s[64:65], v[110:111] op_sel:[0,0,1] op_sel_hi:[1,0,0] neg_lo:[0,0,1]
	v_pk_add_f32 v[78:79], v[94:95], v[86:87]
	v_pk_add_f32 v[108:109], v[66:67], v[64:65]
	v_pk_add_f32 v[76:77], v[96:97], v[100:101] op_sel:[0,1] op_sel_hi:[1,0] neg_hi:[0,1]
	v_pk_add_f32 v[88:89], v[80:81], v[104:105]
	v_pk_add_f32 v[86:87], v[94:95], v[86:87] neg_lo:[0,1] neg_hi:[0,1]
	v_pk_add_f32 v[64:65], v[66:67], v[64:65] neg_lo:[0,1] neg_hi:[0,1]
	v_pk_add_f32 v[100:101], v[96:97], v[100:101] op_sel:[0,1] op_sel_hi:[1,0] neg_lo:[0,1]
	v_pk_add_f32 v[104:105], v[80:81], v[104:105] neg_lo:[0,1] neg_hi:[0,1]
	v_pk_add_f32 v[80:81], v[90:91], v[82:83]
	v_pk_add_f32 v[96:97], v[92:93], v[106:107]
	v_pk_add_f32 v[66:67], v[72:73], v[102:103]
	v_pk_add_f32 v[94:95], v[70:71], v[110:111]
	v_pk_add_f32 v[82:83], v[90:91], v[82:83] neg_lo:[0,1] neg_hi:[0,1]
	v_pk_add_f32 v[92:93], v[92:93], v[106:107] neg_lo:[0,1] neg_hi:[0,1]
	v_pk_add_f32 v[102:103], v[72:73], v[102:103] neg_lo:[0,1] neg_hi:[0,1]
	v_pk_add_f32 v[70:71], v[70:71], v[110:111] neg_lo:[0,1] neg_hi:[0,1]
	v_pk_add_f32 v[110:111], v[78:79], v[80:81]
	v_pk_add_f32 v[72:73], v[108:109], v[96:97]
	v_pk_add_f32 v[106:107], v[76:77], v[66:67]
	v_pk_add_f32 v[90:91], v[88:89], v[94:95]
	v_pk_add_f32 v[80:81], v[78:79], v[80:81] neg_lo:[0,1] neg_hi:[0,1]
	v_pk_add_f32 v[96:97], v[108:109], v[96:97] neg_lo:[0,1] neg_hi:[0,1]
	v_pk_add_f32 v[76:77], v[76:77], v[66:67] neg_lo:[0,1] neg_hi:[0,1]
	v_pk_add_f32 v[94:95], v[88:89], v[94:95] neg_lo:[0,1] neg_hi:[0,1]
	v_pk_add_f32 v[88:89], v[86:87], v[82:83] op_sel:[0,1] op_sel_hi:[1,0] neg_hi:[0,1]
	v_pk_add_f32 v[66:67], v[64:65], v[92:93] op_sel:[0,1] op_sel_hi:[1,0] neg_hi:[0,1]
	v_pk_add_f32 v[108:109], v[100:101], v[102:103] op_sel:[0,1] op_sel_hi:[1,0] neg_hi:[0,1]
	v_pk_add_f32 v[78:79], v[104:105], v[70:71] op_sel:[0,1] op_sel_hi:[1,0] neg_hi:[0,1]
	v_pk_add_f32 v[82:83], v[86:87], v[82:83] op_sel:[0,1] op_sel_hi:[1,0] neg_lo:[0,1]
	v_pk_add_f32 v[92:93], v[64:65], v[92:93] op_sel:[0,1] op_sel_hi:[1,0] neg_lo:[0,1]
	v_pk_add_f32 v[100:101], v[100:101], v[102:103] op_sel:[0,1] op_sel_hi:[1,0] neg_lo:[0,1]
	v_pk_add_f32 v[70:71], v[104:105], v[70:71] op_sel:[0,1] op_sel_hi:[1,0] neg_lo:[0,1]
	v_pk_mul_f32 v[104:105], v[72:73], v[232:233] op_sel:[0,1] op_sel_hi:[1,1]
	v_pk_mul_f32 v[102:103], v[106:107], v[234:235] op_sel:[0,1] op_sel_hi:[1,1]
	v_pk_fma_f32 v[72:73], v[72:73], v[232:233], v[104:105] op_sel:[0,0,1] op_sel_hi:[1,0,0] neg_lo:[0,0,1]
	v_pk_mul_f32 v[104:105], v[90:91], v[208:209] op_sel:[0,1] op_sel_hi:[1,1]
	v_pk_fma_f32 v[102:103], v[106:107], v[234:235], v[102:103] op_sel:[0,0,1] op_sel_hi:[1,0,0] neg_lo:[0,0,1]
	v_pk_mul_f32 v[106:107], v[88:89], v[210:211] op_sel:[0,1] op_sel_hi:[1,1]
	v_pk_fma_f32 v[90:91], v[90:91], v[208:209], v[104:105] op_sel:[0,0,1] op_sel_hi:[1,0,0] neg_lo:[0,0,1]
	v_pk_mul_f32 v[104:105], v[66:67], v[204:205] op_sel:[0,1] op_sel_hi:[1,1]
; #define LAS __attribute__((address_space(3)))
; template <bool INV> __device__ __forceinline__ void bfly16_tab(f32x2 (&x)[16], const LAS f32x2* T, int tstride, int j) {
;     if (INV) {
; #pragma unroll
;         for (int q = 1; q < 16; ++q) { f32x2 p = T[q * tstride + j]; p.y = -p.y; x[q] = cmul(x[q], p); } }
;     dft16<INV>(x);
;     if (!INV) {
; #pragma unroll
;         for (int r = 1; r < 16; ++r) { const f32x2 p = T[r * tstride + j]; x[4 * (r & 3) + (r >> 2)] = cmul(x[4 * (r & 3) + (r >> 2)], p); } }
; }
; template <bool INV> __device__ __forceinline__ void pass16_s64(LAS f32x2* X, const LAS f32x2* TH, int base, int j) {
;     f32x2 x[16];
; #pragma unroll
;     for (int q = 0; q < 16; ++q) x[q] = X[base + q * 68];
;     bfly16_tab<INV>(x, TH - 2048, 64, j);
; #pragma unroll
;     for (int c = 0; c < 4; ++c)
; #pragma unroll
;         for (int d = 0; d < 4; ++d) X[base + (c + 4 * d) * 68] = x[4 * c + d];
; }
; template <bool INV> __device__ __forceinline__ void pass16(LAS f32x2* X, const LAS f32x2* TH, const LAS f32x2* TL, int base, int stride, int tw) {
;     f32x2 x[16];
; #pragma unroll
;     for (int q = 0; q < 16; ++q) x[q] = X[base + q * stride];
;     bfly16<INV>(x, TH, TL, tw);
; #pragma unroll
;     for (int c = 0; c < 4; ++c)
; #pragma unroll
;         for (int d = 0; d < 4; ++d) X[base + (c + 4 * d) * stride] = x[4 * c + d];
; }
; template <bool INV> __device__ __forceinline__ void pass16_s4(LAS f32x2* X, const LAS f32x2* TH, const LAS f32x2* TL, int tid) {
; #pragma unroll 1
;     for (int s = 0; s < 2; ++s) {
;         const int b = tid + NTHR * s, blk = b >> 2, jj = b & 3;
;         LAS f32x2* P = X + blk * 68 + jj;
;         f32x2 x[16];
; #pragma unroll
;         for (int q = 0; q < 16; ++q) x[q] = P[4 * q];
;         bfly16_tab<INV>(x, TH - 1024, 4, jj);
; #pragma unroll
;         for (int c = 0; c < 4; ++c)
; #pragma unroll
;             for (int d = 0; d < 4; ++d) P[4 * (c + 4 * d)] = x[4 * c + d];
;     }
; }
; __device__ __forceinline__ void hyena_latent(Frame& F, int l, int ch, LAS f32x2* X, const LAS f32x2* TH, const LAS f32x2* TL, GAS f32x2* KS, const LAS float* CT  , bool wr = true) {
;     ...
;             for (int i = 0; i < 8; ++i) { const int b = LT() + NTHR * i; const LAS f32x4* P = (const LAS f32x4*)(X + 4 * b + ((b >> 4) << 2)); const f32x4 u = P[0], v = P[1];
	v_pk_fma_f32 v[88:89], v[88:89], v[210:211], v[106:107] op_sel:[0,0,1] op_sel_hi:[1,0,0] neg_lo:[0,0,1]
	v_pk_mul_f32 v[106:107], v[108:109], v[206:207] op_sel:[0,1] op_sel_hi:[1,1]
	v_pk_fma_f32 v[104:105], v[66:67], v[204:205], v[104:105] op_sel:[0,0,1] op_sel_hi:[1,0,0] neg_lo:[0,0,1]
	v_pk_mul_f32 v[66:67], v[78:79], v[200:201] op_sel:[0,1] op_sel_hi:[1,1]
	v_pk_fma_f32 v[106:107], v[108:109], v[206:207], v[106:107] op_sel:[0,0,1] op_sel_hi:[1,0,0] neg_lo:[0,0,1]
	v_pk_mul_f32 v[108:109], v[80:81], v[202:203] op_sel:[0,1] op_sel_hi:[1,1]
	v_pk_fma_f32 v[66:67], v[78:79], v[200:201], v[66:67] op_sel:[0,0,1] op_sel_hi:[1,0,0] neg_lo:[0,0,1]
	v_pk_mul_f32 v[78:79], v[96:97], v[196:197] op_sel:[0,1] op_sel_hi:[1,1]
	v_pk_fma_f32 v[108:109], v[80:81], v[202:203], v[108:109] op_sel:[0,0,1] op_sel_hi:[1,0,0] neg_lo:[0,0,1]
	v_pk_mul_f32 v[80:81], v[76:77], v[198:199] op_sel:[0,1] op_sel_hi:[1,1]
	v_pk_fma_f32 v[96:97], v[96:97], v[196:197], v[78:79] op_sel:[0,0,1] op_sel_hi:[1,0,0] neg_lo:[0,0,1]
	v_pk_mul_f32 v[78:79], v[94:95], v[192:193] op_sel:[0,1] op_sel_hi:[1,1]
	v_pk_fma_f32 v[80:81], v[76:77], v[198:199], v[80:81] op_sel:[0,0,1] op_sel_hi:[1,0,0] neg_lo:[0,0,1]
	v_pk_mul_f32 v[76:77], v[82:83], v[194:195] op_sel:[0,1] op_sel_hi:[1,1]
	v_pk_fma_f32 v[78:79], v[94:95], v[192:193], v[78:79] op_sel:[0,0,1] op_sel_hi:[1,0,0] neg_lo:[0,0,1]
	v_pk_mul_f32 v[94:95], v[92:93], v[188:189] op_sel:[0,1] op_sel_hi:[1,1]
	v_pk_fma_f32 v[82:83], v[82:83], v[194:195], v[76:77] op_sel:[0,0,1] op_sel_hi:[1,0,0] neg_lo:[0,0,1]
	v_pk_mul_f32 v[76:77], v[100:101], v[190:191] op_sel:[0,1] op_sel_hi:[1,1]
	v_pk_fma_f32 v[92:93], v[92:93], v[188:189], v[94:95] op_sel:[0,0,1] op_sel_hi:[1,0,0] neg_lo:[0,0,1]
	v_pk_mul_f32 v[94:95], v[70:71], v[186:187] op_sel:[0,1] op_sel_hi:[1,1]
	v_pk_fma_f32 v[100:101], v[100:101], v[190:191], v[76:77] op_sel:[0,0,1] op_sel_hi:[1,0,0] neg_lo:[0,0,1]
	v_pk_fma_f32 v[94:95], v[70:71], v[186:187], v[94:95] op_sel:[0,0,1] op_sel_hi:[1,0,0] neg_lo:[0,0,1]
	ds_write_b64 v151, v[110:111] offset:0
	ds_write_b64 v151, v[72:73] offset:32
	ds_write_b64 v151, v[102:103] offset:64
	ds_write_b64 v151, v[90:91] offset:96
	ds_write_b64 v151, v[88:89] offset:128
	ds_write_b64 v151, v[104:105] offset:160
	ds_write_b64 v151, v[106:107] offset:192
	ds_write_b64 v151, v[66:67] offset:224
	ds_write_b64 v151, v[108:109] offset:256
	ds_write_b64 v151, v[96:97] offset:288
	ds_write_b64 v151, v[80:81] offset:320
	ds_write_b64 v151, v[78:79] offset:352
	ds_write_b64 v151, v[82:83] offset:384
	ds_write_b64 v151, v[92:93] offset:416
	ds_write_b64 v151, v[100:101] offset:448
	ds_write_b64 v151, v[94:95] offset:480
	s_cbranch_scc1 .LBB0_850
	v_pk_add_f32 v[68:69], v[56:57], v[60:61]
	v_pk_add_f32 v[56:57], v[56:57], v[60:61] neg_lo:[0,1] neg_hi:[0,1]
	v_pk_add_f32 v[60:61], v[58:59], v[62:63]
	v_pk_add_f32 v[58:59], v[58:59], v[62:63] neg_lo:[0,1] neg_hi:[0,1]
	v_pk_add_f32 v[66:67], v[68:69], v[60:61]
	v_xor_b32_e32 v71, 0x80000000, v58
	v_mov_b32_e32 v70, v59
	v_pk_add_f32 v[62:63], v[68:69], v[60:61] neg_lo:[0,1] neg_hi:[0,1]
	v_pk_add_f32 v[68:69], v[48:49], v[52:53]
	v_pk_add_f32 v[48:49], v[48:49], v[52:53] neg_lo:[0,1] neg_hi:[0,1]
	v_pk_add_f32 v[52:53], v[50:51], v[54:55]
	v_pk_add_f32 v[50:51], v[50:51], v[54:55] neg_lo:[0,1] neg_hi:[0,1]
	v_pk_add_f32 v[64:65], v[56:57], v[70:71]
	v_pk_add_f32 v[60:61], v[56:57], v[70:71] neg_lo:[0,1] neg_hi:[0,1]
	v_xor_b32_e32 v71, 0x80000000, v50
	v_mov_b32_e32 v70, v51
	v_pk_add_f32 v[58:59], v[68:69], v[52:53]
	v_pk_add_f32 v[54:55], v[68:69], v[52:53] neg_lo:[0,1] neg_hi:[0,1]
	v_pk_add_f32 v[68:69], v[40:41], v[44:45]
	v_pk_add_f32 v[40:41], v[40:41], v[44:45] neg_lo:[0,1] neg_hi:[0,1]
	v_pk_add_f32 v[44:45], v[42:43], v[46:47]
	v_pk_add_f32 v[42:43], v[42:43], v[46:47] neg_lo:[0,1] neg_hi:[0,1]
	v_pk_add_f32 v[56:57], v[48:49], v[70:71]
	v_pk_add_f32 v[52:53], v[48:49], v[70:71] neg_lo:[0,1] neg_hi:[0,1]
	v_xor_b32_e32 v71, 0x80000000, v42
	v_mov_b32_e32 v70, v43
	v_pk_add_f32 v[50:51], v[68:69], v[44:45]
	v_pk_add_f32 v[46:47], v[68:69], v[44:45] neg_lo:[0,1] neg_hi:[0,1]
	v_pk_add_f32 v[68:69], v[32:33], v[36:37]
	v_pk_add_f32 v[32:33], v[32:33], v[36:37] neg_lo:[0,1] neg_hi:[0,1]
	v_pk_add_f32 v[36:37], v[34:35], v[38:39]
	v_pk_add_f32 v[34:35], v[34:35], v[38:39] neg_lo:[0,1] neg_hi:[0,1]
	v_pk_add_f32 v[48:49], v[40:41], v[70:71]
	v_pk_add_f32 v[44:45], v[40:41], v[70:71] neg_lo:[0,1] neg_hi:[0,1]
	v_xor_b32_e32 v71, 0x80000000, v34
	v_mov_b32_e32 v70, v35
	v_pk_add_f32 v[42:43], v[68:69], v[36:37]
	v_pk_add_f32 v[38:39], v[68:69], v[36:37] neg_lo:[0,1] neg_hi:[0,1]
	v_pk_add_f32 v[68:69], v[24:25], v[28:29]
	v_pk_add_f32 v[24:25], v[24:25], v[28:29] neg_lo:[0,1] neg_hi:[0,1]
	v_pk_add_f32 v[28:29], v[26:27], v[30:31]
	v_pk_add_f32 v[26:27], v[26:27], v[30:31] neg_lo:[0,1] neg_hi:[0,1]
	v_pk_add_f32 v[40:41], v[32:33], v[70:71]
	v_pk_add_f32 v[36:37], v[32:33], v[70:71] neg_lo:[0,1] neg_hi:[0,1]
	v_xor_b32_e32 v71, 0x80000000, v26
	v_mov_b32_e32 v70, v27
	v_pk_add_f32 v[34:35], v[68:69], v[28:29]
	v_pk_add_f32 v[30:31], v[68:69], v[28:29] neg_lo:[0,1] neg_hi:[0,1]
	v_pk_add_f32 v[68:69], v[12:13], v[20:21]
	v_pk_add_f32 v[12:13], v[12:13], v[20:21] neg_lo:[0,1] neg_hi:[0,1]
	v_pk_add_f32 v[20:21], v[14:15], v[22:23]
	v_pk_add_f32 v[14:15], v[14:15], v[22:23] neg_lo:[0,1] neg_hi:[0,1]
	v_pk_add_f32 v[32:33], v[24:25], v[70:71]
	v_pk_add_f32 v[28:29], v[24:25], v[70:71] neg_lo:[0,1] neg_hi:[0,1]
	v_xor_b32_e32 v71, 0x80000000, v14
	v_mov_b32_e32 v70, v15
	v_pk_add_f32 v[14:15], v[6:7], v[18:19]
	v_pk_add_f32 v[6:7], v[6:7], v[18:19] neg_lo:[0,1] neg_hi:[0,1]
	v_pk_add_f32 v[26:27], v[68:69], v[20:21]
	v_pk_add_f32 v[24:25], v[12:13], v[70:71]
	v_pk_add_f32 v[22:23], v[68:69], v[20:21] neg_lo:[0,1] neg_hi:[0,1]
	v_pk_add_f32 v[20:21], v[12:13], v[70:71] neg_lo:[0,1] neg_hi:[0,1]
	v_pk_add_f32 v[12:13], v[4:5], v[16:17]
	v_pk_add_f32 v[4:5], v[4:5], v[16:17] neg_lo:[0,1] neg_hi:[0,1]
	v_xor_b32_e32 v69, 0x80000000, v6
	v_mov_b32_e32 v68, v7
	v_pk_add_f32 v[18:19], v[12:13], v[14:15]
	v_pk_add_f32 v[16:17], v[4:5], v[68:69]
	v_pk_add_f32 v[14:15], v[12:13], v[14:15] neg_lo:[0,1] neg_hi:[0,1]
	v_pk_add_f32 v[12:13], v[4:5], v[68:69] neg_lo:[0,1] neg_hi:[0,1]
	v_pk_add_f32 v[68:69], v[0:1], v[8:9]
	v_pk_add_f32 v[0:1], v[0:1], v[8:9] neg_lo:[0,1] neg_hi:[0,1]
	v_pk_add_f32 v[8:9], v[2:3], v[10:11]
	v_pk_add_f32 v[2:3], v[2:3], v[10:11] neg_lo:[0,1] neg_hi:[0,1]
	v_pk_add_f32 v[6:7], v[68:69], v[8:9]
	v_xor_b32_e32 v11, 0x80000000, v2
	v_mov_b32_e32 v10, v3
	v_pk_add_f32 v[2:3], v[68:69], v[8:9] neg_lo:[0,1] neg_hi:[0,1]
	v_mov_b32_e32 v8, v140
	s_waitcnt lgkmcnt(0)
	s_barrier
; #define LAS __attribute__((address_space(3)))
; __device__ __forceinline__ f32x2 cmul(f32x2 a, f32x2 b) { return (f32x2){a.x * b.x - a.y * b.y, a.x * b.y + a.y * b.x}; }
; #define LT() ({ int lt_ = tid; asm volatile("" : "+v"(lt_)); lt_; })
; __device__ __forceinline__ void hyena_latent(Frame& F, int l, int ch, LAS f32x2* X, const LAS f32x2* TH, const LAS f32x2* TL, GAS f32x2* KS, const LAS float* CT  , bool wr = true) {
;     ...
;             for (int i = 0; i < 8; ++i) { const int b = LT() + NTHR * i; LAS f32x4* P = (LAS f32x4*)(X + 4 * b + ((b >> 4) << 2)); const f32x4 u = P[0], v = P[1], k0 = kreg[2 * i], k1 = kreg[2 * i + 1];
;                 f32x2 x0 = {u.x, u.y}, x1 = {u.z, u.w}, x2 = {v.x, v.y}, x3 = {v.z, v.w}; r4<false>(x0, x1, x2, x3);
;                 x0 = cmul(x0, (f32x2){k0.x, k0.y}); x1 = cmul(x1, (f32x2){k0.z, k0.w}); x2 = cmul(x2, (f32x2){k1.x, k1.y}); x3 = cmul(x3, (f32x2){k1.z, k1.w});
;                 r4<true>(x0, x1, x2, x3);
;                 P[0] = (f32x4){x0.x, x0.y, x1.x, x1.y}; P[1] = (f32x4){x2.x, x2.y, x3.x, x3.y};
;                 if (i & 1) asm volatile("" ::: "memory"); }
	v_pk_add_f32 v[4:5], v[0:1], v[10:11]
	v_lshlrev_b32_e32 v9, 5, v8
	v_lshlrev_b32_e32 v8, 1, v8
	v_and_b32_e32 v8, 0xffffffe0, v8
	v_add3_u32 v76, 0, v9, v8
	v_pk_add_f32 v[0:1], v[0:1], v[10:11] neg_lo:[0,1] neg_hi:[0,1]
	ds_read_b128 v[8:11], v76
	ds_read_b128 v[68:71], v76 offset:16
	s_mov_b32 s0, 0
	s_mov_b64 s[12:13], -1
	s_waitcnt lgkmcnt(0)
	v_pk_add_f32 v[72:73], v[8:9], v[68:69]
	v_pk_add_f32 v[8:9], v[8:9], v[68:69] neg_lo:[0,1] neg_hi:[0,1]
	v_pk_add_f32 v[68:69], v[10:11], v[70:71]
	v_pk_add_f32 v[10:11], v[10:11], v[70:71] neg_lo:[0,1] neg_hi:[0,1]
	s_nop 0
	v_xor_b32_e32 v71, 0x80000000, v10
	v_mov_b32_e32 v70, v11
	v_pk_add_f32 v[10:11], v[72:73], v[68:69]
	v_pk_add_f32 v[74:75], v[8:9], v[70:71]
	v_pk_add_f32 v[8:9], v[8:9], v[70:71] neg_lo:[0,1] neg_hi:[0,1]
	v_pk_mul_f32 v[70:71], v[66:67], v[10:11] op_sel:[1,1] op_sel_hi:[0,1]
	v_pk_add_f32 v[68:69], v[72:73], v[68:69] neg_lo:[0,1] neg_hi:[0,1]
	v_pk_fma_f32 v[72:73], v[66:67], v[10:11], v[70:71] neg_lo:[0,0,1] neg_hi:[0,0,1]
	v_pk_fma_f32 v[10:11], v[66:67], v[10:11], v[70:71] op_sel_hi:[1,0,1]
	s_nop 0
	v_mov_b32_e32 v73, v11
	v_pk_mul_f32 v[10:11], v[64:65], v[74:75] op_sel:[1,1] op_sel_hi:[0,1]
	v_pk_fma_f32 v[66:67], v[64:65], v[74:75], v[10:11] neg_lo:[0,0,1] neg_hi:[0,0,1]
	v_pk_fma_f32 v[10:11], v[64:65], v[74:75], v[10:11] op_sel_hi:[1,0,1]
	s_nop 0
	v_mov_b32_e32 v67, v11
	v_pk_mul_f32 v[10:11], v[62:63], v[68:69] op_sel:[1,1] op_sel_hi:[0,1]
	v_pk_fma_f32 v[64:65], v[62:63], v[68:69], v[10:11] neg_lo:[0,0,1] neg_hi:[0,0,1]
	v_pk_fma_f32 v[10:11], v[62:63], v[68:69], v[10:11] op_sel_hi:[1,0,1]
	s_nop 0
	v_mov_b32_e32 v65, v11
	v_pk_mul_f32 v[10:11], v[60:61], v[8:9] op_sel:[1,1] op_sel_hi:[0,1]
	v_pk_fma_f32 v[62:63], v[60:61], v[8:9], v[10:11] neg_lo:[0,0,1] neg_hi:[0,0,1]
	v_pk_fma_f32 v[8:9], v[60:61], v[8:9], v[10:11] op_sel_hi:[1,0,1]
	v_pk_add_f32 v[60:61], v[72:73], v[64:65]
	v_mov_b32_e32 v63, v9
	v_pk_add_f32 v[8:9], v[66:67], v[62:63] neg_lo:[0,1] neg_hi:[0,1]
	v_pk_add_f32 v[64:65], v[72:73], v[64:65] neg_lo:[0,1] neg_hi:[0,1]
	v_pk_add_f32 v[68:69], v[66:67], v[62:63]
	v_xor_b32_e32 v62, 0x80000000, v9
	v_mov_b32_e32 v63, v8
	v_pk_add_f32 v[8:9], v[60:61], v[68:69]
	v_pk_add_f32 v[10:11], v[64:65], v[62:63]
	v_pk_add_f32 v[60:61], v[60:61], v[68:69] neg_lo:[0,1] neg_hi:[0,1]
	v_pk_add_f32 v[62:63], v[64:65], v[62:63] neg_lo:[0,1] neg_hi:[0,1]
	ds_write_b128 v76, v[8:11]
	ds_write_b128 v76, v[60:63] offset:16
	v_mov_b32_e32 v8, v140
	s_nop 0
	v_add_u32_e32 v8, 0x200, v8
	v_lshlrev_b32_e32 v9, 5, v8
	v_lshlrev_b32_e32 v8, 1, v8
	v_and_b32_e32 v8, 0xffffffe0, v8
	v_add3_u32 v68, 0, v9, v8
	ds_read_b128 v[8:11], v68
	ds_read_b128 v[60:63], v68 offset:16
	s_waitcnt lgkmcnt(0)
	v_pk_add_f32 v[64:65], v[8:9], v[60:61]
	v_pk_add_f32 v[8:9], v[8:9], v[60:61] neg_lo:[0,1] neg_hi:[0,1]
	v_pk_add_f32 v[60:61], v[10:11], v[62:63]
	v_pk_add_f32 v[10:11], v[10:11], v[62:63] neg_lo:[0,1] neg_hi:[0,1]
	s_nop 0
	v_xor_b32_e32 v63, 0x80000000, v10
	v_mov_b32_e32 v62, v11
	v_pk_add_f32 v[10:11], v[64:65], v[60:61]
	v_pk_add_f32 v[66:67], v[8:9], v[62:63]
	v_pk_add_f32 v[8:9], v[8:9], v[62:63] neg_lo:[0,1] neg_hi:[0,1]
	v_pk_mul_f32 v[62:63], v[58:59], v[10:11] op_sel:[1,1] op_sel_hi:[0,1]
	v_pk_add_f32 v[60:61], v[64:65], v[60:61] neg_lo:[0,1] neg_hi:[0,1]
	v_pk_fma_f32 v[64:65], v[58:59], v[10:11], v[62:63] neg_lo:[0,0,1] neg_hi:[0,0,1]
	v_pk_fma_f32 v[10:11], v[58:59], v[10:11], v[62:63] op_sel_hi:[1,0,1]
	s_nop 0
	v_mov_b32_e32 v65, v11
	v_pk_mul_f32 v[10:11], v[56:57], v[66:67] op_sel:[1,1] op_sel_hi:[0,1]
	v_pk_fma_f32 v[58:59], v[56:57], v[66:67], v[10:11] neg_lo:[0,0,1] neg_hi:[0,0,1]
	v_pk_fma_f32 v[10:11], v[56:57], v[66:67], v[10:11] op_sel_hi:[1,0,1]
	s_nop 0
	v_mov_b32_e32 v59, v11
	v_pk_mul_f32 v[10:11], v[54:55], v[60:61] op_sel:[1,1] op_sel_hi:[0,1]
	v_pk_fma_f32 v[56:57], v[54:55], v[60:61], v[10:11] neg_lo:[0,0,1] neg_hi:[0,0,1]
	v_pk_fma_f32 v[10:11], v[54:55], v[60:61], v[10:11] op_sel_hi:[1,0,1]
	s_nop 0
	v_mov_b32_e32 v57, v11
	v_pk_mul_f32 v[10:11], v[52:53], v[8:9] op_sel:[1,1] op_sel_hi:[0,1]
	v_pk_fma_f32 v[54:55], v[52:53], v[8:9], v[10:11] neg_lo:[0,0,1] neg_hi:[0,0,1]
	v_pk_fma_f32 v[8:9], v[52:53], v[8:9], v[10:11] op_sel_hi:[1,0,1]
	v_pk_add_f32 v[52:53], v[64:65], v[56:57]
	v_mov_b32_e32 v55, v9
	v_pk_add_f32 v[8:9], v[58:59], v[54:55] neg_lo:[0,1] neg_hi:[0,1]
	v_pk_add_f32 v[56:57], v[64:65], v[56:57] neg_lo:[0,1] neg_hi:[0,1]
	v_pk_add_f32 v[60:61], v[58:59], v[54:55]
	v_xor_b32_e32 v54, 0x80000000, v9
	v_mov_b32_e32 v55, v8
	v_pk_add_f32 v[8:9], v[52:53], v[60:61]
	v_pk_add_f32 v[10:11], v[56:57], v[54:55]
	v_pk_add_f32 v[52:53], v[52:53], v[60:61] neg_lo:[0,1] neg_hi:[0,1]
	v_pk_add_f32 v[54:55], v[56:57], v[54:55] neg_lo:[0,1] neg_hi:[0,1]
	ds_write_b128 v68, v[8:11]
	ds_write_b128 v68, v[52:55] offset:16
	v_mov_b32_e32 v8, v140
	s_nop 0
	v_add_u32_e32 v8, 0x400, v8
	v_lshlrev_b32_e32 v9, 5, v8
	v_lshlrev_b32_e32 v8, 1, v8
	v_and_b32_e32 v8, 0xffffffe0, v8
	v_add3_u32 v60, 0, v9, v8
	ds_read_b128 v[8:11], v60
	ds_read_b128 v[52:55], v60 offset:16
	s_waitcnt lgkmcnt(0)
; #define LAS __attribute__((address_space(3)))
; __device__ __forceinline__ f32x2 cmul(f32x2 a, f32x2 b) { return (f32x2){a.x * b.x - a.y * b.y, a.x * b.y + a.y * b.x}; }
; #define LT() ({ int lt_ = tid; asm volatile("" : "+v"(lt_)); lt_; })
; __device__ __forceinline__ void hyena_latent(Frame& F, int l, int ch, LAS f32x2* X, const LAS f32x2* TH, const LAS f32x2* TL, GAS f32x2* KS, const LAS float* CT  , bool wr = true) {
;     ...
;             for (int i = 0; i < 8; ++i) { const int b = LT() + NTHR * i; LAS f32x4* P = (LAS f32x4*)(X + 4 * b + ((b >> 4) << 2)); const f32x4 u = P[0], v = P[1], k0 = kreg[2 * i], k1 = kreg[2 * i + 1];
;                 f32x2 x0 = {u.x, u.y}, x1 = {u.z, u.w}, x2 = {v.x, v.y}, x3 = {v.z, v.w}; r4<false>(x0, x1, x2, x3);
;                 x0 = cmul(x0, (f32x2){k0.x, k0.y}); x1 = cmul(x1, (f32x2){k0.z, k0.w}); x2 = cmul(x2, (f32x2){k1.x, k1.y}); x3 = cmul(x3, (f32x2){k1.z, k1.w});
;                 r4<true>(x0, x1, x2, x3);
;                 P[0] = (f32x4){x0.x, x0.y, x1.x, x1.y}; P[1] = (f32x4){x2.x, x2.y, x3.x, x3.y};
;                 if (i & 1) asm volatile("" ::: "memory"); }
	v_pk_add_f32 v[56:57], v[8:9], v[52:53]
	v_pk_add_f32 v[8:9], v[8:9], v[52:53] neg_lo:[0,1] neg_hi:[0,1]
	v_pk_add_f32 v[52:53], v[10:11], v[54:55]
	v_pk_add_f32 v[10:11], v[10:11], v[54:55] neg_lo:[0,1] neg_hi:[0,1]
	s_nop 0
	v_xor_b32_e32 v55, 0x80000000, v10
	v_mov_b32_e32 v54, v11
	v_pk_add_f32 v[10:11], v[56:57], v[52:53]
	v_pk_add_f32 v[58:59], v[8:9], v[54:55]
	v_pk_add_f32 v[8:9], v[8:9], v[54:55] neg_lo:[0,1] neg_hi:[0,1]
	v_pk_mul_f32 v[54:55], v[50:51], v[10:11] op_sel:[1,1] op_sel_hi:[0,1]
	v_pk_add_f32 v[52:53], v[56:57], v[52:53] neg_lo:[0,1] neg_hi:[0,1]
	v_pk_fma_f32 v[56:57], v[50:51], v[10:11], v[54:55] neg_lo:[0,0,1] neg_hi:[0,0,1]
	v_pk_fma_f32 v[10:11], v[50:51], v[10:11], v[54:55] op_sel_hi:[1,0,1]
	s_nop 0
	v_mov_b32_e32 v57, v11
	v_pk_mul_f32 v[10:11], v[48:49], v[58:59] op_sel:[1,1] op_sel_hi:[0,1]
	v_pk_fma_f32 v[50:51], v[48:49], v[58:59], v[10:11] neg_lo:[0,0,1] neg_hi:[0,0,1]
	v_pk_fma_f32 v[10:11], v[48:49], v[58:59], v[10:11] op_sel_hi:[1,0,1]
	s_nop 0
	v_mov_b32_e32 v51, v11
	v_pk_mul_f32 v[10:11], v[46:47], v[52:53] op_sel:[1,1] op_sel_hi:[0,1]
	v_pk_fma_f32 v[48:49], v[46:47], v[52:53], v[10:11] neg_lo:[0,0,1] neg_hi:[0,0,1]
	v_pk_fma_f32 v[10:11], v[46:47], v[52:53], v[10:11] op_sel_hi:[1,0,1]
	s_nop 0
	v_mov_b32_e32 v49, v11
	v_pk_mul_f32 v[10:11], v[44:45], v[8:9] op_sel:[1,1] op_sel_hi:[0,1]
	v_pk_fma_f32 v[46:47], v[44:45], v[8:9], v[10:11] neg_lo:[0,0,1] neg_hi:[0,0,1]
	v_pk_fma_f32 v[8:9], v[44:45], v[8:9], v[10:11] op_sel_hi:[1,0,1]
	v_pk_add_f32 v[44:45], v[56:57], v[48:49]
	v_mov_b32_e32 v47, v9
	v_pk_add_f32 v[8:9], v[50:51], v[46:47] neg_lo:[0,1] neg_hi:[0,1]
	v_pk_add_f32 v[48:49], v[56:57], v[48:49] neg_lo:[0,1] neg_hi:[0,1]
	v_pk_add_f32 v[52:53], v[50:51], v[46:47]
	v_xor_b32_e32 v46, 0x80000000, v9
	v_mov_b32_e32 v47, v8
	v_pk_add_f32 v[8:9], v[44:45], v[52:53]
	v_pk_add_f32 v[10:11], v[48:49], v[46:47]
	v_pk_add_f32 v[44:45], v[44:45], v[52:53] neg_lo:[0,1] neg_hi:[0,1]
	v_pk_add_f32 v[46:47], v[48:49], v[46:47] neg_lo:[0,1] neg_hi:[0,1]
	ds_write_b128 v60, v[8:11]
	ds_write_b128 v60, v[44:47] offset:16
	v_mov_b32_e32 v8, v140
	s_nop 0
	v_add_u32_e32 v8, 0x600, v8
	v_lshlrev_b32_e32 v9, 5, v8
	v_lshlrev_b32_e32 v8, 1, v8
	v_and_b32_e32 v8, 0xffffffe0, v8
	v_add3_u32 v52, 0, v9, v8
	ds_read_b128 v[8:11], v52
	ds_read_b128 v[44:47], v52 offset:16
	s_waitcnt lgkmcnt(0)
	v_pk_add_f32 v[48:49], v[8:9], v[44:45]
	v_pk_add_f32 v[8:9], v[8:9], v[44:45] neg_lo:[0,1] neg_hi:[0,1]
	v_pk_add_f32 v[44:45], v[10:11], v[46:47]
	v_pk_add_f32 v[10:11], v[10:11], v[46:47] neg_lo:[0,1] neg_hi:[0,1]
	s_nop 0
	v_xor_b32_e32 v47, 0x80000000, v10
	v_mov_b32_e32 v46, v11
	v_pk_add_f32 v[10:11], v[48:49], v[44:45]
	v_pk_add_f32 v[50:51], v[8:9], v[46:47]
	v_pk_add_f32 v[8:9], v[8:9], v[46:47] neg_lo:[0,1] neg_hi:[0,1]
	v_pk_mul_f32 v[46:47], v[42:43], v[10:11] op_sel:[1,1] op_sel_hi:[0,1]
	v_pk_add_f32 v[44:45], v[48:49], v[44:45] neg_lo:[0,1] neg_hi:[0,1]
	v_pk_fma_f32 v[48:49], v[42:43], v[10:11], v[46:47] neg_lo:[0,0,1] neg_hi:[0,0,1]
	v_pk_fma_f32 v[10:11], v[42:43], v[10:11], v[46:47] op_sel_hi:[1,0,1]
	s_nop 0
	v_mov_b32_e32 v49, v11
	v_pk_mul_f32 v[10:11], v[40:41], v[50:51] op_sel:[1,1] op_sel_hi:[0,1]
	v_pk_fma_f32 v[42:43], v[40:41], v[50:51], v[10:11] neg_lo:[0,0,1] neg_hi:[0,0,1]
	v_pk_fma_f32 v[10:11], v[40:41], v[50:51], v[10:11] op_sel_hi:[1,0,1]
	s_nop 0
	v_mov_b32_e32 v43, v11
	v_pk_mul_f32 v[10:11], v[38:39], v[44:45] op_sel:[1,1] op_sel_hi:[0,1]
	v_pk_fma_f32 v[40:41], v[38:39], v[44:45], v[10:11] neg_lo:[0,0,1] neg_hi:[0,0,1]
	v_pk_fma_f32 v[10:11], v[38:39], v[44:45], v[10:11] op_sel_hi:[1,0,1]
	s_nop 0
	v_mov_b32_e32 v41, v11
	v_pk_mul_f32 v[10:11], v[36:37], v[8:9] op_sel:[1,1] op_sel_hi:[0,1]
	v_pk_fma_f32 v[38:39], v[36:37], v[8:9], v[10:11] neg_lo:[0,0,1] neg_hi:[0,0,1]
	v_pk_fma_f32 v[8:9], v[36:37], v[8:9], v[10:11] op_sel_hi:[1,0,1]
	v_pk_add_f32 v[36:37], v[48:49], v[40:41]
	v_mov_b32_e32 v39, v9
	v_pk_add_f32 v[8:9], v[42:43], v[38:39] neg_lo:[0,1] neg_hi:[0,1]
	v_pk_add_f32 v[40:41], v[48:49], v[40:41] neg_lo:[0,1] neg_hi:[0,1]
	v_pk_add_f32 v[44:45], v[42:43], v[38:39]
	v_xor_b32_e32 v38, 0x80000000, v9
	v_mov_b32_e32 v39, v8
	v_pk_add_f32 v[8:9], v[36:37], v[44:45]
	v_pk_add_f32 v[10:11], v[40:41], v[38:39]
	v_pk_add_f32 v[36:37], v[36:37], v[44:45] neg_lo:[0,1] neg_hi:[0,1]
	v_pk_add_f32 v[38:39], v[40:41], v[38:39] neg_lo:[0,1] neg_hi:[0,1]
	ds_write_b128 v52, v[8:11]
	ds_write_b128 v52, v[36:39] offset:16
	v_mov_b32_e32 v8, v140
	s_nop 0
	v_add_u32_e32 v8, 0x800, v8
	v_lshlrev_b32_e32 v9, 5, v8
	v_lshlrev_b32_e32 v8, 1, v8
	v_and_b32_e32 v8, 0xffffffe0, v8
	v_add3_u32 v44, 0, v9, v8
	ds_read_b128 v[8:11], v44
	ds_read_b128 v[36:39], v44 offset:16
	s_waitcnt lgkmcnt(0)
; #define LAS __attribute__((address_space(3)))
; __device__ __forceinline__ f32x2 cmul(f32x2 a, f32x2 b) { return (f32x2){a.x * b.x - a.y * b.y, a.x * b.y + a.y * b.x}; }
; #define LT() ({ int lt_ = tid; asm volatile("" : "+v"(lt_)); lt_; })
; __device__ __forceinline__ void hyena_latent(Frame& F, int l, int ch, LAS f32x2* X, const LAS f32x2* TH, const LAS f32x2* TL, GAS f32x2* KS, const LAS float* CT  , bool wr = true) {
;     ...
;             for (int i = 0; i < 8; ++i) { const int b = LT() + NTHR * i; LAS f32x4* P = (LAS f32x4*)(X + 4 * b + ((b >> 4) << 2)); const f32x4 u = P[0], v = P[1], k0 = kreg[2 * i], k1 = kreg[2 * i + 1];
;                 f32x2 x0 = {u.x, u.y}, x1 = {u.z, u.w}, x2 = {v.x, v.y}, x3 = {v.z, v.w}; r4<false>(x0, x1, x2, x3);
;                 x0 = cmul(x0, (f32x2){k0.x, k0.y}); x1 = cmul(x1, (f32x2){k0.z, k0.w}); x2 = cmul(x2, (f32x2){k1.x, k1.y}); x3 = cmul(x3, (f32x2){k1.z, k1.w});
;                 r4<true>(x0, x1, x2, x3);
;                 P[0] = (f32x4){x0.x, x0.y, x1.x, x1.y}; P[1] = (f32x4){x2.x, x2.y, x3.x, x3.y};
;                 if (i & 1) asm volatile("" ::: "memory"); }
	v_pk_add_f32 v[40:41], v[8:9], v[36:37]
	v_pk_add_f32 v[8:9], v[8:9], v[36:37] neg_lo:[0,1] neg_hi:[0,1]
	v_pk_add_f32 v[36:37], v[10:11], v[38:39]
	v_pk_add_f32 v[10:11], v[10:11], v[38:39] neg_lo:[0,1] neg_hi:[0,1]
	s_nop 0
	v_xor_b32_e32 v39, 0x80000000, v10
	v_mov_b32_e32 v38, v11
	v_pk_add_f32 v[10:11], v[40:41], v[36:37]
	v_pk_add_f32 v[42:43], v[8:9], v[38:39]
	v_pk_add_f32 v[8:9], v[8:9], v[38:39] neg_lo:[0,1] neg_hi:[0,1]
	v_pk_mul_f32 v[38:39], v[34:35], v[10:11] op_sel:[1,1] op_sel_hi:[0,1]
	v_pk_add_f32 v[36:37], v[40:41], v[36:37] neg_lo:[0,1] neg_hi:[0,1]
	v_pk_fma_f32 v[40:41], v[34:35], v[10:11], v[38:39] neg_lo:[0,0,1] neg_hi:[0,0,1]
	v_pk_fma_f32 v[10:11], v[34:35], v[10:11], v[38:39] op_sel_hi:[1,0,1]
	s_nop 0
	v_mov_b32_e32 v41, v11
	v_pk_mul_f32 v[10:11], v[32:33], v[42:43] op_sel:[1,1] op_sel_hi:[0,1]
	v_pk_fma_f32 v[34:35], v[32:33], v[42:43], v[10:11] neg_lo:[0,0,1] neg_hi:[0,0,1]
	v_pk_fma_f32 v[10:11], v[32:33], v[42:43], v[10:11] op_sel_hi:[1,0,1]
	s_nop 0
	v_mov_b32_e32 v35, v11
	v_pk_mul_f32 v[10:11], v[30:31], v[36:37] op_sel:[1,1] op_sel_hi:[0,1]
	v_pk_fma_f32 v[32:33], v[30:31], v[36:37], v[10:11] neg_lo:[0,0,1] neg_hi:[0,0,1]
	v_pk_fma_f32 v[10:11], v[30:31], v[36:37], v[10:11] op_sel_hi:[1,0,1]
	s_nop 0
	v_mov_b32_e32 v33, v11
	v_pk_mul_f32 v[10:11], v[28:29], v[8:9] op_sel:[1,1] op_sel_hi:[0,1]
	v_pk_fma_f32 v[30:31], v[28:29], v[8:9], v[10:11] neg_lo:[0,0,1] neg_hi:[0,0,1]
	v_pk_fma_f32 v[8:9], v[28:29], v[8:9], v[10:11] op_sel_hi:[1,0,1]
	v_pk_add_f32 v[28:29], v[40:41], v[32:33]
	v_mov_b32_e32 v31, v9
	v_pk_add_f32 v[8:9], v[34:35], v[30:31] neg_lo:[0,1] neg_hi:[0,1]
	v_pk_add_f32 v[32:33], v[40:41], v[32:33] neg_lo:[0,1] neg_hi:[0,1]
	v_pk_add_f32 v[36:37], v[34:35], v[30:31]
	v_xor_b32_e32 v30, 0x80000000, v9
	v_mov_b32_e32 v31, v8
	v_pk_add_f32 v[8:9], v[28:29], v[36:37]
	v_pk_add_f32 v[10:11], v[32:33], v[30:31]
	v_pk_add_f32 v[28:29], v[28:29], v[36:37] neg_lo:[0,1] neg_hi:[0,1]
	v_pk_add_f32 v[30:31], v[32:33], v[30:31] neg_lo:[0,1] neg_hi:[0,1]
	ds_write_b128 v44, v[8:11]
	ds_write_b128 v44, v[28:31] offset:16
	v_mov_b32_e32 v8, v140
	s_nop 0
	v_add_u32_e32 v8, 0xa00, v8
	v_lshlrev_b32_e32 v9, 5, v8
	v_lshlrev_b32_e32 v8, 1, v8
	v_and_b32_e32 v8, 0xffffffe0, v8
	v_add3_u32 v36, 0, v9, v8
	ds_read_b128 v[8:11], v36
	ds_read_b128 v[28:31], v36 offset:16
	s_waitcnt lgkmcnt(0)
	v_pk_add_f32 v[32:33], v[8:9], v[28:29]
	v_pk_add_f32 v[8:9], v[8:9], v[28:29] neg_lo:[0,1] neg_hi:[0,1]
	v_pk_add_f32 v[28:29], v[10:11], v[30:31]
	v_pk_add_f32 v[10:11], v[10:11], v[30:31] neg_lo:[0,1] neg_hi:[0,1]
	s_nop 0
	v_xor_b32_e32 v31, 0x80000000, v10
	v_mov_b32_e32 v30, v11
	v_pk_add_f32 v[10:11], v[32:33], v[28:29]
	v_pk_add_f32 v[34:35], v[8:9], v[30:31]
	v_pk_add_f32 v[8:9], v[8:9], v[30:31] neg_lo:[0,1] neg_hi:[0,1]
	v_pk_mul_f32 v[30:31], v[26:27], v[10:11] op_sel:[1,1] op_sel_hi:[0,1]
	v_pk_add_f32 v[28:29], v[32:33], v[28:29] neg_lo:[0,1] neg_hi:[0,1]
	v_pk_fma_f32 v[32:33], v[26:27], v[10:11], v[30:31] neg_lo:[0,0,1] neg_hi:[0,0,1]
	v_pk_fma_f32 v[10:11], v[26:27], v[10:11], v[30:31] op_sel_hi:[1,0,1]
	s_nop 0
	v_mov_b32_e32 v33, v11
	v_pk_mul_f32 v[10:11], v[24:25], v[34:35] op_sel:[1,1] op_sel_hi:[0,1]
	v_pk_fma_f32 v[26:27], v[24:25], v[34:35], v[10:11] neg_lo:[0,0,1] neg_hi:[0,0,1]
	v_pk_fma_f32 v[10:11], v[24:25], v[34:35], v[10:11] op_sel_hi:[1,0,1]
	s_nop 0
	v_mov_b32_e32 v27, v11
	v_pk_mul_f32 v[10:11], v[22:23], v[28:29] op_sel:[1,1] op_sel_hi:[0,1]
	v_pk_fma_f32 v[24:25], v[22:23], v[28:29], v[10:11] neg_lo:[0,0,1] neg_hi:[0,0,1]
	v_pk_fma_f32 v[10:11], v[22:23], v[28:29], v[10:11] op_sel_hi:[1,0,1]
	s_nop 0
	v_mov_b32_e32 v25, v11
	v_pk_mul_f32 v[10:11], v[20:21], v[8:9] op_sel:[1,1] op_sel_hi:[0,1]
	v_pk_fma_f32 v[22:23], v[20:21], v[8:9], v[10:11] neg_lo:[0,0,1] neg_hi:[0,0,1]
	v_pk_fma_f32 v[8:9], v[20:21], v[8:9], v[10:11] op_sel_hi:[1,0,1]
	v_pk_add_f32 v[20:21], v[32:33], v[24:25]
	v_mov_b32_e32 v23, v9
	v_pk_add_f32 v[8:9], v[26:27], v[22:23] neg_lo:[0,1] neg_hi:[0,1]
	v_pk_add_f32 v[24:25], v[32:33], v[24:25] neg_lo:[0,1] neg_hi:[0,1]
	v_pk_add_f32 v[28:29], v[26:27], v[22:23]
	v_xor_b32_e32 v22, 0x80000000, v9
	v_mov_b32_e32 v23, v8
	v_pk_add_f32 v[8:9], v[20:21], v[28:29]
	v_pk_add_f32 v[10:11], v[24:25], v[22:23]
	v_pk_add_f32 v[20:21], v[20:21], v[28:29] neg_lo:[0,1] neg_hi:[0,1]
	v_pk_add_f32 v[22:23], v[24:25], v[22:23] neg_lo:[0,1] neg_hi:[0,1]
	ds_write_b128 v36, v[8:11]
	ds_write_b128 v36, v[20:23] offset:16
	v_mov_b32_e32 v8, v140
	s_nop 0
	v_add_u32_e32 v8, 0xc00, v8
	v_lshlrev_b32_e32 v9, 5, v8
	v_lshlrev_b32_e32 v8, 1, v8
	v_and_b32_e32 v8, 0xffffffe0, v8
	v_add3_u32 v28, 0, v9, v8
	ds_read_b128 v[8:11], v28
	ds_read_b128 v[20:23], v28 offset:16
	s_waitcnt lgkmcnt(0)
; #define LAS __attribute__((address_space(3)))
; __device__ __forceinline__ f32x2 cmul(f32x2 a, f32x2 b) { return (f32x2){a.x * b.x - a.y * b.y, a.x * b.y + a.y * b.x}; }
; #define LT() ({ int lt_ = tid; asm volatile("" : "+v"(lt_)); lt_; })
; template <bool INV> __device__ __forceinline__ void bfly16_tab(f32x2 (&x)[16], const LAS f32x2* T, int tstride, int j) {
;     if (INV) {
; #pragma unroll
;         for (int q = 1; q < 16; ++q) { f32x2 p = T[q * tstride + j]; p.y = -p.y; x[q] = cmul(x[q], p); } }
; template <bool INV> __device__ __forceinline__ void pass16_s4(LAS f32x2* X, const LAS f32x2* TH, const LAS f32x2* TL, int tid) {
; #pragma unroll 1
;     for (int s = 0; s < 2; ++s) {
;         const int b = tid + NTHR * s, blk = b >> 2, jj = b & 3;
;         LAS f32x2* P = X + blk * 68 + jj;
;         f32x2 x[16];
; #pragma unroll
;         for (int q = 0; q < 16; ++q) x[q] = P[4 * q];
;         bfly16_tab<INV>(x, TH - 1024, 4, jj);
; __device__ __forceinline__ void hyena_latent(Frame& F, int l, int ch, LAS f32x2* X, const LAS f32x2* TH, const LAS f32x2* TL, GAS f32x2* KS, const LAS float* CT  , bool wr = true) {
;     ...
;             for (int i = 0; i < 8; ++i) { const int b = LT() + NTHR * i; LAS f32x4* P = (LAS f32x4*)(X + 4 * b + ((b >> 4) << 2)); const f32x4 u = P[0], v = P[1], k0 = kreg[2 * i], k1 = kreg[2 * i + 1];
;                 f32x2 x0 = {u.x, u.y}, x1 = {u.z, u.w}, x2 = {v.x, v.y}, x3 = {v.z, v.w}; r4<false>(x0, x1, x2, x3);
;                 x0 = cmul(x0, (f32x2){k0.x, k0.y}); x1 = cmul(x1, (f32x2){k0.z, k0.w}); x2 = cmul(x2, (f32x2){k1.x, k1.y}); x3 = cmul(x3, (f32x2){k1.z, k1.w});
;                 r4<true>(x0, x1, x2, x3);
;                 P[0] = (f32x4){x0.x, x0.y, x1.x, x1.y}; P[1] = (f32x4){x2.x, x2.y, x3.x, x3.y};
;                 if (i & 1) asm volatile("" ::: "memory"); }
	v_pk_add_f32 v[24:25], v[8:9], v[20:21]
	v_pk_add_f32 v[8:9], v[8:9], v[20:21] neg_lo:[0,1] neg_hi:[0,1]
	v_pk_add_f32 v[20:21], v[10:11], v[22:23]
	v_pk_add_f32 v[10:11], v[10:11], v[22:23] neg_lo:[0,1] neg_hi:[0,1]
	s_nop 0
	v_xor_b32_e32 v23, 0x80000000, v10
	v_mov_b32_e32 v22, v11
	v_pk_add_f32 v[10:11], v[24:25], v[20:21]
	v_pk_add_f32 v[26:27], v[8:9], v[22:23]
	v_pk_add_f32 v[8:9], v[8:9], v[22:23] neg_lo:[0,1] neg_hi:[0,1]
	v_pk_mul_f32 v[22:23], v[18:19], v[10:11] op_sel:[1,1] op_sel_hi:[0,1]
	v_pk_add_f32 v[20:21], v[24:25], v[20:21] neg_lo:[0,1] neg_hi:[0,1]
	v_pk_fma_f32 v[24:25], v[18:19], v[10:11], v[22:23] neg_lo:[0,0,1] neg_hi:[0,0,1]
	v_pk_fma_f32 v[10:11], v[18:19], v[10:11], v[22:23] op_sel_hi:[1,0,1]
	s_nop 0
	v_mov_b32_e32 v25, v11
	v_pk_mul_f32 v[10:11], v[16:17], v[26:27] op_sel:[1,1] op_sel_hi:[0,1]
	v_pk_fma_f32 v[18:19], v[16:17], v[26:27], v[10:11] neg_lo:[0,0,1] neg_hi:[0,0,1]
	v_pk_fma_f32 v[10:11], v[16:17], v[26:27], v[10:11] op_sel_hi:[1,0,1]
	s_nop 0
	v_mov_b32_e32 v19, v11
	v_pk_mul_f32 v[10:11], v[14:15], v[20:21] op_sel:[1,1] op_sel_hi:[0,1]
	v_pk_fma_f32 v[16:17], v[14:15], v[20:21], v[10:11] neg_lo:[0,0,1] neg_hi:[0,0,1]
	v_pk_fma_f32 v[10:11], v[14:15], v[20:21], v[10:11] op_sel_hi:[1,0,1]
	s_nop 0
	v_mov_b32_e32 v17, v11
	v_pk_mul_f32 v[10:11], v[12:13], v[8:9] op_sel:[1,1] op_sel_hi:[0,1]
	v_pk_fma_f32 v[14:15], v[12:13], v[8:9], v[10:11] neg_lo:[0,0,1] neg_hi:[0,0,1]
	v_pk_fma_f32 v[8:9], v[12:13], v[8:9], v[10:11] op_sel_hi:[1,0,1]
	v_pk_add_f32 v[12:13], v[24:25], v[16:17]
	v_mov_b32_e32 v15, v9
	v_pk_add_f32 v[8:9], v[18:19], v[14:15] neg_lo:[0,1] neg_hi:[0,1]
	v_pk_add_f32 v[16:17], v[24:25], v[16:17] neg_lo:[0,1] neg_hi:[0,1]
	v_pk_add_f32 v[20:21], v[18:19], v[14:15]
	v_xor_b32_e32 v14, 0x80000000, v9
	v_mov_b32_e32 v15, v8
	v_pk_add_f32 v[8:9], v[12:13], v[20:21]
	v_pk_add_f32 v[10:11], v[16:17], v[14:15]
	v_pk_add_f32 v[12:13], v[12:13], v[20:21] neg_lo:[0,1] neg_hi:[0,1]
	v_pk_add_f32 v[14:15], v[16:17], v[14:15] neg_lo:[0,1] neg_hi:[0,1]
	ds_write_b128 v28, v[8:11]
	ds_write_b128 v28, v[12:15] offset:16
	v_mov_b32_e32 v8, v140
	s_nop 0
	v_add_u32_e32 v8, 0xe00, v8
	v_lshlrev_b32_e32 v9, 5, v8
	v_lshlrev_b32_e32 v8, 1, v8
	v_and_b32_e32 v8, 0xffffffe0, v8
	v_add3_u32 v20, 0, v9, v8
	ds_read_b128 v[8:11], v20
	ds_read_b128 v[12:15], v20 offset:16
	s_waitcnt lgkmcnt(0)
	v_pk_add_f32 v[16:17], v[8:9], v[12:13]
	v_pk_add_f32 v[8:9], v[8:9], v[12:13] neg_lo:[0,1] neg_hi:[0,1]
	v_pk_add_f32 v[12:13], v[10:11], v[14:15]
	v_pk_add_f32 v[10:11], v[10:11], v[14:15] neg_lo:[0,1] neg_hi:[0,1]
	s_nop 0
	v_xor_b32_e32 v15, 0x80000000, v10
	v_mov_b32_e32 v14, v11
	v_pk_add_f32 v[10:11], v[16:17], v[12:13]
	v_pk_add_f32 v[18:19], v[8:9], v[14:15]
	v_pk_add_f32 v[8:9], v[8:9], v[14:15] neg_lo:[0,1] neg_hi:[0,1]
	v_pk_mul_f32 v[14:15], v[6:7], v[10:11] op_sel:[1,1] op_sel_hi:[0,1]
	v_pk_add_f32 v[12:13], v[16:17], v[12:13] neg_lo:[0,1] neg_hi:[0,1]
	v_pk_fma_f32 v[16:17], v[6:7], v[10:11], v[14:15] neg_lo:[0,0,1] neg_hi:[0,0,1]
	v_pk_fma_f32 v[6:7], v[6:7], v[10:11], v[14:15] op_sel_hi:[1,0,1]
	s_nop 0
	v_mov_b32_e32 v17, v7
	v_pk_mul_f32 v[6:7], v[4:5], v[18:19] op_sel:[1,1] op_sel_hi:[0,1]
	v_pk_fma_f32 v[10:11], v[4:5], v[18:19], v[6:7] neg_lo:[0,0,1] neg_hi:[0,0,1]
	v_pk_fma_f32 v[4:5], v[4:5], v[18:19], v[6:7] op_sel_hi:[1,0,1]
	s_nop 0
	v_mov_b32_e32 v11, v5
	v_pk_mul_f32 v[4:5], v[2:3], v[12:13] op_sel:[1,1] op_sel_hi:[0,1]
	v_pk_fma_f32 v[6:7], v[2:3], v[12:13], v[4:5] neg_lo:[0,0,1] neg_hi:[0,0,1]
	v_pk_fma_f32 v[2:3], v[2:3], v[12:13], v[4:5] op_sel_hi:[1,0,1]
	s_nop 0
	v_mov_b32_e32 v7, v3
	v_pk_mul_f32 v[2:3], v[0:1], v[8:9] op_sel:[1,1] op_sel_hi:[0,1]
	v_pk_fma_f32 v[4:5], v[0:1], v[8:9], v[2:3] neg_lo:[0,0,1] neg_hi:[0,0,1]
	v_pk_fma_f32 v[0:1], v[0:1], v[8:9], v[2:3] op_sel_hi:[1,0,1]
	v_pk_add_f32 v[8:9], v[16:17], v[6:7]
	v_mov_b32_e32 v5, v1
	v_pk_add_f32 v[0:1], v[10:11], v[4:5] neg_lo:[0,1] neg_hi:[0,1]
	v_pk_add_f32 v[6:7], v[16:17], v[6:7] neg_lo:[0,1] neg_hi:[0,1]
	v_pk_add_f32 v[12:13], v[10:11], v[4:5]
	v_xor_b32_e32 v10, 0x80000000, v1
	v_mov_b32_e32 v11, v0
	v_pk_add_f32 v[0:1], v[8:9], v[12:13]
	v_pk_add_f32 v[2:3], v[6:7], v[10:11]
	v_pk_add_f32 v[4:5], v[8:9], v[12:13] neg_lo:[0,1] neg_hi:[0,1]
	v_pk_add_f32 v[6:7], v[6:7], v[10:11] neg_lo:[0,1] neg_hi:[0,1]
	ds_write_b128 v20, v[0:3]
	ds_write_b128 v20, v[4:7] offset:16
	s_waitcnt lgkmcnt(0)
	s_barrier
	ds_read2_b64 v[232:235], v141 offset0:4 offset1:8
	ds_read2_b64 v[208:211], v141 offset0:12 offset1:16
	ds_read2_b64 v[204:207], v141 offset0:20 offset1:24
	ds_read2_b64 v[200:203], v141 offset0:28 offset1:32
	ds_read2_b64 v[196:199], v141 offset0:36 offset1:40
	ds_read2_b64 v[192:195], v141 offset0:44 offset1:48
	ds_read2_b64 v[188:191], v141 offset0:52 offset1:56
	ds_read_b64 v[186:187], v141 offset:480
; #define LAS __attribute__((address_space(3)))
; __device__ __forceinline__ f32x2 cmul(f32x2 a, f32x2 b) { return (f32x2){a.x * b.x - a.y * b.y, a.x * b.y + a.y * b.x}; }
; template <bool INV> __device__ __forceinline__ void bfly16_tab(f32x2 (&x)[16], const LAS f32x2* T, int tstride, int j) {
;     if (INV) {
; #pragma unroll
;         for (int q = 1; q < 16; ++q) { f32x2 p = T[q * tstride + j]; p.y = -p.y; x[q] = cmul(x[q], p); } }
;     dft16<INV>(x);
;     if (!INV) {
; #pragma unroll
;         for (int r = 1; r < 16; ++r) { const f32x2 p = T[r * tstride + j]; x[4 * (r & 3) + (r >> 2)] = cmul(x[4 * (r & 3) + (r >> 2)], p); } }
; }
; template <bool INV> __device__ __forceinline__ void pass16_s64(LAS f32x2* X, const LAS f32x2* TH, int base, int j) {
;     f32x2 x[16];
; #pragma unroll
;     for (int q = 0; q < 16; ++q) x[q] = X[base + q * 68];
;     bfly16_tab<INV>(x, TH - 2048, 64, j);
; #pragma unroll
;     for (int c = 0; c < 4; ++c)
; #pragma unroll
;         for (int d = 0; d < 4; ++d) X[base + (c + 4 * d) * 68] = x[4 * c + d];
; }
; template <bool INV> __device__ __forceinline__ void pass16(LAS f32x2* X, const LAS f32x2* TH, const LAS f32x2* TL, int base, int stride, int tw) {
;     f32x2 x[16];
; #pragma unroll
;     for (int q = 0; q < 16; ++q) x[q] = X[base + q * stride];
;     bfly16<INV>(x, TH, TL, tw);
; #pragma unroll
;     for (int c = 0; c < 4; ++c)
; #pragma unroll
;         for (int d = 0; d < 4; ++d) X[base + (c + 4 * d) * stride] = x[4 * c + d];
; }
; template <bool INV> __device__ __forceinline__ void pass16_s4(LAS f32x2* X, const LAS f32x2* TH, const LAS f32x2* TL, int tid) {
; #pragma unroll 1
;     for (int s = 0; s < 2; ++s) {
;         const int b = tid + NTHR * s, blk = b >> 2, jj = b & 3;
;         LAS f32x2* P = X + blk * 68 + jj;
;         f32x2 x[16];
; #pragma unroll
;         for (int q = 0; q < 16; ++q) x[q] = P[4 * q];
;         bfly16_tab<INV>(x, TH - 1024, 4, jj);
; #pragma unroll
;         for (int c = 0; c < 4; ++c)
; #pragma unroll
;             for (int d = 0; d < 4; ++d) P[4 * (c + 4 * d)] = x[4 * c + d];
;     }
; }
.LBB0_852:
	v_add_u32_e32 v128, s0, v140
	v_lshrrev_b32_e32 v147, 2, v128
	v_mad_u32_u24 v151, v147, s43, v144
	ds_read_b64 v[0:1], v151 offset:32
	ds_read_b64 v[2:3], v151 offset:64
	ds_read_b64 v[4:5], v151 offset:96
	ds_read_b64 v[6:7], v151 offset:128
	ds_read_b64 v[8:9], v151 offset:160
	ds_read_b64 v[10:11], v151 offset:192
	ds_read_b64 v[12:13], v151 offset:224
	ds_read_b64 v[14:15], v151 offset:256
	ds_read_b64 v[16:17], v151 offset:288
	ds_read_b64 v[18:19], v151 offset:320
	ds_read_b64 v[20:21], v151 offset:352
	ds_read_b64 v[22:23], v151 offset:384
	ds_read_b64 v[24:25], v151 offset:416
	ds_read_b64 v[26:27], v151 offset:448
	ds_read_b64 v[28:29], v151 offset:480
	ds_read_b64 v[30:31], v151 offset:0
	s_cmp_eq_u32 s0, 0
	s_movk_i32 s0, 0x200
	s_mov_b64 s[12:13], 0
	s_waitcnt lgkmcnt(15)
	v_pk_mul_f32 v[32:33], v[0:1], v[232:233] op_sel:[0,1] op_sel_hi:[1,1]
	s_waitcnt lgkmcnt(14)
	v_pk_mul_f32 v[34:35], v[2:3], v[234:235] op_sel:[0,1] op_sel_hi:[1,1]
	v_pk_fma_f32 v[32:33], v[0:1], v[232:233], v[32:33] op_sel:[0,0,1] op_sel_hi:[1,0,0] neg_hi:[0,0,1]
	s_waitcnt lgkmcnt(13)
	v_pk_mul_f32 v[0:1], v[4:5], v[208:209] op_sel:[0,1] op_sel_hi:[1,1]
	v_pk_fma_f32 v[2:3], v[2:3], v[234:235], v[34:35] op_sel:[0,0,1] op_sel_hi:[1,0,0] neg_hi:[0,0,1]
	s_waitcnt lgkmcnt(12)
	v_pk_mul_f32 v[34:35], v[6:7], v[210:211] op_sel:[0,1] op_sel_hi:[1,1]
	v_pk_fma_f32 v[4:5], v[4:5], v[208:209], v[0:1] op_sel:[0,0,1] op_sel_hi:[1,0,0] neg_hi:[0,0,1]
	s_waitcnt lgkmcnt(11)
	v_pk_mul_f32 v[0:1], v[8:9], v[204:205] op_sel:[0,1] op_sel_hi:[1,1]
	v_pk_fma_f32 v[34:35], v[6:7], v[210:211], v[34:35] op_sel:[0,0,1] op_sel_hi:[1,0,0] neg_hi:[0,0,1]
	s_waitcnt lgkmcnt(10)
	v_pk_mul_f32 v[6:7], v[10:11], v[206:207] op_sel:[0,1] op_sel_hi:[1,1]
	v_pk_fma_f32 v[8:9], v[8:9], v[204:205], v[0:1] op_sel:[0,0,1] op_sel_hi:[1,0,0] neg_hi:[0,0,1]
	s_waitcnt lgkmcnt(9)
	v_pk_mul_f32 v[0:1], v[12:13], v[200:201] op_sel:[0,1] op_sel_hi:[1,1]
	v_pk_fma_f32 v[6:7], v[10:11], v[206:207], v[6:7] op_sel:[0,0,1] op_sel_hi:[1,0,0] neg_hi:[0,0,1]
	s_waitcnt lgkmcnt(8)
	v_pk_mul_f32 v[10:11], v[14:15], v[202:203] op_sel:[0,1] op_sel_hi:[1,1]
	v_pk_fma_f32 v[0:1], v[12:13], v[200:201], v[0:1] op_sel:[0,0,1] op_sel_hi:[1,0,0] neg_hi:[0,0,1]
	s_waitcnt lgkmcnt(7)
	v_pk_mul_f32 v[12:13], v[16:17], v[196:197] op_sel:[0,1] op_sel_hi:[1,1]
	v_pk_fma_f32 v[14:15], v[14:15], v[202:203], v[10:11] op_sel:[0,0,1] op_sel_hi:[1,0,0] neg_hi:[0,0,1]
	s_waitcnt lgkmcnt(6)
	v_pk_mul_f32 v[10:11], v[18:19], v[198:199] op_sel:[0,1] op_sel_hi:[1,1]
	v_pk_fma_f32 v[16:17], v[16:17], v[196:197], v[12:13] op_sel:[0,0,1] op_sel_hi:[1,0,0] neg_hi:[0,0,1]
	s_waitcnt lgkmcnt(5)
	v_pk_mul_f32 v[12:13], v[20:21], v[192:193] op_sel:[0,1] op_sel_hi:[1,1]
	v_pk_fma_f32 v[10:11], v[18:19], v[198:199], v[10:11] op_sel:[0,0,1] op_sel_hi:[1,0,0] neg_hi:[0,0,1]
	s_waitcnt lgkmcnt(4)
	v_pk_mul_f32 v[18:19], v[22:23], v[194:195] op_sel:[0,1] op_sel_hi:[1,1]
	v_pk_fma_f32 v[20:21], v[20:21], v[192:193], v[12:13] op_sel:[0,0,1] op_sel_hi:[1,0,0] neg_hi:[0,0,1]
	s_waitcnt lgkmcnt(3)
	v_pk_mul_f32 v[12:13], v[24:25], v[188:189] op_sel:[0,1] op_sel_hi:[1,1]
	v_pk_fma_f32 v[22:23], v[22:23], v[194:195], v[18:19] op_sel:[0,0,1] op_sel_hi:[1,0,0] neg_hi:[0,0,1]
	s_waitcnt lgkmcnt(2)
	v_pk_mul_f32 v[18:19], v[26:27], v[190:191] op_sel:[0,1] op_sel_hi:[1,1]
	v_pk_fma_f32 v[12:13], v[24:25], v[188:189], v[12:13] op_sel:[0,0,1] op_sel_hi:[1,0,0] neg_hi:[0,0,1]
	s_waitcnt lgkmcnt(1)
	v_pk_mul_f32 v[24:25], v[28:29], v[186:187] op_sel:[0,1] op_sel_hi:[1,1]
	v_pk_fma_f32 v[18:19], v[26:27], v[190:191], v[18:19] op_sel:[0,0,1] op_sel_hi:[1,0,0] neg_hi:[0,0,1]
	v_pk_fma_f32 v[28:29], v[28:29], v[186:187], v[24:25] op_sel:[0,0,1] op_sel_hi:[1,0,0] neg_hi:[0,0,1]
	s_waitcnt lgkmcnt(0)
	v_pk_add_f32 v[24:25], v[30:31], v[14:15]
	v_pk_add_f32 v[26:27], v[32:33], v[16:17]
	v_pk_add_f32 v[36:37], v[2:3], v[10:11]
	v_pk_add_f32 v[38:39], v[4:5], v[20:21]
	v_pk_add_f32 v[14:15], v[30:31], v[14:15] neg_lo:[0,1] neg_hi:[0,1]
	v_pk_add_f32 v[32:33], v[32:33], v[16:17] neg_lo:[0,1] neg_hi:[0,1]
	v_pk_add_f32 v[10:11], v[2:3], v[10:11] neg_lo:[0,1] neg_hi:[0,1]
	v_pk_add_f32 v[20:21], v[4:5], v[20:21] neg_lo:[0,1] neg_hi:[0,1]
	v_pk_add_f32 v[4:5], v[34:35], v[22:23]
	v_pk_add_f32 v[2:3], v[8:9], v[12:13]
	v_pk_add_f32 v[16:17], v[6:7], v[18:19]
	v_pk_add_f32 v[30:31], v[0:1], v[28:29]
	v_pk_add_f32 v[22:23], v[34:35], v[22:23] neg_lo:[0,1] neg_hi:[0,1]
	v_pk_add_f32 v[8:9], v[8:9], v[12:13] neg_lo:[0,1] neg_hi:[0,1]
	v_pk_add_f32 v[18:19], v[6:7], v[18:19] neg_lo:[0,1] neg_hi:[0,1]
	v_pk_add_f32 v[28:29], v[0:1], v[28:29] neg_lo:[0,1] neg_hi:[0,1]
	v_pk_add_f32 v[0:1], v[24:25], v[4:5]
	v_pk_add_f32 v[6:7], v[26:27], v[2:3]
	v_pk_add_f32 v[12:13], v[36:37], v[16:17]
	v_pk_add_f32 v[34:35], v[38:39], v[30:31]
	v_pk_add_f32 v[24:25], v[24:25], v[4:5] neg_lo:[0,1] neg_hi:[0,1]
	v_pk_add_f32 v[2:3], v[26:27], v[2:3] neg_lo:[0,1] neg_hi:[0,1]
	v_pk_add_f32 v[36:37], v[36:37], v[16:17] neg_lo:[0,1] neg_hi:[0,1]
	v_pk_add_f32 v[30:31], v[38:39], v[30:31] neg_lo:[0,1] neg_hi:[0,1]
	v_pk_add_f32 v[38:39], v[14:15], v[22:23] op_sel:[0,1] op_sel_hi:[1,0] neg_lo:[0,1]
	v_pk_add_f32 v[16:17], v[32:33], v[8:9] op_sel:[0,1] op_sel_hi:[1,0] neg_lo:[0,1]
	v_pk_add_f32 v[26:27], v[10:11], v[18:19] op_sel:[0,1] op_sel_hi:[1,0] neg_lo:[0,1]
	v_pk_add_f32 v[4:5], v[20:21], v[28:29] op_sel:[0,1] op_sel_hi:[1,0] neg_lo:[0,1]
	v_pk_add_f32 v[14:15], v[14:15], v[22:23] op_sel:[0,1] op_sel_hi:[1,0] neg_hi:[0,1]
	v_pk_add_f32 v[8:9], v[32:33], v[8:9] op_sel:[0,1] op_sel_hi:[1,0] neg_hi:[0,1]
	v_pk_add_f32 v[10:11], v[10:11], v[18:19] op_sel:[0,1] op_sel_hi:[1,0] neg_hi:[0,1]
; #define LAS __attribute__((address_space(3)))
; __device__ __forceinline__ f32x2 cmul(f32x2 a, f32x2 b) { return (f32x2){a.x * b.x - a.y * b.y, a.x * b.y + a.y * b.x}; }
; template <bool INV> __device__ __forceinline__ void dft16(f32x2 (&x)[16]) {
; #pragma unroll
;     for (int b = 0; b < 4; ++b) r4<INV>(x[b], x[4 + b], x[8 + b], x[12 + b]);
;     const float sg = INV ? -1.f : 1.f;
;     const f32x2 W1 = {0.92387953251f, -0.38268343236f * sg}, W2 = {0.70710678118f, -0.70710678118f * sg}, W3 = {0.38268343236f, -0.92387953251f * sg},
;                 W4 = {0.f, -1.f * sg}, W6 = {-0.70710678118f, -0.70710678118f * sg}, W9 = {-0.92387953251f, 0.38268343236f * sg};
;     x[5] = cmul(x[5], W1); x[9] = cmul(x[9], W2); x[13] = cmul(x[13], W3);
;     x[6] = cmul(x[6], W2); x[10] = cmul(x[10], W4); x[14] = cmul(x[14], W6);
;     x[7] = cmul(x[7], W3); x[11] = cmul(x[11], W6); x[15] = cmul(x[15], W9);
; #pragma unroll
;     for (int c = 0; c < 4; ++c) r4<INV>(x[4 * c], x[4 * c + 1], x[4 * c + 2], x[4 * c + 3]);
; }
; template <bool INV> __device__ __forceinline__ void pass16_s4(LAS f32x2* X, const LAS f32x2* TH, const LAS f32x2* TL, int tid) {
; #pragma unroll 1
;     for (int s = 0; s < 2; ++s) {
;         const int b = tid + NTHR * s, blk = b >> 2, jj = b & 3;
;         LAS f32x2* P = X + blk * 68 + jj;
;         f32x2 x[16];
; #pragma unroll
;         for (int q = 0; q < 16; ++q) x[q] = P[4 * q];
;         bfly16_tab<INV>(x, TH - 1024, 4, jj);
; #pragma unroll
;         for (int c = 0; c < 4; ++c)
; #pragma unroll
;             for (int d = 0; d < 4; ++d) P[4 * (c + 4 * d)] = x[4 * c + d];
;     }
; }
	v_pk_add_f32 v[20:21], v[20:21], v[28:29] op_sel:[0,1] op_sel_hi:[1,0] neg_hi:[0,1]
	v_pk_mul_f32 v[28:29], v[16:17], s[82:83] op_sel_hi:[1,0]
	v_pk_mul_f32 v[18:19], v[2:3], s[76:77] op_sel_hi:[1,0]
	v_pk_mul_f32 v[32:33], v[8:9], s[44:45] op_sel_hi:[1,0]
	v_pk_mul_f32 v[22:23], v[26:27], s[76:77] op_sel_hi:[1,0]
	v_pk_mul_f32 v[40:41], v[10:11], s[76:77] op_sel_hi:[1,0]
	v_pk_mul_f32 v[42:43], v[4:5], s[44:45] op_sel_hi:[1,0]
	v_pk_mul_f32 v[44:45], v[30:31], s[76:77] op_sel_hi:[1,0]
	v_pk_mul_f32 v[46:47], v[20:21], s[70:71] op_sel_hi:[1,0]
	v_pk_fma_f32 v[16:17], v[16:17], s[44:45], v[28:29] op_sel:[0,0,1] op_sel_hi:[1,0,0] neg_lo:[0,0,1]
	v_pk_fma_f32 v[2:3], v[2:3], s[76:77], v[18:19] op_sel:[0,0,1] op_sel_hi:[1,0,0] neg_lo:[0,0,1]
	v_pk_fma_f32 v[8:9], v[8:9], s[82:83], v[32:33] op_sel:[0,0,1] op_sel_hi:[1,0,0] neg_lo:[0,0,1]
	v_pk_fma_f32 v[26:27], v[26:27], s[76:77], v[22:23] op_sel:[0,0,1] op_sel_hi:[1,0,0] neg_lo:[0,0,1]
	v_pk_fma_f32 v[40:41], v[10:11], s[72:73], v[40:41] op_sel:[0,0,1] op_sel_hi:[1,0,0] neg_lo:[0,0,1]
	v_pk_fma_f32 v[4:5], v[4:5], s[82:83], v[42:43] op_sel:[0,0,1] op_sel_hi:[1,0,0] neg_lo:[0,0,1]
	v_pk_fma_f32 v[44:45], v[30:31], s[72:73], v[44:45] op_sel:[0,0,1] op_sel_hi:[1,0,0] neg_lo:[0,0,1]
	v_pk_fma_f32 v[20:21], v[20:21], s[64:65], v[46:47] op_sel:[0,0,1] op_sel_hi:[1,0,0] neg_lo:[0,0,1]
	v_pk_add_f32 v[46:47], v[0:1], v[12:13]
	v_pk_add_f32 v[30:31], v[38:39], v[26:27]
	v_pk_add_f32 v[42:43], v[24:25], v[36:37] op_sel:[0,1] op_sel_hi:[1,0] neg_lo:[0,1]
	v_pk_add_f32 v[10:11], v[14:15], v[40:41]
	v_pk_add_f32 v[0:1], v[0:1], v[12:13] neg_lo:[0,1] neg_hi:[0,1]
	v_pk_add_f32 v[26:27], v[38:39], v[26:27] neg_lo:[0,1] neg_hi:[0,1]
	v_pk_add_f32 v[36:37], v[24:25], v[36:37] op_sel:[0,1] op_sel_hi:[1,0] neg_hi:[0,1]
	v_pk_add_f32 v[40:41], v[14:15], v[40:41] neg_lo:[0,1] neg_hi:[0,1]
	v_pk_add_f32 v[14:15], v[6:7], v[34:35]
	v_pk_add_f32 v[24:25], v[16:17], v[4:5]
	v_pk_add_f32 v[38:39], v[2:3], v[44:45]
	v_pk_add_f32 v[12:13], v[8:9], v[20:21]
	v_pk_add_f32 v[6:7], v[6:7], v[34:35] neg_lo:[0,1] neg_hi:[0,1]
	v_pk_add_f32 v[16:17], v[16:17], v[4:5] neg_lo:[0,1] neg_hi:[0,1]
	v_pk_add_f32 v[2:3], v[2:3], v[44:45] neg_lo:[0,1] neg_hi:[0,1]
	v_pk_add_f32 v[8:9], v[8:9], v[20:21] neg_lo:[0,1] neg_hi:[0,1]
	v_pk_add_f32 v[20:21], v[46:47], v[14:15]
	v_pk_add_f32 v[44:45], v[30:31], v[24:25]
	v_pk_add_f32 v[4:5], v[42:43], v[38:39]
	v_pk_add_f32 v[34:35], v[10:11], v[12:13]
	v_pk_add_f32 v[46:47], v[46:47], v[14:15] neg_lo:[0,1] neg_hi:[0,1]
	v_pk_add_f32 v[30:31], v[30:31], v[24:25] neg_lo:[0,1] neg_hi:[0,1]
	v_pk_add_f32 v[38:39], v[42:43], v[38:39] neg_lo:[0,1] neg_hi:[0,1]
	v_pk_add_f32 v[12:13], v[10:11], v[12:13] neg_lo:[0,1] neg_hi:[0,1]
	v_pk_add_f32 v[10:11], v[0:1], v[6:7] op_sel:[0,1] op_sel_hi:[1,0] neg_lo:[0,1]
	v_pk_add_f32 v[42:43], v[26:27], v[16:17] op_sel:[0,1] op_sel_hi:[1,0] neg_lo:[0,1]
	v_pk_add_f32 v[24:25], v[36:37], v[2:3] op_sel:[0,1] op_sel_hi:[1,0] neg_lo:[0,1]
	v_pk_add_f32 v[14:15], v[40:41], v[8:9] op_sel:[0,1] op_sel_hi:[1,0] neg_lo:[0,1]
	v_pk_add_f32 v[6:7], v[0:1], v[6:7] op_sel:[0,1] op_sel_hi:[1,0] neg_hi:[0,1]
	v_pk_add_f32 v[16:17], v[26:27], v[16:17] op_sel:[0,1] op_sel_hi:[1,0] neg_hi:[0,1]
	v_pk_add_f32 v[2:3], v[36:37], v[2:3] op_sel:[0,1] op_sel_hi:[1,0] neg_hi:[0,1]
	v_pk_add_f32 v[8:9], v[40:41], v[8:9] op_sel:[0,1] op_sel_hi:[1,0] neg_hi:[0,1]
	ds_write_b64 v151, v[20:21] offset:0
	ds_write_b64 v151, v[44:45] offset:32
	ds_write_b64 v151, v[4:5] offset:64
	ds_write_b64 v151, v[34:35] offset:96
	ds_write_b64 v151, v[10:11] offset:128
	ds_write_b64 v151, v[42:43] offset:160
	ds_write_b64 v151, v[24:25] offset:192
	ds_write_b64 v151, v[14:15] offset:224
	ds_write_b64 v151, v[46:47] offset:256
	ds_write_b64 v151, v[30:31] offset:288
	ds_write_b64 v151, v[38:39] offset:320
	ds_write_b64 v151, v[12:13] offset:352
	ds_write_b64 v151, v[6:7] offset:384
	ds_write_b64 v151, v[16:17] offset:416
	ds_write_b64 v151, v[2:3] offset:448
	ds_write_b64 v151, v[8:9] offset:480
	s_cbranch_scc1 .LBB0_852
	s_waitcnt lgkmcnt(0)
	s_barrier
	s_mov_b32 s0, 0
	s_mov_b64 s[12:13], -1
	ds_read2st64_b64 v[232:235], v139 offset0:1 offset1:2
	ds_read2st64_b64 v[208:211], v139 offset0:3 offset1:4
	ds_read2st64_b64 v[204:207], v139 offset0:5 offset1:6
	ds_read2st64_b64 v[200:203], v139 offset0:7 offset1:8
	ds_read2st64_b64 v[196:199], v139 offset0:9 offset1:10
	ds_read2st64_b64 v[192:195], v139 offset0:11 offset1:12
	ds_read2st64_b64 v[188:191], v139 offset0:13 offset1:14
	ds_read_b64 v[186:187], v139 offset:7680
; #define LAS __attribute__((address_space(3)))
; __device__ __forceinline__ f32x2 cmul(f32x2 a, f32x2 b) { return (f32x2){a.x * b.x - a.y * b.y, a.x * b.y + a.y * b.x}; }
; template <bool INV> __device__ __forceinline__ void bfly16_tab(f32x2 (&x)[16], const LAS f32x2* T, int tstride, int j) {
;     if (INV) {
; #pragma unroll
;         for (int q = 1; q < 16; ++q) { f32x2 p = T[q * tstride + j]; p.y = -p.y; x[q] = cmul(x[q], p); } }
;     dft16<INV>(x);
;     if (!INV) {
; #pragma unroll
;         for (int r = 1; r < 16; ++r) { const f32x2 p = T[r * tstride + j]; x[4 * (r & 3) + (r >> 2)] = cmul(x[4 * (r & 3) + (r >> 2)], p); } }
; }
; template <bool INV> __device__ __forceinline__ void pass16_s64(LAS f32x2* X, const LAS f32x2* TH, int base, int j) {
;     f32x2 x[16];
; #pragma unroll
;     for (int q = 0; q < 16; ++q) x[q] = X[base + q * 68];
;     bfly16_tab<INV>(x, TH - 2048, 64, j);
; #pragma unroll
;     for (int c = 0; c < 4; ++c)
; #pragma unroll
;         for (int d = 0; d < 4; ++d) X[base + (c + 4 * d) * 68] = x[4 * c + d];
; }
.LBB0_854:
	v_add_u32_e32 v128, s0, v140
	v_lshrrev_b32_e32 v147, 6, v128
	v_mad_u32_u24 v151, v147, s77, v142
	ds_read_b64 v[0:1], v151 offset:544
	ds_read_b64 v[2:3], v151 offset:1088
	ds_read_b64 v[4:5], v151 offset:1632
	ds_read_b64 v[6:7], v151 offset:2176
	ds_read_b64 v[8:9], v151 offset:2720
	ds_read_b64 v[10:11], v151 offset:3264
	ds_read_b64 v[12:13], v151 offset:3808
	ds_read_b64 v[14:15], v151 offset:4352
	ds_read_b64 v[16:17], v151 offset:4896
	ds_read_b64 v[18:19], v151 offset:5440
	ds_read_b64 v[20:21], v151 offset:5984
	ds_read_b64 v[22:23], v151 offset:6528
	ds_read_b64 v[24:25], v151 offset:7072
	ds_read_b64 v[26:27], v151 offset:7616
	ds_read_b64 v[28:29], v151 offset:8160
	ds_read_b64 v[30:31], v151 offset:0
	s_cmp_eq_u32 s0, 0
	s_movk_i32 s0, 0x200
	s_mov_b64 s[12:13], 0
	s_waitcnt lgkmcnt(15)
	v_pk_mul_f32 v[32:33], v[0:1], v[232:233] op_sel:[0,1] op_sel_hi:[1,1]
	s_waitcnt lgkmcnt(14)
	v_pk_mul_f32 v[34:35], v[2:3], v[234:235] op_sel:[0,1] op_sel_hi:[1,1]
	v_pk_fma_f32 v[0:1], v[0:1], v[232:233], v[32:33] op_sel:[0,0,1] op_sel_hi:[1,0,0] neg_hi:[0,0,1]
	s_waitcnt lgkmcnt(13)
	v_pk_mul_f32 v[32:33], v[4:5], v[208:209] op_sel:[0,1] op_sel_hi:[1,1]
	v_pk_fma_f32 v[2:3], v[2:3], v[234:235], v[34:35] op_sel:[0,0,1] op_sel_hi:[1,0,0] neg_hi:[0,0,1]
	s_waitcnt lgkmcnt(12)
	v_pk_mul_f32 v[34:35], v[6:7], v[210:211] op_sel:[0,1] op_sel_hi:[1,1]
	v_pk_fma_f32 v[32:33], v[4:5], v[208:209], v[32:33] op_sel:[0,0,1] op_sel_hi:[1,0,0] neg_hi:[0,0,1]
	s_waitcnt lgkmcnt(11)
	v_pk_mul_f32 v[4:5], v[8:9], v[204:205] op_sel:[0,1] op_sel_hi:[1,1]
	v_pk_fma_f32 v[34:35], v[6:7], v[210:211], v[34:35] op_sel:[0,0,1] op_sel_hi:[1,0,0] neg_hi:[0,0,1]
	s_waitcnt lgkmcnt(10)
	v_pk_mul_f32 v[6:7], v[10:11], v[206:207] op_sel:[0,1] op_sel_hi:[1,1]
	v_pk_fma_f32 v[8:9], v[8:9], v[204:205], v[4:5] op_sel:[0,0,1] op_sel_hi:[1,0,0] neg_hi:[0,0,1]
	s_waitcnt lgkmcnt(9)
	v_pk_mul_f32 v[4:5], v[12:13], v[200:201] op_sel:[0,1] op_sel_hi:[1,1]
	v_pk_fma_f32 v[10:11], v[10:11], v[206:207], v[6:7] op_sel:[0,0,1] op_sel_hi:[1,0,0] neg_hi:[0,0,1]
	s_waitcnt lgkmcnt(8)
	v_pk_mul_f32 v[6:7], v[14:15], v[202:203] op_sel:[0,1] op_sel_hi:[1,1]
	v_pk_fma_f32 v[4:5], v[12:13], v[200:201], v[4:5] op_sel:[0,0,1] op_sel_hi:[1,0,0] neg_hi:[0,0,1]
	s_waitcnt lgkmcnt(7)
	v_pk_mul_f32 v[12:13], v[16:17], v[196:197] op_sel:[0,1] op_sel_hi:[1,1]
	v_pk_fma_f32 v[14:15], v[14:15], v[202:203], v[6:7] op_sel:[0,0,1] op_sel_hi:[1,0,0] neg_hi:[0,0,1]
	s_waitcnt lgkmcnt(6)
	v_pk_mul_f32 v[6:7], v[18:19], v[198:199] op_sel:[0,1] op_sel_hi:[1,1]
	v_pk_fma_f32 v[16:17], v[16:17], v[196:197], v[12:13] op_sel:[0,0,1] op_sel_hi:[1,0,0] neg_hi:[0,0,1]
	s_waitcnt lgkmcnt(5)
	v_pk_mul_f32 v[12:13], v[20:21], v[192:193] op_sel:[0,1] op_sel_hi:[1,1]
	v_pk_fma_f32 v[6:7], v[18:19], v[198:199], v[6:7] op_sel:[0,0,1] op_sel_hi:[1,0,0] neg_hi:[0,0,1]
	s_waitcnt lgkmcnt(4)
	v_pk_mul_f32 v[18:19], v[22:23], v[194:195] op_sel:[0,1] op_sel_hi:[1,1]
	v_pk_fma_f32 v[20:21], v[20:21], v[192:193], v[12:13] op_sel:[0,0,1] op_sel_hi:[1,0,0] neg_hi:[0,0,1]
	s_waitcnt lgkmcnt(3)
	v_pk_mul_f32 v[12:13], v[24:25], v[188:189] op_sel:[0,1] op_sel_hi:[1,1]
	v_pk_fma_f32 v[18:19], v[22:23], v[194:195], v[18:19] op_sel:[0,0,1] op_sel_hi:[1,0,0] neg_hi:[0,0,1]
	s_waitcnt lgkmcnt(2)
	v_pk_mul_f32 v[22:23], v[26:27], v[190:191] op_sel:[0,1] op_sel_hi:[1,1]
	v_pk_fma_f32 v[12:13], v[24:25], v[188:189], v[12:13] op_sel:[0,0,1] op_sel_hi:[1,0,0] neg_hi:[0,0,1]
	s_waitcnt lgkmcnt(1)
	v_pk_mul_f32 v[24:25], v[28:29], v[186:187] op_sel:[0,1] op_sel_hi:[1,1]
	v_pk_fma_f32 v[26:27], v[26:27], v[190:191], v[22:23] op_sel:[0,0,1] op_sel_hi:[1,0,0] neg_hi:[0,0,1]
	v_pk_fma_f32 v[24:25], v[28:29], v[186:187], v[24:25] op_sel:[0,0,1] op_sel_hi:[1,0,0] neg_hi:[0,0,1]
	s_waitcnt lgkmcnt(0)
	v_pk_add_f32 v[28:29], v[30:31], v[14:15]
	v_pk_add_f32 v[22:23], v[0:1], v[16:17]
	v_pk_add_f32 v[36:37], v[2:3], v[6:7]
	v_pk_add_f32 v[38:39], v[32:33], v[20:21]
	v_pk_add_f32 v[30:31], v[30:31], v[14:15] neg_lo:[0,1] neg_hi:[0,1]
	v_pk_add_f32 v[16:17], v[0:1], v[16:17] neg_lo:[0,1] neg_hi:[0,1]
	v_pk_add_f32 v[6:7], v[2:3], v[6:7] neg_lo:[0,1] neg_hi:[0,1]
	v_pk_add_f32 v[20:21], v[32:33], v[20:21] neg_lo:[0,1] neg_hi:[0,1]
	v_pk_add_f32 v[32:33], v[34:35], v[18:19]
	v_pk_add_f32 v[2:3], v[8:9], v[12:13]
	v_pk_add_f32 v[0:1], v[10:11], v[26:27]
	v_pk_add_f32 v[14:15], v[4:5], v[24:25]
	v_pk_add_f32 v[34:35], v[34:35], v[18:19] neg_lo:[0,1] neg_hi:[0,1]
	v_pk_add_f32 v[12:13], v[8:9], v[12:13] neg_lo:[0,1] neg_hi:[0,1]
	v_pk_add_f32 v[10:11], v[10:11], v[26:27] neg_lo:[0,1] neg_hi:[0,1]
	v_pk_add_f32 v[24:25], v[4:5], v[24:25] neg_lo:[0,1] neg_hi:[0,1]
	v_pk_add_f32 v[4:5], v[28:29], v[32:33]
	v_pk_add_f32 v[26:27], v[22:23], v[2:3]
	v_pk_add_f32 v[8:9], v[36:37], v[0:1]
	v_pk_add_f32 v[18:19], v[38:39], v[14:15]
	v_pk_add_f32 v[32:33], v[28:29], v[32:33] neg_lo:[0,1] neg_hi:[0,1]
	v_pk_add_f32 v[22:23], v[22:23], v[2:3] neg_lo:[0,1] neg_hi:[0,1]
	v_pk_add_f32 v[0:1], v[36:37], v[0:1] neg_lo:[0,1] neg_hi:[0,1]
	v_pk_add_f32 v[14:15], v[38:39], v[14:15] neg_lo:[0,1] neg_hi:[0,1]
	v_pk_add_f32 v[38:39], v[30:31], v[34:35] op_sel:[0,1] op_sel_hi:[1,0] neg_lo:[0,1]
	v_pk_add_f32 v[36:37], v[16:17], v[12:13] op_sel:[0,1] op_sel_hi:[1,0] neg_lo:[0,1]
	v_pk_add_f32 v[2:3], v[6:7], v[10:11] op_sel:[0,1] op_sel_hi:[1,0] neg_lo:[0,1]
	v_pk_add_f32 v[28:29], v[20:21], v[24:25] op_sel:[0,1] op_sel_hi:[1,0] neg_lo:[0,1]
	v_pk_add_f32 v[30:31], v[30:31], v[34:35] op_sel:[0,1] op_sel_hi:[1,0] neg_hi:[0,1]
	v_pk_add_f32 v[16:17], v[16:17], v[12:13] op_sel:[0,1] op_sel_hi:[1,0] neg_hi:[0,1]
	v_pk_add_f32 v[6:7], v[6:7], v[10:11] op_sel:[0,1] op_sel_hi:[1,0] neg_hi:[0,1]
; #define LAS __attribute__((address_space(3)))
; __device__ __forceinline__ f32x2 cmul(f32x2 a, f32x2 b) { return (f32x2){a.x * b.x - a.y * b.y, a.x * b.y + a.y * b.x}; }
; template <bool INV> __device__ __forceinline__ void bfly16_tab(f32x2 (&x)[16], const LAS f32x2* T, int tstride, int j) {
;     if (INV) {
; #pragma unroll
;         for (int q = 1; q < 16; ++q) { f32x2 p = T[q * tstride + j]; p.y = -p.y; x[q] = cmul(x[q], p); } }
;     dft16<INV>(x);
;     if (!INV) {
; #pragma unroll
;         for (int r = 1; r < 16; ++r) { const f32x2 p = T[r * tstride + j]; x[4 * (r & 3) + (r >> 2)] = cmul(x[4 * (r & 3) + (r >> 2)], p); } }
; }
; template <bool INV> __device__ __forceinline__ void pass16_s64(LAS f32x2* X, const LAS f32x2* TH, int base, int j) {
;     f32x2 x[16];
; #pragma unroll
;     for (int q = 0; q < 16; ++q) x[q] = X[base + q * 68];
;     bfly16_tab<INV>(x, TH - 2048, 64, j);
; #pragma unroll
;     for (int c = 0; c < 4; ++c)
; #pragma unroll
;         for (int d = 0; d < 4; ++d) X[base + (c + 4 * d) * 68] = x[4 * c + d];
; }
; template <bool INV> __device__ __forceinline__ void pass16(LAS f32x2* X, const LAS f32x2* TH, const LAS f32x2* TL, int base, int stride, int tw) {
;     f32x2 x[16];
; #pragma unroll
;     for (int q = 0; q < 16; ++q) x[q] = X[base + q * stride];
;     bfly16<INV>(x, TH, TL, tw);
; #pragma unroll
;     for (int c = 0; c < 4; ++c)
; #pragma unroll
;         for (int d = 0; d < 4; ++d) X[base + (c + 4 * d) * stride] = x[4 * c + d];
; }
	v_pk_add_f32 v[24:25], v[20:21], v[24:25] op_sel:[0,1] op_sel_hi:[1,0] neg_hi:[0,1]
	v_pk_mul_f32 v[20:21], v[36:37], s[82:83] op_sel_hi:[1,0]
	v_pk_mul_f32 v[10:11], v[22:23], s[76:77] op_sel_hi:[1,0]
	v_pk_mul_f32 v[12:13], v[16:17], s[44:45] op_sel_hi:[1,0]
	v_pk_mul_f32 v[34:35], v[2:3], s[76:77] op_sel_hi:[1,0]
	v_pk_mul_f32 v[40:41], v[6:7], s[76:77] op_sel_hi:[1,0]
	v_pk_mul_f32 v[42:43], v[28:29], s[44:45] op_sel_hi:[1,0]
	v_pk_mul_f32 v[44:45], v[14:15], s[76:77] op_sel_hi:[1,0]
	v_pk_mul_f32 v[46:47], v[24:25], s[70:71] op_sel_hi:[1,0]
	v_pk_fma_f32 v[36:37], v[36:37], s[44:45], v[20:21] op_sel:[0,0,1] op_sel_hi:[1,0,0] neg_lo:[0,0,1]
	v_pk_fma_f32 v[22:23], v[22:23], s[76:77], v[10:11] op_sel:[0,0,1] op_sel_hi:[1,0,0] neg_lo:[0,0,1]
	v_pk_fma_f32 v[12:13], v[16:17], s[82:83], v[12:13] op_sel:[0,0,1] op_sel_hi:[1,0,0] neg_lo:[0,0,1]
	v_pk_fma_f32 v[2:3], v[2:3], s[76:77], v[34:35] op_sel:[0,0,1] op_sel_hi:[1,0,0] neg_lo:[0,0,1]
	v_pk_fma_f32 v[6:7], v[6:7], s[72:73], v[40:41] op_sel:[0,0,1] op_sel_hi:[1,0,0] neg_lo:[0,0,1]
	v_pk_fma_f32 v[28:29], v[28:29], s[82:83], v[42:43] op_sel:[0,0,1] op_sel_hi:[1,0,0] neg_lo:[0,0,1]
	v_pk_fma_f32 v[44:45], v[14:15], s[72:73], v[44:45] op_sel:[0,0,1] op_sel_hi:[1,0,0] neg_lo:[0,0,1]
	v_pk_fma_f32 v[46:47], v[24:25], s[64:65], v[46:47] op_sel:[0,0,1] op_sel_hi:[1,0,0] neg_lo:[0,0,1]
	v_pk_add_f32 v[24:25], v[4:5], v[8:9]
	v_pk_add_f32 v[14:15], v[38:39], v[2:3]
	v_pk_add_f32 v[42:43], v[32:33], v[0:1] op_sel:[0,1] op_sel_hi:[1,0] neg_lo:[0,1]
	v_pk_add_f32 v[40:41], v[30:31], v[6:7]
	v_pk_add_f32 v[8:9], v[4:5], v[8:9] neg_lo:[0,1] neg_hi:[0,1]
	v_pk_add_f32 v[2:3], v[38:39], v[2:3] neg_lo:[0,1] neg_hi:[0,1]
	v_pk_add_f32 v[32:33], v[32:33], v[0:1] op_sel:[0,1] op_sel_hi:[1,0] neg_hi:[0,1]
	v_pk_add_f32 v[6:7], v[30:31], v[6:7] neg_lo:[0,1] neg_hi:[0,1]
	v_pk_add_f32 v[30:31], v[26:27], v[18:19]
	v_pk_add_f32 v[0:1], v[36:37], v[28:29]
	v_pk_add_f32 v[38:39], v[22:23], v[44:45]
	v_pk_add_f32 v[4:5], v[12:13], v[46:47]
	v_pk_add_f32 v[26:27], v[26:27], v[18:19] neg_lo:[0,1] neg_hi:[0,1]
	v_pk_add_f32 v[36:37], v[36:37], v[28:29] neg_lo:[0,1] neg_hi:[0,1]
	v_pk_add_f32 v[44:45], v[22:23], v[44:45] neg_lo:[0,1] neg_hi:[0,1]
	v_pk_add_f32 v[12:13], v[12:13], v[46:47] neg_lo:[0,1] neg_hi:[0,1]
	v_pk_add_f32 v[46:47], v[24:25], v[30:31]
	v_pk_add_f32 v[22:23], v[14:15], v[0:1]
	v_pk_add_f32 v[28:29], v[42:43], v[38:39]
	v_pk_add_f32 v[18:19], v[40:41], v[4:5]
	v_pk_add_f32 v[24:25], v[24:25], v[30:31] neg_lo:[0,1] neg_hi:[0,1]
	v_pk_add_f32 v[14:15], v[14:15], v[0:1] neg_lo:[0,1] neg_hi:[0,1]
	v_pk_add_f32 v[42:43], v[42:43], v[38:39] neg_lo:[0,1] neg_hi:[0,1]
	v_pk_add_f32 v[40:41], v[40:41], v[4:5] neg_lo:[0,1] neg_hi:[0,1]
	v_pk_add_f32 v[4:5], v[8:9], v[26:27] op_sel:[0,1] op_sel_hi:[1,0] neg_lo:[0,1]
	v_pk_add_f32 v[38:39], v[2:3], v[36:37] op_sel:[0,1] op_sel_hi:[1,0] neg_lo:[0,1]
	v_pk_add_f32 v[0:1], v[32:33], v[44:45] op_sel:[0,1] op_sel_hi:[1,0] neg_lo:[0,1]
	v_pk_add_f32 v[30:31], v[6:7], v[12:13] op_sel:[0,1] op_sel_hi:[1,0] neg_lo:[0,1]
	v_pk_add_f32 v[26:27], v[8:9], v[26:27] op_sel:[0,1] op_sel_hi:[1,0] neg_hi:[0,1]
	v_pk_add_f32 v[36:37], v[2:3], v[36:37] op_sel:[0,1] op_sel_hi:[1,0] neg_hi:[0,1]
	v_pk_add_f32 v[32:33], v[32:33], v[44:45] op_sel:[0,1] op_sel_hi:[1,0] neg_hi:[0,1]
	v_pk_add_f32 v[6:7], v[6:7], v[12:13] op_sel:[0,1] op_sel_hi:[1,0] neg_hi:[0,1]
	ds_write_b64 v151, v[46:47] offset:0
	ds_write_b64 v151, v[22:23] offset:544
	ds_write_b64 v151, v[28:29] offset:1088
	ds_write_b64 v151, v[18:19] offset:1632
	ds_write_b64 v151, v[4:5] offset:2176
	ds_write_b64 v151, v[38:39] offset:2720
	ds_write_b64 v151, v[0:1] offset:3264
	ds_write_b64 v151, v[30:31] offset:3808
	ds_write_b64 v151, v[24:25] offset:4352
	ds_write_b64 v151, v[14:15] offset:4896
	ds_write_b64 v151, v[42:43] offset:5440
	ds_write_b64 v151, v[40:41] offset:5984
	ds_write_b64 v151, v[26:27] offset:6528
	ds_write_b64 v151, v[36:37] offset:7072
	ds_write_b64 v151, v[32:33] offset:7616
	ds_write_b64 v151, v[6:7] offset:8160
	s_cbranch_scc1 .LBB0_854
	s_waitcnt lgkmcnt(0)
	s_barrier
	s_mov_b32 s0, 0
	s_mov_b64 s[12:13], -1
.LBB0_856:
	v_add_u32_e32 v128, s0, v140
	v_lshrrev_b32_e32 v147, 6, v128
	v_and_b32_e32 v157, 63, v128
	v_lshlrev_b32_e32 v151, 5, v147
	v_lshlrev_b32_e32 v155, 3, v147
	v_lshlrev_b32_e32 v157, 4, v157
	v_lshl_add_u32 v151, v128, 3, v151
	v_add_u32_e32 v155, 0x26000, v155
	v_add_u32_e32 v157, 0x26400, v157
	v_add_u32_e32 v176, 0x11000, v151
	ds_read_b64 v[0:1], v155
	ds_read_b64 v[2:3], v157
	ds_read_b64 v[4:5], v151 offset:8704
	ds_read_b64 v[6:7], v151 offset:17408
	ds_read_b64 v[8:9], v151 offset:26112
	ds_read_b64 v[10:11], v151 offset:34816
	ds_read_b64 v[12:13], v151 offset:43520
	ds_read_b64 v[14:15], v151 offset:52224
	ds_read_b64 v[16:17], v151 offset:60928
	ds_read_b64 v[18:19], v176 offset:0
	ds_read_b64 v[20:21], v176 offset:8704
	ds_read_b64 v[22:23], v176 offset:17408
	ds_read_b64 v[24:25], v176 offset:26112
	ds_read_b64 v[26:27], v176 offset:34816
	ds_read_b64 v[28:29], v176 offset:43520
	ds_read_b64 v[30:31], v176 offset:52224
	ds_read_b64 v[32:33], v176 offset:60928
	ds_read_b64 v[34:35], v151 offset:0
	s_cmp_eq_u32 s0, 0
	s_movk_i32 s0, 0x200
	s_mov_b64 s[12:13], 0
	s_waitcnt lgkmcnt(15)
; #define LAS __attribute__((address_space(3)))
; __device__ __forceinline__ f32x2 cmul(f32x2 a, f32x2 b) { return (f32x2){a.x * b.x - a.y * b.y, a.x * b.y + a.y * b.x}; }
; __device__ __forceinline__ f32x2 tw32k(const LAS f32x2* TH, const LAS f32x2* TL, int n) { return cmul(TH[n >> 7], TL[n & 127]); }
; template <bool INV> __device__ __forceinline__ void bfly16(f32x2 (&x)[16], const LAS f32x2* TH, const LAS f32x2* TL, int tw) {
;     f32x2 W = tw32k(TH, TL, tw); if (INV) W.y = -W.y;
;     if (INV) { f32x2 p = W;
; #pragma unroll
;         for (int q = 1; q < 16; ++q) { x[q] = cmul(x[q], p); if (q < 15) p = cmul(p, W); } }
;     dft16<INV>(x);
; template <bool INV> __device__ __forceinline__ void pass16(LAS f32x2* X, const LAS f32x2* TH, const LAS f32x2* TL, int base, int stride, int tw) {
;     f32x2 x[16];
; #pragma unroll
;     for (int q = 0; q < 16; ++q) x[q] = X[base + q * stride];
;     bfly16<INV>(x, TH, TL, tw);
	v_pk_mul_f32 v[36:37], v[0:1], v[2:3] op_sel:[0,1] op_sel_hi:[1,1]
	s_nop 0
	v_pk_fma_f32 v[36:37], v[0:1], v[2:3], v[36:37] op_sel:[0,0,1] op_sel_hi:[1,0,0] neg_lo:[0,0,1]
	s_nop 0
	v_pk_mul_f32 v[0:1], v[36:37], v[36:37] op_sel:[0,1] op_sel_hi:[1,1]
	s_nop 0
	v_pk_fma_f32 v[0:1], v[36:37], v[36:37], v[0:1] op_sel:[0,0,1] op_sel_hi:[1,0,0] neg_lo:[0,0,1]
	s_nop 0
	v_pk_mul_f32 v[2:3], v[0:1], v[36:37] op_sel:[0,1] op_sel_hi:[1,1]
	v_pk_mul_f32 v[38:39], v[0:1], v[0:1] op_sel:[0,1] op_sel_hi:[1,1]
	v_pk_fma_f32 v[2:3], v[0:1], v[36:37], v[2:3] op_sel:[0,0,1] op_sel_hi:[1,0,0] neg_lo:[0,0,1]
	v_pk_fma_f32 v[38:39], v[0:1], v[0:1], v[38:39] op_sel:[0,0,1] op_sel_hi:[1,0,0] neg_lo:[0,0,1]
	s_nop 0
	v_pk_mul_f32 v[40:41], v[38:39], v[36:37] op_sel:[0,1] op_sel_hi:[1,1]
	v_pk_mul_f32 v[42:43], v[38:39], v[0:1] op_sel:[0,1] op_sel_hi:[1,1]
	v_pk_mul_f32 v[44:45], v[38:39], v[2:3] op_sel:[0,1] op_sel_hi:[1,1]
	v_pk_fma_f32 v[40:41], v[38:39], v[36:37], v[40:41] op_sel:[0,0,1] op_sel_hi:[1,0,0] neg_lo:[0,0,1]
	v_pk_fma_f32 v[42:43], v[38:39], v[0:1], v[42:43] op_sel:[0,0,1] op_sel_hi:[1,0,0] neg_lo:[0,0,1]
	v_pk_fma_f32 v[44:45], v[38:39], v[2:3], v[44:45] op_sel:[0,0,1] op_sel_hi:[1,0,0] neg_lo:[0,0,1]
	v_pk_mul_f32 v[46:47], v[38:39], v[38:39] op_sel:[0,1] op_sel_hi:[1,1]
	s_nop 0
	v_pk_fma_f32 v[46:47], v[38:39], v[38:39], v[46:47] op_sel:[0,0,1] op_sel_hi:[1,0,0] neg_lo:[0,0,1]
	s_nop 0
	v_pk_mul_f32 v[48:49], v[46:47], v[36:37] op_sel:[0,1] op_sel_hi:[1,1]
	v_pk_mul_f32 v[50:51], v[46:47], v[0:1] op_sel:[0,1] op_sel_hi:[1,1]
	v_pk_mul_f32 v[52:53], v[46:47], v[2:3] op_sel:[0,1] op_sel_hi:[1,1]
	v_pk_fma_f32 v[48:49], v[46:47], v[36:37], v[48:49] op_sel:[0,0,1] op_sel_hi:[1,0,0] neg_lo:[0,0,1]
	v_pk_fma_f32 v[50:51], v[46:47], v[0:1], v[50:51] op_sel:[0,0,1] op_sel_hi:[1,0,0] neg_lo:[0,0,1]
	v_pk_fma_f32 v[52:53], v[46:47], v[2:3], v[52:53] op_sel:[0,0,1] op_sel_hi:[1,0,0] neg_lo:[0,0,1]
	v_pk_mul_f32 v[54:55], v[46:47], v[38:39] op_sel:[0,1] op_sel_hi:[1,1]
	v_pk_mul_f32 v[56:57], v[46:47], v[40:41] op_sel:[0,1] op_sel_hi:[1,1]
	v_pk_mul_f32 v[58:59], v[46:47], v[42:43] op_sel:[0,1] op_sel_hi:[1,1]
	v_pk_fma_f32 v[54:55], v[46:47], v[38:39], v[54:55] op_sel:[0,0,1] op_sel_hi:[1,0,0] neg_lo:[0,0,1]
	v_pk_fma_f32 v[56:57], v[46:47], v[40:41], v[56:57] op_sel:[0,0,1] op_sel_hi:[1,0,0] neg_lo:[0,0,1]
	v_pk_fma_f32 v[58:59], v[46:47], v[42:43], v[58:59] op_sel:[0,0,1] op_sel_hi:[1,0,0] neg_lo:[0,0,1]
	v_pk_mul_f32 v[60:61], v[46:47], v[44:45] op_sel:[0,1] op_sel_hi:[1,1]
	s_nop 0
	v_pk_fma_f32 v[60:61], v[46:47], v[44:45], v[60:61] op_sel:[0,0,1] op_sel_hi:[1,0,0] neg_lo:[0,0,1]
	v_pk_mul_f32 v[62:63], v[4:5], v[36:37] op_sel:[0,1] op_sel_hi:[1,1]
	s_waitcnt lgkmcnt(14)
	v_pk_mul_f32 v[64:65], v[6:7], v[0:1] op_sel:[0,1] op_sel_hi:[1,1]
	v_pk_fma_f32 v[4:5], v[4:5], v[36:37], v[62:63] op_sel:[0,0,1] op_sel_hi:[1,0,0] neg_hi:[0,0,1]
	s_waitcnt lgkmcnt(13)
	v_pk_mul_f32 v[62:63], v[8:9], v[2:3] op_sel:[0,1] op_sel_hi:[1,1]
	v_pk_fma_f32 v[64:65], v[6:7], v[0:1], v[64:65] op_sel:[0,0,1] op_sel_hi:[1,0,0] neg_hi:[0,0,1]
	s_waitcnt lgkmcnt(12)
	v_pk_mul_f32 v[6:7], v[10:11], v[38:39] op_sel:[0,1] op_sel_hi:[1,1]
	v_pk_fma_f32 v[62:63], v[8:9], v[2:3], v[62:63] op_sel:[0,0,1] op_sel_hi:[1,0,0] neg_hi:[0,0,1]
	s_waitcnt lgkmcnt(11)
	v_pk_mul_f32 v[2:3], v[12:13], v[40:41] op_sel:[0,1] op_sel_hi:[1,1]
	v_pk_fma_f32 v[38:39], v[10:11], v[38:39], v[6:7] op_sel:[0,0,1] op_sel_hi:[1,0,0] neg_hi:[0,0,1]
	s_waitcnt lgkmcnt(10)
	v_pk_mul_f32 v[10:11], v[14:15], v[42:43] op_sel:[0,1] op_sel_hi:[1,1]
	v_pk_fma_f32 v[2:3], v[12:13], v[40:41], v[2:3] op_sel:[0,0,1] op_sel_hi:[1,0,0] neg_hi:[0,0,1]
	s_waitcnt lgkmcnt(9)
	v_pk_mul_f32 v[12:13], v[16:17], v[44:45] op_sel:[0,1] op_sel_hi:[1,1]
	v_pk_fma_f32 v[42:43], v[14:15], v[42:43], v[10:11] op_sel:[0,0,1] op_sel_hi:[1,0,0] neg_hi:[0,0,1]
	s_waitcnt lgkmcnt(8)
	v_pk_mul_f32 v[10:11], v[18:19], v[46:47] op_sel:[0,1] op_sel_hi:[1,1]
	v_pk_fma_f32 v[12:13], v[16:17], v[44:45], v[12:13] op_sel:[0,0,1] op_sel_hi:[1,0,0] neg_hi:[0,0,1]
	s_waitcnt lgkmcnt(7)
	v_pk_mul_f32 v[16:17], v[20:21], v[48:49] op_sel:[0,1] op_sel_hi:[1,1]
	v_pk_fma_f32 v[10:11], v[18:19], v[46:47], v[10:11] op_sel:[0,0,1] op_sel_hi:[1,0,0] neg_hi:[0,0,1]
	s_waitcnt lgkmcnt(6)
	v_pk_mul_f32 v[18:19], v[22:23], v[50:51] op_sel:[0,1] op_sel_hi:[1,1]
	v_pk_fma_f32 v[48:49], v[20:21], v[48:49], v[16:17] op_sel:[0,0,1] op_sel_hi:[1,0,0] neg_hi:[0,0,1]
	s_waitcnt lgkmcnt(5)
	v_pk_mul_f32 v[20:21], v[24:25], v[52:53] op_sel:[0,1] op_sel_hi:[1,1]
	v_pk_fma_f32 v[50:51], v[22:23], v[50:51], v[18:19] op_sel:[0,0,1] op_sel_hi:[1,0,0] neg_hi:[0,0,1]
	s_waitcnt lgkmcnt(4)
	v_pk_mul_f32 v[18:19], v[26:27], v[54:55] op_sel:[0,1] op_sel_hi:[1,1]
	v_pk_fma_f32 v[24:25], v[24:25], v[52:53], v[20:21] op_sel:[0,0,1] op_sel_hi:[1,0,0] neg_hi:[0,0,1]
	s_waitcnt lgkmcnt(3)
	v_pk_mul_f32 v[52:53], v[28:29], v[56:57] op_sel:[0,1] op_sel_hi:[1,1]
	v_pk_fma_f32 v[18:19], v[26:27], v[54:55], v[18:19] op_sel:[0,0,1] op_sel_hi:[1,0,0] neg_hi:[0,0,1]
	s_waitcnt lgkmcnt(2)
	v_pk_mul_f32 v[54:55], v[30:31], v[58:59] op_sel:[0,1] op_sel_hi:[1,1]
	v_pk_fma_f32 v[52:53], v[28:29], v[56:57], v[52:53] op_sel:[0,0,1] op_sel_hi:[1,0,0] neg_hi:[0,0,1]
	s_waitcnt lgkmcnt(1)
	v_pk_mul_f32 v[56:57], v[32:33], v[60:61] op_sel:[0,1] op_sel_hi:[1,1]
	v_pk_fma_f32 v[58:59], v[30:31], v[58:59], v[54:55] op_sel:[0,0,1] op_sel_hi:[1,0,0] neg_hi:[0,0,1]
	v_pk_fma_f32 v[32:33], v[32:33], v[60:61], v[56:57] op_sel:[0,0,1] op_sel_hi:[1,0,0] neg_hi:[0,0,1]
	s_waitcnt lgkmcnt(0)
; __device__ __forceinline__ f32x2 cmul(f32x2 a, f32x2 b) { return (f32x2){a.x * b.x - a.y * b.y, a.x * b.y + a.y * b.x}; }
; template <bool INV> __device__ __forceinline__ void dft16(f32x2 (&x)[16]) {
; #pragma unroll
;     for (int b = 0; b < 4; ++b) r4<INV>(x[b], x[4 + b], x[8 + b], x[12 + b]);
;     const float sg = INV ? -1.f : 1.f;
;     const f32x2 W1 = {0.92387953251f, -0.38268343236f * sg}, W2 = {0.70710678118f, -0.70710678118f * sg}, W3 = {0.38268343236f, -0.92387953251f * sg},
;                 W4 = {0.f, -1.f * sg}, W6 = {-0.70710678118f, -0.70710678118f * sg}, W9 = {-0.92387953251f, 0.38268343236f * sg};
;     x[5] = cmul(x[5], W1); x[9] = cmul(x[9], W2); x[13] = cmul(x[13], W3);
;     x[6] = cmul(x[6], W2); x[10] = cmul(x[10], W4); x[14] = cmul(x[14], W6);
;     x[7] = cmul(x[7], W3); x[11] = cmul(x[11], W6); x[15] = cmul(x[15], W9);
; #pragma unroll
;     for (int c = 0; c < 4; ++c) r4<INV>(x[4 * c], x[4 * c + 1], x[4 * c + 2], x[4 * c + 3]);
; }
; template <bool INV> __device__ __forceinline__ void pass16(LAS f32x2* X, const LAS f32x2* TH, const LAS f32x2* TL, int base, int stride, int tw) {
;     ...
; #pragma unroll
;     for (int c = 0; c < 4; ++c)
; #pragma unroll
;         for (int d = 0; d < 4; ++d) X[base + (c + 4 * d) * stride] = x[4 * c + d];
; }
	v_pk_add_f32 v[56:57], v[34:35], v[10:11]
	v_pk_add_f32 v[60:61], v[4:5], v[48:49]
	v_pk_add_f32 v[30:31], v[64:65], v[50:51]
	v_pk_add_f32 v[54:55], v[62:63], v[24:25]
	v_pk_add_f32 v[10:11], v[34:35], v[10:11] neg_lo:[0,1] neg_hi:[0,1]
	v_pk_add_f32 v[4:5], v[4:5], v[48:49] neg_lo:[0,1] neg_hi:[0,1]
	v_pk_add_f32 v[50:51], v[64:65], v[50:51] neg_lo:[0,1] neg_hi:[0,1]
	v_pk_add_f32 v[62:63], v[62:63], v[24:25] neg_lo:[0,1] neg_hi:[0,1]
	v_pk_add_f32 v[24:25], v[38:39], v[18:19]
	v_pk_add_f32 v[64:65], v[2:3], v[52:53]
	v_pk_add_f32 v[48:49], v[42:43], v[58:59]
	v_pk_add_f32 v[34:35], v[12:13], v[32:33]
	v_pk_add_f32 v[38:39], v[38:39], v[18:19] neg_lo:[0,1] neg_hi:[0,1]
	v_pk_add_f32 v[52:53], v[2:3], v[52:53] neg_lo:[0,1] neg_hi:[0,1]
	v_pk_add_f32 v[42:43], v[42:43], v[58:59] neg_lo:[0,1] neg_hi:[0,1]
	v_pk_add_f32 v[32:33], v[12:13], v[32:33] neg_lo:[0,1] neg_hi:[0,1]
	v_pk_add_f32 v[12:13], v[56:57], v[24:25]
	v_pk_add_f32 v[58:59], v[60:61], v[64:65]
	v_pk_add_f32 v[2:3], v[30:31], v[48:49]
	v_pk_add_f32 v[18:19], v[54:55], v[34:35]
	v_pk_add_f32 v[56:57], v[56:57], v[24:25] neg_lo:[0,1] neg_hi:[0,1]
	v_pk_add_f32 v[60:61], v[60:61], v[64:65] neg_lo:[0,1] neg_hi:[0,1]
	v_pk_add_f32 v[30:31], v[30:31], v[48:49] neg_lo:[0,1] neg_hi:[0,1]
	v_pk_add_f32 v[34:35], v[54:55], v[34:35] neg_lo:[0,1] neg_hi:[0,1]
	v_pk_add_f32 v[54:55], v[10:11], v[38:39] op_sel:[0,1] op_sel_hi:[1,0] neg_lo:[0,1]
	v_pk_add_f32 v[48:49], v[4:5], v[52:53] op_sel:[0,1] op_sel_hi:[1,0] neg_lo:[0,1]
	v_pk_add_f32 v[64:65], v[50:51], v[42:43] op_sel:[0,1] op_sel_hi:[1,0] neg_lo:[0,1]
	v_pk_add_f32 v[24:25], v[62:63], v[32:33] op_sel:[0,1] op_sel_hi:[1,0] neg_lo:[0,1]
	v_pk_add_f32 v[10:11], v[10:11], v[38:39] op_sel:[0,1] op_sel_hi:[1,0] neg_hi:[0,1]
	v_pk_add_f32 v[4:5], v[4:5], v[52:53] op_sel:[0,1] op_sel_hi:[1,0] neg_hi:[0,1]
	v_pk_add_f32 v[50:51], v[50:51], v[42:43] op_sel:[0,1] op_sel_hi:[1,0] neg_hi:[0,1]
	v_pk_add_f32 v[32:33], v[62:63], v[32:33] op_sel:[0,1] op_sel_hi:[1,0] neg_hi:[0,1]
	v_pk_mul_f32 v[62:63], v[48:49], s[82:83] op_sel_hi:[1,0]
	v_pk_mul_f32 v[42:43], v[60:61], s[76:77] op_sel_hi:[1,0]
	v_pk_mul_f32 v[52:53], v[4:5], s[44:45] op_sel_hi:[1,0]
	v_pk_mul_f32 v[38:39], v[64:65], s[76:77] op_sel_hi:[1,0]
	v_pk_mul_f32 v[28:29], v[50:51], s[76:77] op_sel_hi:[1,0]
	v_pk_mul_f32 v[26:27], v[24:25], s[44:45] op_sel_hi:[1,0]
	v_pk_mul_f32 v[20:21], v[34:35], s[76:77] op_sel_hi:[1,0]
	v_pk_mul_f32 v[22:23], v[32:33], s[70:71] op_sel_hi:[1,0]
	v_pk_fma_f32 v[62:63], v[48:49], s[44:45], v[62:63] op_sel:[0,0,1] op_sel_hi:[1,0,0] neg_lo:[0,0,1]
	v_pk_fma_f32 v[60:61], v[60:61], s[76:77], v[42:43] op_sel:[0,0,1] op_sel_hi:[1,0,0] neg_lo:[0,0,1]
	v_pk_fma_f32 v[4:5], v[4:5], s[82:83], v[52:53] op_sel:[0,0,1] op_sel_hi:[1,0,0] neg_lo:[0,0,1]
	v_pk_fma_f32 v[38:39], v[64:65], s[76:77], v[38:39] op_sel:[0,0,1] op_sel_hi:[1,0,0] neg_lo:[0,0,1]
	v_pk_fma_f32 v[50:51], v[50:51], s[72:73], v[28:29] op_sel:[0,0,1] op_sel_hi:[1,0,0] neg_lo:[0,0,1]
	v_pk_fma_f32 v[26:27], v[24:25], s[82:83], v[26:27] op_sel:[0,0,1] op_sel_hi:[1,0,0] neg_lo:[0,0,1]
	v_pk_fma_f32 v[20:21], v[34:35], s[72:73], v[20:21] op_sel:[0,0,1] op_sel_hi:[1,0,0] neg_lo:[0,0,1]
	v_pk_fma_f32 v[32:33], v[32:33], s[64:65], v[22:23] op_sel:[0,0,1] op_sel_hi:[1,0,0] neg_lo:[0,0,1]
	v_pk_add_f32 v[22:23], v[12:13], v[2:3]
	v_pk_add_f32 v[34:35], v[54:55], v[38:39]
	v_pk_add_f32 v[24:25], v[56:57], v[30:31] op_sel:[0,1] op_sel_hi:[1,0] neg_lo:[0,1]
	v_pk_add_f32 v[28:29], v[10:11], v[50:51]
	v_pk_add_f32 v[12:13], v[12:13], v[2:3] neg_lo:[0,1] neg_hi:[0,1]
	v_pk_add_f32 v[54:55], v[54:55], v[38:39] neg_lo:[0,1] neg_hi:[0,1]
	v_pk_add_f32 v[56:57], v[56:57], v[30:31] op_sel:[0,1] op_sel_hi:[1,0] neg_hi:[0,1]
	v_pk_add_f32 v[50:51], v[10:11], v[50:51] neg_lo:[0,1] neg_hi:[0,1]
	v_pk_add_f32 v[10:11], v[58:59], v[18:19]
	v_pk_add_f32 v[30:31], v[62:63], v[26:27]
	v_pk_add_f32 v[38:39], v[60:61], v[20:21]
	v_pk_add_f32 v[2:3], v[4:5], v[32:33]
	v_pk_add_f32 v[58:59], v[58:59], v[18:19] neg_lo:[0,1] neg_hi:[0,1]
	v_pk_add_f32 v[62:63], v[62:63], v[26:27] neg_lo:[0,1] neg_hi:[0,1]
	v_pk_add_f32 v[20:21], v[60:61], v[20:21] neg_lo:[0,1] neg_hi:[0,1]
	v_pk_add_f32 v[4:5], v[4:5], v[32:33] neg_lo:[0,1] neg_hi:[0,1]
	v_pk_add_f32 v[32:33], v[22:23], v[10:11]
	v_pk_add_f32 v[60:61], v[34:35], v[30:31]
	v_pk_add_f32 v[26:27], v[24:25], v[38:39]
	v_pk_add_f32 v[18:19], v[28:29], v[2:3]
	v_pk_add_f32 v[10:11], v[22:23], v[10:11] neg_lo:[0,1] neg_hi:[0,1]
	v_pk_add_f32 v[30:31], v[34:35], v[30:31] neg_lo:[0,1] neg_hi:[0,1]
	v_pk_add_f32 v[38:39], v[24:25], v[38:39] neg_lo:[0,1] neg_hi:[0,1]
	v_pk_add_f32 v[2:3], v[28:29], v[2:3] neg_lo:[0,1] neg_hi:[0,1]
	v_pk_add_f32 v[28:29], v[12:13], v[58:59] op_sel:[0,1] op_sel_hi:[1,0] neg_lo:[0,1]
	v_pk_add_f32 v[24:25], v[54:55], v[62:63] op_sel:[0,1] op_sel_hi:[1,0] neg_lo:[0,1]
	v_pk_add_f32 v[34:35], v[56:57], v[20:21] op_sel:[0,1] op_sel_hi:[1,0] neg_lo:[0,1]
	v_pk_add_f32 v[22:23], v[50:51], v[4:5] op_sel:[0,1] op_sel_hi:[1,0] neg_lo:[0,1]
	v_pk_add_f32 v[12:13], v[12:13], v[58:59] op_sel:[0,1] op_sel_hi:[1,0] neg_hi:[0,1]
	v_pk_add_f32 v[54:55], v[54:55], v[62:63] op_sel:[0,1] op_sel_hi:[1,0] neg_hi:[0,1]
	v_pk_add_f32 v[56:57], v[56:57], v[20:21] op_sel:[0,1] op_sel_hi:[1,0] neg_hi:[0,1]
	v_pk_add_f32 v[50:51], v[50:51], v[4:5] op_sel:[0,1] op_sel_hi:[1,0] neg_hi:[0,1]
	ds_write_b64 v151, v[32:33] offset:0
	ds_write_b64 v151, v[60:61] offset:8704
	ds_write_b64 v151, v[26:27] offset:17408
	ds_write_b64 v151, v[18:19] offset:26112
	ds_write_b64 v151, v[28:29] offset:34816
	ds_write_b64 v151, v[24:25] offset:43520
	ds_write_b64 v151, v[34:35] offset:52224
	ds_write_b64 v151, v[22:23] offset:60928
	ds_write_b64 v176, v[10:11] offset:0
	ds_write_b64 v176, v[30:31] offset:8704
	ds_write_b64 v176, v[38:39] offset:17408
	ds_write_b64 v176, v[2:3] offset:26112
	ds_write_b64 v176, v[12:13] offset:34816
	ds_write_b64 v176, v[54:55] offset:43520
	ds_write_b64 v176, v[56:57] offset:52224
	ds_write_b64 v176, v[50:51] offset:60928
	s_cbranch_scc1 .LBB0_856
; #define LAS __attribute__((address_space(3)))
; #define LT() ({ int lt_ = tid; asm volatile("" : "+v"(lt_)); lt_; })
; __device__ __forceinline__ void hyena_latent(Frame& F, int l, int ch, LAS f32x2* X, const LAS f32x2* TH, const LAS f32x2* TL, GAS f32x2* KS, const LAS float* CT  , bool wr = true) {
;     ...
;             if (par == 0) {
; #pragma unroll
;                 for (int i = 0; i < 8; ++i) { const int g = LT() + NTHR * i; const LAS f32x4* XP = (const LAS f32x4*)(X + phys(4 * g)); KE4[2 * g] = XP[0]; KE4[2 * g + 1] = XP[1]; }
;                 __syncthreads();
	s_waitcnt lgkmcnt(0)
	s_barrier
	s_andn2_b64 vcc, exec, s[34:35]
	s_mov_b64 s[12:13], -1
	s_cbranch_vccnz .LBB0_662
	v_mov_b32_e32 v1, v140
	s_mov_b64 s[12:13], 0
	v_lshlrev_b32_e32 v0, 1, v1
	v_and_b32_e32 v2, 0xffffffe0, v0
	v_lshlrev_b32_e32 v1, 5, v1
	v_add3_u32 v4, 0, v2, v1
	v_ashrrev_i32_e32 v1, 31, v0
	v_lshl_add_u64 v[8:9], v[0:1], 4, s[18:19]
	ds_read_b128 v[0:3], v4
	ds_read_b128 v[4:7], v4 offset:16
	s_waitcnt lgkmcnt(1)
	global_store_dwordx4 v[8:9], v[0:3], off
	s_waitcnt lgkmcnt(0)
	global_store_dwordx4 v[8:9], v[4:7], off offset:16
	v_mov_b32_e32 v0, v140
	s_nop 0
	v_add_u32_e32 v1, 0x200, v0
	v_lshlrev_b32_e32 v0, 1, v1
	v_and_b32_e32 v2, 0xffffffe0, v0
	v_lshlrev_b32_e32 v1, 5, v1
	v_add3_u32 v4, 0, v2, v1
	v_ashrrev_i32_e32 v1, 31, v0
	v_lshl_add_u64 v[8:9], v[0:1], 4, s[18:19]
	ds_read_b128 v[0:3], v4
	ds_read_b128 v[4:7], v4 offset:16
	s_waitcnt lgkmcnt(1)
	global_store_dwordx4 v[8:9], v[0:3], off
	s_waitcnt lgkmcnt(0)
	global_store_dwordx4 v[8:9], v[4:7], off offset:16
	v_mov_b32_e32 v0, v140
	s_nop 0
	v_add_u32_e32 v1, 0x400, v0
	v_lshlrev_b32_e32 v0, 1, v1
	v_and_b32_e32 v2, 0xffffffe0, v0
	v_lshlrev_b32_e32 v1, 5, v1
	v_add3_u32 v4, 0, v2, v1
	v_ashrrev_i32_e32 v1, 31, v0
	v_lshl_add_u64 v[8:9], v[0:1], 4, s[18:19]
	ds_read_b128 v[0:3], v4
	ds_read_b128 v[4:7], v4 offset:16
	s_waitcnt lgkmcnt(1)
	global_store_dwordx4 v[8:9], v[0:3], off
	s_waitcnt lgkmcnt(0)
	global_store_dwordx4 v[8:9], v[4:7], off offset:16
	v_mov_b32_e32 v0, v140
	s_nop 0
	v_add_u32_e32 v1, 0x600, v0
	v_lshlrev_b32_e32 v0, 1, v1
	v_and_b32_e32 v2, 0xffffffe0, v0
	v_lshlrev_b32_e32 v1, 5, v1
	v_add3_u32 v4, 0, v2, v1
	v_ashrrev_i32_e32 v1, 31, v0
	v_lshl_add_u64 v[8:9], v[0:1], 4, s[18:19]
	ds_read_b128 v[0:3], v4
	ds_read_b128 v[4:7], v4 offset:16
	s_waitcnt lgkmcnt(1)
	global_store_dwordx4 v[8:9], v[0:3], off
	s_waitcnt lgkmcnt(0)
	global_store_dwordx4 v[8:9], v[4:7], off offset:16
	v_mov_b32_e32 v0, v140
	s_nop 0
	v_add_u32_e32 v1, 0x800, v0
	v_lshlrev_b32_e32 v0, 1, v1
	v_and_b32_e32 v2, 0xffffffe0, v0
	v_lshlrev_b32_e32 v1, 5, v1
	v_add3_u32 v4, 0, v2, v1
	v_ashrrev_i32_e32 v1, 31, v0
	v_lshl_add_u64 v[8:9], v[0:1], 4, s[18:19]
	ds_read_b128 v[0:3], v4
	ds_read_b128 v[4:7], v4 offset:16
	s_waitcnt lgkmcnt(1)
	global_store_dwordx4 v[8:9], v[0:3], off
	s_waitcnt lgkmcnt(0)
	global_store_dwordx4 v[8:9], v[4:7], off offset:16
	v_mov_b32_e32 v0, v140
	s_nop 0
	v_add_u32_e32 v1, 0xa00, v0
	v_lshlrev_b32_e32 v0, 1, v1
	v_and_b32_e32 v2, 0xffffffe0, v0
	v_lshlrev_b32_e32 v1, 5, v1
	v_add3_u32 v4, 0, v2, v1
	v_ashrrev_i32_e32 v1, 31, v0
	v_lshl_add_u64 v[8:9], v[0:1], 4, s[18:19]
	ds_read_b128 v[0:3], v4
	ds_read_b128 v[4:7], v4 offset:16
	s_waitcnt lgkmcnt(1)
	global_store_dwordx4 v[8:9], v[0:3], off
	s_waitcnt lgkmcnt(0)
	global_store_dwordx4 v[8:9], v[4:7], off offset:16
	v_mov_b32_e32 v0, v140
	s_nop 0
	v_add_u32_e32 v1, 0xc00, v0
	v_lshlrev_b32_e32 v0, 1, v1
	v_and_b32_e32 v2, 0xffffffe0, v0
	v_lshlrev_b32_e32 v1, 5, v1
	v_add3_u32 v4, 0, v2, v1
	v_ashrrev_i32_e32 v1, 31, v0
	v_lshl_add_u64 v[8:9], v[0:1], 4, s[18:19]
	ds_read_b128 v[0:3], v4
	ds_read_b128 v[4:7], v4 offset:16
	s_waitcnt lgkmcnt(1)
	global_store_dwordx4 v[8:9], v[0:3], off
	s_waitcnt lgkmcnt(0)
	global_store_dwordx4 v[8:9], v[4:7], off offset:16
	v_mov_b32_e32 v0, v140
	s_nop 0
	v_add_u32_e32 v1, 0xe00, v0
	v_lshlrev_b32_e32 v0, 1, v1
	v_and_b32_e32 v2, 0xffffffe0, v0
	v_lshlrev_b32_e32 v1, 5, v1
	v_add3_u32 v4, 0, v2, v1
	v_ashrrev_i32_e32 v1, 31, v0
	v_lshl_add_u64 v[8:9], v[0:1], 4, s[18:19]
	ds_read_b128 v[0:3], v4
	ds_read_b128 v[4:7], v4 offset:16
	s_waitcnt lgkmcnt(1)
	global_store_dwordx4 v[8:9], v[0:3], off
	s_waitcnt lgkmcnt(0)
	global_store_dwordx4 v[8:9], v[4:7], off offset:16
	s_barrier
	s_branch .LBB0_662

; #define LAS __attribute__((address_space(3)))
; __device__ __forceinline__ f32x2 cmul(f32x2 a, f32x2 b) { return (f32x2){a.x * b.x - a.y * b.y, a.x * b.y + a.y * b.x}; }
; __device__ __forceinline__ f32x2 tw32k(const LAS f32x2* TH, const LAS f32x2* TL, int n) { return cmul(TH[n >> 7], TL[n & 127]); }
; template <bool INV> __device__ __forceinline__ void bfly16(f32x2 (&x)[16], const LAS f32x2* TH, const LAS f32x2* TL, int tw) {
;     f32x2 W = tw32k(TH, TL, tw); if (INV) W.y = -W.y;
;     if (INV) { f32x2 p = W;
; #pragma unroll
;         for (int q = 1; q < 16; ++q) { x[q] = cmul(x[q], p); if (q < 15) p = cmul(p, W); } }
;     dft16<INV>(x);
;     if (!INV) { f32x2 p = W;
; #pragma unroll
;         for (int r = 1; r < 16; ++r) { x[4 * (r & 3) + (r >> 2)] = cmul(x[4 * (r & 3) + (r >> 2)], p); if (r < 15) p = cmul(p, W); } }
; }
; template <bool INV> __device__ __forceinline__ void bfly16_tab(f32x2 (&x)[16], const LAS f32x2* T, int tstride, int j) {
;     if (INV) {
; #pragma unroll
;         for (int q = 1; q < 16; ++q) { f32x2 p = T[q * tstride + j]; p.y = -p.y; x[q] = cmul(x[q], p); } }
;     dft16<INV>(x);
;     if (!INV) {
; #pragma unroll
;         for (int r = 1; r < 16; ++r) { const f32x2 p = T[r * tstride + j]; x[4 * (r & 3) + (r >> 2)] = cmul(x[4 * (r & 3) + (r >> 2)], p); } }
; }
; template <bool INV> __device__ __forceinline__ void pass16_s64(LAS f32x2* X, const LAS f32x2* TH, int base, int j) {
;     f32x2 x[16];
; #pragma unroll
;     for (int q = 0; q < 16; ++q) x[q] = X[base + q * 68];
;     bfly16_tab<INV>(x, TH - 2048, 64, j);
; #pragma unroll
;     for (int c = 0; c < 4; ++c)
; #pragma unroll
;         for (int d = 0; d < 4; ++d) X[base + (c + 4 * d) * 68] = x[4 * c + d];
; }
; template <bool INV> __device__ __forceinline__ void pass16(LAS f32x2* X, const LAS f32x2* TH, const LAS f32x2* TL, int base, int stride, int tw) {
;     f32x2 x[16];
; #pragma unroll
;     for (int q = 0; q < 16; ++q) x[q] = X[base + q * stride];
;     bfly16<INV>(x, TH, TL, tw);
; #pragma unroll
;     for (int c = 0; c < 4; ++c)
; #pragma unroll
;         for (int d = 0; d < 4; ++d) X[base + (c + 4 * d) * stride] = x[4 * c + d];
; }
.LBB0_944:
	v_add_u32_e32 v37, s0, v140
	v_lshrrev_b32_e32 v138, 6, v37
	v_and_b32_e32 v234, 63, v37
	v_lshlrev_b32_e32 v176, 5, v138
	v_lshlrev_b32_e32 v218, 3, v138
	v_lshlrev_b32_e32 v234, 4, v234
	v_lshl_add_u32 v176, v37, 3, v176
	v_add_u32_e32 v218, 0x26000, v218
	v_add_u32_e32 v234, 0x26400, v234
	v_add_u32_e32 v235, 0x11000, v176
	ds_read_b64 v[0:1], v218
	ds_read_b64 v[2:3], v234
	ds_read_b64 v[4:5], v176 offset:0
	ds_read_b64 v[6:7], v235 offset:0
	ds_read_b64 v[8:9], v176 offset:8704
	ds_read_b64 v[10:11], v235 offset:8704
	ds_read_b64 v[12:13], v176 offset:17408
	ds_read_b64 v[14:15], v235 offset:17408
	ds_read_b64 v[16:17], v176 offset:26112
	ds_read_b64 v[18:19], v235 offset:26112
	ds_read_b64 v[20:21], v176 offset:34816
	ds_read_b64 v[22:23], v235 offset:34816
	ds_read_b64 v[24:25], v176 offset:43520
	ds_read_b64 v[26:27], v235 offset:43520
	ds_read_b64 v[28:29], v176 offset:52224
	ds_read_b64 v[30:31], v235 offset:52224
	ds_read_b64 v[32:33], v176 offset:60928
	ds_read_b64 v[34:35], v235 offset:60928
	s_cmp_eq_u32 s0, 0
	s_movk_i32 s0, 0x200
	s_mov_b64 s[8:9], 0
	s_waitcnt lgkmcnt(15)
	v_pk_mul_f32 v[38:39], v[0:1], v[2:3] op_sel:[0,1] op_sel_hi:[1,1]
	s_nop 0
	v_pk_fma_f32 v[38:39], v[0:1], v[2:3], v[38:39] op_sel:[0,0,1] op_sel_hi:[1,0,0] neg_lo:[0,0,1]
	s_nop 0
	v_pk_mul_f32 v[2:3], v[38:39], v[38:39] op_sel:[0,1] op_sel_hi:[1,1]
	s_nop 0
	v_pk_fma_f32 v[2:3], v[38:39], v[38:39], v[2:3] op_sel:[0,0,1] op_sel_hi:[1,0,0] neg_lo:[0,0,1]
	s_nop 0
	v_pk_mul_f32 v[0:1], v[2:3], v[38:39] op_sel:[0,1] op_sel_hi:[1,1]
	v_pk_mul_f32 v[40:41], v[2:3], v[2:3] op_sel:[0,1] op_sel_hi:[1,1]
	v_pk_fma_f32 v[0:1], v[2:3], v[38:39], v[0:1] op_sel:[0,0,1] op_sel_hi:[1,0,0] neg_lo:[0,0,1]
	v_pk_fma_f32 v[40:41], v[2:3], v[2:3], v[40:41] op_sel:[0,0,1] op_sel_hi:[1,0,0] neg_lo:[0,0,1]
	s_nop 0
	v_pk_mul_f32 v[42:43], v[40:41], v[38:39] op_sel:[0,1] op_sel_hi:[1,1]
	v_pk_mul_f32 v[44:45], v[40:41], v[2:3] op_sel:[0,1] op_sel_hi:[1,1]
	v_pk_mul_f32 v[46:47], v[40:41], v[0:1] op_sel:[0,1] op_sel_hi:[1,1]
	v_pk_fma_f32 v[42:43], v[40:41], v[38:39], v[42:43] op_sel:[0,0,1] op_sel_hi:[1,0,0] neg_lo:[0,0,1]
	v_pk_fma_f32 v[44:45], v[40:41], v[2:3], v[44:45] op_sel:[0,0,1] op_sel_hi:[1,0,0] neg_lo:[0,0,1]
	v_pk_fma_f32 v[46:47], v[40:41], v[0:1], v[46:47] op_sel:[0,0,1] op_sel_hi:[1,0,0] neg_lo:[0,0,1]
	v_pk_mul_f32 v[48:49], v[40:41], v[40:41] op_sel:[0,1] op_sel_hi:[1,1]
	s_nop 0
	v_pk_fma_f32 v[48:49], v[40:41], v[40:41], v[48:49] op_sel:[0,0,1] op_sel_hi:[1,0,0] neg_lo:[0,0,1]
	s_nop 0
	v_pk_mul_f32 v[50:51], v[48:49], v[38:39] op_sel:[0,1] op_sel_hi:[1,1]
	v_pk_mul_f32 v[52:53], v[48:49], v[2:3] op_sel:[0,1] op_sel_hi:[1,1]
	v_pk_mul_f32 v[54:55], v[48:49], v[0:1] op_sel:[0,1] op_sel_hi:[1,1]
	v_pk_fma_f32 v[50:51], v[48:49], v[38:39], v[50:51] op_sel:[0,0,1] op_sel_hi:[1,0,0] neg_lo:[0,0,1]
	v_pk_fma_f32 v[52:53], v[48:49], v[2:3], v[52:53] op_sel:[0,0,1] op_sel_hi:[1,0,0] neg_lo:[0,0,1]
	v_pk_fma_f32 v[54:55], v[48:49], v[0:1], v[54:55] op_sel:[0,0,1] op_sel_hi:[1,0,0] neg_lo:[0,0,1]
	v_pk_mul_f32 v[56:57], v[48:49], v[40:41] op_sel:[0,1] op_sel_hi:[1,1]
	v_pk_mul_f32 v[58:59], v[48:49], v[42:43] op_sel:[0,1] op_sel_hi:[1,1]
	v_pk_mul_f32 v[60:61], v[48:49], v[44:45] op_sel:[0,1] op_sel_hi:[1,1]
	v_pk_fma_f32 v[56:57], v[48:49], v[40:41], v[56:57] op_sel:[0,0,1] op_sel_hi:[1,0,0] neg_lo:[0,0,1]
	v_pk_fma_f32 v[58:59], v[48:49], v[42:43], v[58:59] op_sel:[0,0,1] op_sel_hi:[1,0,0] neg_lo:[0,0,1]
	v_pk_fma_f32 v[60:61], v[48:49], v[44:45], v[60:61] op_sel:[0,0,1] op_sel_hi:[1,0,0] neg_lo:[0,0,1]
	v_pk_mul_f32 v[62:63], v[48:49], v[46:47] op_sel:[0,1] op_sel_hi:[1,1]
	s_nop 0
	v_pk_fma_f32 v[62:63], v[48:49], v[46:47], v[62:63] op_sel:[0,0,1] op_sel_hi:[1,0,0] neg_lo:[0,0,1]
	s_waitcnt lgkmcnt(14)
	v_pk_add_f32 v[64:65], v[4:5], v[6:7]
	s_waitcnt lgkmcnt(12)
	v_pk_add_f32 v[66:67], v[8:9], v[10:11]
	s_waitcnt lgkmcnt(10)
	v_pk_add_f32 v[68:69], v[12:13], v[14:15]
	s_waitcnt lgkmcnt(8)
	v_pk_add_f32 v[70:71], v[16:17], v[18:19]
	v_pk_add_f32 v[6:7], v[4:5], v[6:7] neg_lo:[0,1] neg_hi:[0,1]
	v_pk_add_f32 v[10:11], v[8:9], v[10:11] neg_lo:[0,1] neg_hi:[0,1]
	v_pk_add_f32 v[12:13], v[12:13], v[14:15] neg_lo:[0,1] neg_hi:[0,1]
	v_pk_add_f32 v[16:17], v[16:17], v[18:19] neg_lo:[0,1] neg_hi:[0,1]
	s_waitcnt lgkmcnt(6)
	v_pk_add_f32 v[18:19], v[20:21], v[22:23]
	s_waitcnt lgkmcnt(4)
	v_pk_add_f32 v[14:15], v[24:25], v[26:27]
	s_waitcnt lgkmcnt(2)
	v_pk_add_f32 v[8:9], v[28:29], v[30:31]
	s_waitcnt lgkmcnt(0)
; #define LAS __attribute__((address_space(3)))
; __device__ __forceinline__ f32x2 cmul(f32x2 a, f32x2 b) { return (f32x2){a.x * b.x - a.y * b.y, a.x * b.y + a.y * b.x}; }
; __device__ __forceinline__ f32x2 tw32k(const LAS f32x2* TH, const LAS f32x2* TL, int n) { return cmul(TH[n >> 7], TL[n & 127]); }
; template <bool INV> __device__ __forceinline__ void dft16(f32x2 (&x)[16]) {
; #pragma unroll
;     for (int b = 0; b < 4; ++b) r4<INV>(x[b], x[4 + b], x[8 + b], x[12 + b]);
;     const float sg = INV ? -1.f : 1.f;
;     const f32x2 W1 = {0.92387953251f, -0.38268343236f * sg}, W2 = {0.70710678118f, -0.70710678118f * sg}, W3 = {0.38268343236f, -0.92387953251f * sg},
;                 W4 = {0.f, -1.f * sg}, W6 = {-0.70710678118f, -0.70710678118f * sg}, W9 = {-0.92387953251f, 0.38268343236f * sg};
;     x[5] = cmul(x[5], W1); x[9] = cmul(x[9], W2); x[13] = cmul(x[13], W3);
;     x[6] = cmul(x[6], W2); x[10] = cmul(x[10], W4); x[14] = cmul(x[14], W6);
;     x[7] = cmul(x[7], W3); x[11] = cmul(x[11], W6); x[15] = cmul(x[15], W9);
; #pragma unroll
;     for (int c = 0; c < 4; ++c) r4<INV>(x[4 * c], x[4 * c + 1], x[4 * c + 2], x[4 * c + 3]);
; }
; template <bool INV> __device__ __forceinline__ void bfly16(f32x2 (&x)[16], const LAS f32x2* TH, const LAS f32x2* TL, int tw) {
;     f32x2 W = tw32k(TH, TL, tw); if (INV) W.y = -W.y;
;     if (INV) { f32x2 p = W;
; #pragma unroll
;         for (int q = 1; q < 16; ++q) { x[q] = cmul(x[q], p); if (q < 15) p = cmul(p, W); } }
;     dft16<INV>(x);
;     if (!INV) { f32x2 p = W;
; #pragma unroll
;         for (int r = 1; r < 16; ++r) { x[4 * (r & 3) + (r >> 2)] = cmul(x[4 * (r & 3) + (r >> 2)], p); if (r < 15) p = cmul(p, W); } }
; }
	v_pk_add_f32 v[4:5], v[32:33], v[34:35]
	v_pk_add_f32 v[22:23], v[20:21], v[22:23] neg_lo:[0,1] neg_hi:[0,1]
	v_pk_add_f32 v[24:25], v[24:25], v[26:27] neg_lo:[0,1] neg_hi:[0,1]
	v_pk_add_f32 v[30:31], v[28:29], v[30:31] neg_lo:[0,1] neg_hi:[0,1]
	v_pk_add_f32 v[32:33], v[32:33], v[34:35] neg_lo:[0,1] neg_hi:[0,1]
	v_pk_add_f32 v[34:35], v[64:65], v[18:19]
	v_pk_add_f32 v[28:29], v[66:67], v[14:15]
	v_pk_add_f32 v[26:27], v[68:69], v[8:9]
	v_pk_add_f32 v[20:21], v[70:71], v[4:5]
	v_pk_add_f32 v[64:65], v[64:65], v[18:19] neg_lo:[0,1] neg_hi:[0,1]
	v_pk_add_f32 v[66:67], v[66:67], v[14:15] neg_lo:[0,1] neg_hi:[0,1]
	v_pk_add_f32 v[68:69], v[68:69], v[8:9] neg_lo:[0,1] neg_hi:[0,1]
	v_pk_add_f32 v[70:71], v[70:71], v[4:5] neg_lo:[0,1] neg_hi:[0,1]
	v_pk_add_f32 v[4:5], v[6:7], v[22:23] op_sel:[0,1] op_sel_hi:[1,0] neg_hi:[0,1]
	v_pk_add_f32 v[8:9], v[10:11], v[24:25] op_sel:[0,1] op_sel_hi:[1,0] neg_hi:[0,1]
	v_pk_add_f32 v[14:15], v[12:13], v[30:31] op_sel:[0,1] op_sel_hi:[1,0] neg_hi:[0,1]
	v_pk_add_f32 v[18:19], v[16:17], v[32:33] op_sel:[0,1] op_sel_hi:[1,0] neg_hi:[0,1]
	v_pk_add_f32 v[22:23], v[6:7], v[22:23] op_sel:[0,1] op_sel_hi:[1,0] neg_lo:[0,1]
	v_pk_add_f32 v[24:25], v[10:11], v[24:25] op_sel:[0,1] op_sel_hi:[1,0] neg_lo:[0,1]
	v_pk_add_f32 v[30:31], v[12:13], v[30:31] op_sel:[0,1] op_sel_hi:[1,0] neg_lo:[0,1]
	v_pk_add_f32 v[16:17], v[16:17], v[32:33] op_sel:[0,1] op_sel_hi:[1,0] neg_lo:[0,1]
	v_pk_mul_f32 v[32:33], v[8:9], s[70:71] op_sel_hi:[1,0]
	v_pk_mul_f32 v[12:13], v[66:67], s[72:73] op_sel_hi:[1,0]
	v_pk_mul_f32 v[10:11], v[24:25], s[64:65] op_sel_hi:[1,0]
	v_pk_mul_f32 v[6:7], v[14:15], s[72:73] op_sel_hi:[1,0]
	v_pk_mul_f32 v[72:73], v[30:31], s[72:73] op_sel_hi:[1,0]
	v_pk_mul_f32 v[74:75], v[18:19], s[64:65] op_sel_hi:[1,0]
	v_pk_mul_f32 v[76:77], v[70:71], s[72:73] op_sel_hi:[1,0]
	v_pk_mul_f32 v[78:79], v[16:17], s[82:83] op_sel_hi:[1,0]
	v_pk_fma_f32 v[8:9], v[8:9], s[44:45], v[32:33] op_sel:[0,0,1] op_sel_hi:[1,0,0] neg_lo:[0,0,1]
	v_pk_fma_f32 v[66:67], v[66:67], s[76:77], v[12:13] op_sel:[0,0,1] op_sel_hi:[1,0,0] neg_lo:[0,0,1]
	v_pk_fma_f32 v[24:25], v[24:25], s[82:83], v[10:11] op_sel:[0,0,1] op_sel_hi:[1,0,0] neg_lo:[0,0,1]
	v_pk_fma_f32 v[14:15], v[14:15], s[76:77], v[6:7] op_sel:[0,0,1] op_sel_hi:[1,0,0] neg_lo:[0,0,1]
	v_pk_fma_f32 v[72:73], v[30:31], s[72:73], v[72:73] op_sel:[0,0,1] op_sel_hi:[1,0,0] neg_lo:[0,0,1]
	v_pk_fma_f32 v[74:75], v[18:19], s[82:83], v[74:75] op_sel:[0,0,1] op_sel_hi:[1,0,0] neg_lo:[0,0,1]
	v_pk_fma_f32 v[70:71], v[70:71], s[72:73], v[76:77] op_sel:[0,0,1] op_sel_hi:[1,0,0] neg_lo:[0,0,1]
	v_pk_fma_f32 v[78:79], v[16:17], s[64:65], v[78:79] op_sel:[0,0,1] op_sel_hi:[1,0,0] neg_lo:[0,0,1]
	v_pk_add_f32 v[16:17], v[34:35], v[26:27]
	v_pk_add_f32 v[76:77], v[4:5], v[14:15]
	v_pk_add_f32 v[18:19], v[64:65], v[68:69] op_sel:[0,1] op_sel_hi:[1,0] neg_hi:[0,1]
	v_pk_add_f32 v[30:31], v[22:23], v[72:73]
	v_pk_add_f32 v[34:35], v[34:35], v[26:27] neg_lo:[0,1] neg_hi:[0,1]
	v_pk_add_f32 v[4:5], v[4:5], v[14:15] neg_lo:[0,1] neg_hi:[0,1]
	v_pk_add_f32 v[64:65], v[64:65], v[68:69] op_sel:[0,1] op_sel_hi:[1,0] neg_lo:[0,1]
	v_pk_add_f32 v[22:23], v[22:23], v[72:73] neg_lo:[0,1] neg_hi:[0,1]
	v_pk_add_f32 v[72:73], v[28:29], v[20:21]
	v_pk_add_f32 v[68:69], v[8:9], v[74:75]
	v_pk_add_f32 v[14:15], v[66:67], v[70:71]
	v_pk_add_f32 v[26:27], v[24:25], v[78:79]
	v_pk_add_f32 v[28:29], v[28:29], v[20:21] neg_lo:[0,1] neg_hi:[0,1]
	v_pk_add_f32 v[74:75], v[8:9], v[74:75] neg_lo:[0,1] neg_hi:[0,1]
	v_pk_add_f32 v[70:71], v[66:67], v[70:71] neg_lo:[0,1] neg_hi:[0,1]
	v_pk_add_f32 v[24:25], v[24:25], v[78:79] neg_lo:[0,1] neg_hi:[0,1]
	v_pk_add_f32 v[78:79], v[16:17], v[72:73]
	v_pk_add_f32 v[66:67], v[76:77], v[68:69]
	v_pk_add_f32 v[8:9], v[18:19], v[14:15]
	v_pk_add_f32 v[20:21], v[30:31], v[26:27]
	v_pk_add_f32 v[16:17], v[16:17], v[72:73] neg_lo:[0,1] neg_hi:[0,1]
	v_pk_add_f32 v[68:69], v[76:77], v[68:69] neg_lo:[0,1] neg_hi:[0,1]
	v_pk_add_f32 v[18:19], v[18:19], v[14:15] neg_lo:[0,1] neg_hi:[0,1]
	v_pk_add_f32 v[30:31], v[30:31], v[26:27] neg_lo:[0,1] neg_hi:[0,1]
	v_pk_add_f32 v[26:27], v[34:35], v[28:29] op_sel:[0,1] op_sel_hi:[1,0] neg_hi:[0,1]
	v_pk_add_f32 v[14:15], v[4:5], v[74:75] op_sel:[0,1] op_sel_hi:[1,0] neg_hi:[0,1]
	v_pk_add_f32 v[76:77], v[64:65], v[70:71] op_sel:[0,1] op_sel_hi:[1,0] neg_hi:[0,1]
	v_pk_add_f32 v[72:73], v[22:23], v[24:25] op_sel:[0,1] op_sel_hi:[1,0] neg_hi:[0,1]
	v_pk_add_f32 v[28:29], v[34:35], v[28:29] op_sel:[0,1] op_sel_hi:[1,0] neg_lo:[0,1]
	v_pk_add_f32 v[4:5], v[4:5], v[74:75] op_sel:[0,1] op_sel_hi:[1,0] neg_lo:[0,1]
	v_pk_add_f32 v[70:71], v[64:65], v[70:71] op_sel:[0,1] op_sel_hi:[1,0] neg_lo:[0,1]
	v_pk_add_f32 v[22:23], v[22:23], v[24:25] op_sel:[0,1] op_sel_hi:[1,0] neg_lo:[0,1]
	v_pk_mul_f32 v[24:25], v[66:67], v[38:39] op_sel:[0,1] op_sel_hi:[1,1]
	v_pk_mul_f32 v[64:65], v[8:9], v[2:3] op_sel:[0,1] op_sel_hi:[1,1]
	v_pk_fma_f32 v[24:25], v[66:67], v[38:39], v[24:25] op_sel:[0,0,1] op_sel_hi:[1,0,0] neg_lo:[0,0,1]
	v_pk_mul_f32 v[66:67], v[20:21], v[0:1] op_sel:[0,1] op_sel_hi:[1,1]
	v_pk_fma_f32 v[64:65], v[8:9], v[2:3], v[64:65] op_sel:[0,0,1] op_sel_hi:[1,0,0] neg_lo:[0,0,1]
	v_pk_mul_f32 v[8:9], v[26:27], v[40:41] op_sel:[0,1] op_sel_hi:[1,1]
	v_pk_fma_f32 v[0:1], v[20:21], v[0:1], v[66:67] op_sel:[0,0,1] op_sel_hi:[1,0,0] neg_lo:[0,0,1]
	v_pk_mul_f32 v[66:67], v[14:15], v[42:43] op_sel:[0,1] op_sel_hi:[1,1]
	v_pk_fma_f32 v[40:41], v[26:27], v[40:41], v[8:9] op_sel:[0,0,1] op_sel_hi:[1,0,0] neg_lo:[0,0,1]
	v_pk_mul_f32 v[26:27], v[76:77], v[44:45] op_sel:[0,1] op_sel_hi:[1,1]
	v_pk_fma_f32 v[42:43], v[14:15], v[42:43], v[66:67] op_sel:[0,0,1] op_sel_hi:[1,0,0] neg_lo:[0,0,1]
; #define LAS __attribute__((address_space(3)))
; __device__ __forceinline__ f32x2 cmul(f32x2 a, f32x2 b) { return (f32x2){a.x * b.x - a.y * b.y, a.x * b.y + a.y * b.x}; }
; template <bool INV> __device__ __forceinline__ void bfly16(f32x2 (&x)[16], const LAS f32x2* TH, const LAS f32x2* TL, int tw) {
;     ...
;     if (!INV) { f32x2 p = W;
; #pragma unroll
;         for (int r = 1; r < 16; ++r) { x[4 * (r & 3) + (r >> 2)] = cmul(x[4 * (r & 3) + (r >> 2)], p); if (r < 15) p = cmul(p, W); } }
; }
; template <bool INV> __device__ __forceinline__ void bfly16_tab(f32x2 (&x)[16], const LAS f32x2* T, int tstride, int j) {
;     if (INV) {
; #pragma unroll
;         for (int q = 1; q < 16; ++q) { f32x2 p = T[q * tstride + j]; p.y = -p.y; x[q] = cmul(x[q], p); } }
;     dft16<INV>(x);
;     if (!INV) {
; #pragma unroll
;         for (int r = 1; r < 16; ++r) { const f32x2 p = T[r * tstride + j]; x[4 * (r & 3) + (r >> 2)] = cmul(x[4 * (r & 3) + (r >> 2)], p); } }
; }
; template <bool INV> __device__ __forceinline__ void pass16_s64(LAS f32x2* X, const LAS f32x2* TH, int base, int j) {
;     f32x2 x[16];
; #pragma unroll
;     for (int q = 0; q < 16; ++q) x[q] = X[base + q * 68];
;     bfly16_tab<INV>(x, TH - 2048, 64, j);
; template <bool INV> __device__ __forceinline__ void pass16(LAS f32x2* X, const LAS f32x2* TH, const LAS f32x2* TL, int base, int stride, int tw) {
;     ...
; #pragma unroll
;     for (int c = 0; c < 4; ++c)
; #pragma unroll
;         for (int d = 0; d < 4; ++d) X[base + (c + 4 * d) * stride] = x[4 * c + d];
	v_pk_mul_f32 v[66:67], v[72:73], v[46:47] op_sel:[0,1] op_sel_hi:[1,1]
	v_pk_fma_f32 v[44:45], v[76:77], v[44:45], v[26:27] op_sel:[0,0,1] op_sel_hi:[1,0,0] neg_lo:[0,0,1]
	v_pk_mul_f32 v[76:77], v[16:17], v[48:49] op_sel:[0,1] op_sel_hi:[1,1]
	v_pk_fma_f32 v[72:73], v[72:73], v[46:47], v[66:67] op_sel:[0,0,1] op_sel_hi:[1,0,0] neg_lo:[0,0,1]
	v_pk_mul_f32 v[66:67], v[68:69], v[50:51] op_sel:[0,1] op_sel_hi:[1,1]
	v_pk_fma_f32 v[16:17], v[16:17], v[48:49], v[76:77] op_sel:[0,0,1] op_sel_hi:[1,0,0] neg_lo:[0,0,1]
	v_pk_mul_f32 v[48:49], v[18:19], v[52:53] op_sel:[0,1] op_sel_hi:[1,1]
	v_pk_fma_f32 v[66:67], v[68:69], v[50:51], v[66:67] op_sel:[0,0,1] op_sel_hi:[1,0,0] neg_lo:[0,0,1]
	v_pk_mul_f32 v[50:51], v[30:31], v[54:55] op_sel:[0,1] op_sel_hi:[1,1]
	v_pk_fma_f32 v[18:19], v[18:19], v[52:53], v[48:49] op_sel:[0,0,1] op_sel_hi:[1,0,0] neg_lo:[0,0,1]
	v_pk_mul_f32 v[52:53], v[28:29], v[56:57] op_sel:[0,1] op_sel_hi:[1,1]
	v_pk_fma_f32 v[30:31], v[30:31], v[54:55], v[50:51] op_sel:[0,0,1] op_sel_hi:[1,0,0] neg_lo:[0,0,1]
	v_pk_mul_f32 v[50:51], v[4:5], v[58:59] op_sel:[0,1] op_sel_hi:[1,1]
	v_pk_fma_f32 v[56:57], v[28:29], v[56:57], v[52:53] op_sel:[0,0,1] op_sel_hi:[1,0,0] neg_lo:[0,0,1]
	v_pk_mul_f32 v[28:29], v[70:71], v[60:61] op_sel:[0,1] op_sel_hi:[1,1]
	v_pk_fma_f32 v[58:59], v[4:5], v[58:59], v[50:51] op_sel:[0,0,1] op_sel_hi:[1,0,0] neg_lo:[0,0,1]
	v_pk_mul_f32 v[4:5], v[22:23], v[62:63] op_sel:[0,1] op_sel_hi:[1,1]
	v_pk_fma_f32 v[70:71], v[70:71], v[60:61], v[28:29] op_sel:[0,0,1] op_sel_hi:[1,0,0] neg_lo:[0,0,1]
	v_pk_fma_f32 v[62:63], v[22:23], v[62:63], v[4:5] op_sel:[0,0,1] op_sel_hi:[1,0,0] neg_lo:[0,0,1]
	ds_write_b64 v176, v[78:79] offset:0
	ds_write_b64 v176, v[24:25] offset:8704
	ds_write_b64 v176, v[64:65] offset:17408
	ds_write_b64 v176, v[0:1] offset:26112
	ds_write_b64 v176, v[40:41] offset:34816
	ds_write_b64 v176, v[42:43] offset:43520
	ds_write_b64 v176, v[44:45] offset:52224
	ds_write_b64 v176, v[72:73] offset:60928
	ds_write_b64 v235, v[16:17] offset:0
	ds_write_b64 v235, v[66:67] offset:8704
	ds_write_b64 v235, v[18:19] offset:17408
	ds_write_b64 v235, v[30:31] offset:26112
	ds_write_b64 v235, v[56:57] offset:34816
	ds_write_b64 v235, v[58:59] offset:43520
	ds_write_b64 v235, v[70:71] offset:52224
	ds_write_b64 v235, v[62:63] offset:60928
	s_cbranch_scc1 .LBB0_944
	s_waitcnt lgkmcnt(0)
	s_barrier
	s_mov_b32 s0, 0
	s_mov_b64 s[8:9], -1
	ds_read2st64_b64 v[208:211], v139 offset0:1 offset1:2
	ds_read2st64_b64 v[204:207], v139 offset0:3 offset1:4
	ds_read2st64_b64 v[200:203], v139 offset0:5 offset1:6
	ds_read2st64_b64 v[196:199], v139 offset0:7 offset1:8
	ds_read2st64_b64 v[192:195], v139 offset0:9 offset1:10
	ds_read2st64_b64 v[188:191], v139 offset0:11 offset1:12
	ds_read2st64_b64 v[184:187], v139 offset0:13 offset1:14
	ds_read_b64 v[232:233], v139 offset:7680
.LBB0_946:
	v_add_u32_e32 v37, s0, v140
	v_lshrrev_b32_e32 v138, 6, v37
	v_mad_u32_u24 v176, v138, s77, v142
	ds_read_b64 v[0:1], v176 offset:0
	ds_read_b64 v[2:3], v176 offset:4352
	ds_read_b64 v[4:5], v176 offset:544
	ds_read_b64 v[6:7], v176 offset:4896
	ds_read_b64 v[8:9], v176 offset:1088
	ds_read_b64 v[10:11], v176 offset:5440
	ds_read_b64 v[12:13], v176 offset:1632
	ds_read_b64 v[14:15], v176 offset:5984
	ds_read_b64 v[16:17], v176 offset:2176
	ds_read_b64 v[18:19], v176 offset:6528
	ds_read_b64 v[20:21], v176 offset:2720
	ds_read_b64 v[22:23], v176 offset:7072
	ds_read_b64 v[24:25], v176 offset:3264
	ds_read_b64 v[26:27], v176 offset:7616
	ds_read_b64 v[28:29], v176 offset:3808
	ds_read_b64 v[30:31], v176 offset:8160
	s_cmp_eq_u32 s0, 0
	s_movk_i32 s0, 0x200
	s_mov_b64 s[8:9], 0
	s_waitcnt lgkmcnt(14)
	v_pk_add_f32 v[32:33], v[0:1], v[2:3]
	s_waitcnt lgkmcnt(12)
	v_pk_add_f32 v[34:35], v[4:5], v[6:7]
	s_waitcnt lgkmcnt(10)
	v_pk_add_f32 v[38:39], v[8:9], v[10:11]
	s_waitcnt lgkmcnt(8)
	v_pk_add_f32 v[40:41], v[12:13], v[14:15]
	v_pk_add_f32 v[0:1], v[0:1], v[2:3] neg_lo:[0,1] neg_hi:[0,1]
	v_pk_add_f32 v[6:7], v[4:5], v[6:7] neg_lo:[0,1] neg_hi:[0,1]
	v_pk_add_f32 v[10:11], v[8:9], v[10:11] neg_lo:[0,1] neg_hi:[0,1]
	v_pk_add_f32 v[14:15], v[12:13], v[14:15] neg_lo:[0,1] neg_hi:[0,1]
	s_waitcnt lgkmcnt(6)
	v_pk_add_f32 v[12:13], v[16:17], v[18:19]
	s_waitcnt lgkmcnt(4)
	v_pk_add_f32 v[8:9], v[20:21], v[22:23]
	s_waitcnt lgkmcnt(2)
	v_pk_add_f32 v[4:5], v[24:25], v[26:27]
	s_waitcnt lgkmcnt(0)
; #define LAS __attribute__((address_space(3)))
; __device__ __forceinline__ f32x2 cmul(f32x2 a, f32x2 b) { return (f32x2){a.x * b.x - a.y * b.y, a.x * b.y + a.y * b.x}; }
; __device__ __forceinline__ f32x2 tw32k(const LAS f32x2* TH, const LAS f32x2* TL, int n) { return cmul(TH[n >> 7], TL[n & 127]); }
; template <bool INV> __device__ __forceinline__ void dft16(f32x2 (&x)[16]) {
; #pragma unroll
;     for (int b = 0; b < 4; ++b) r4<INV>(x[b], x[4 + b], x[8 + b], x[12 + b]);
;     const float sg = INV ? -1.f : 1.f;
;     const f32x2 W1 = {0.92387953251f, -0.38268343236f * sg}, W2 = {0.70710678118f, -0.70710678118f * sg}, W3 = {0.38268343236f, -0.92387953251f * sg},
;                 W4 = {0.f, -1.f * sg}, W6 = {-0.70710678118f, -0.70710678118f * sg}, W9 = {-0.92387953251f, 0.38268343236f * sg};
;     x[5] = cmul(x[5], W1); x[9] = cmul(x[9], W2); x[13] = cmul(x[13], W3);
;     x[6] = cmul(x[6], W2); x[10] = cmul(x[10], W4); x[14] = cmul(x[14], W6);
;     x[7] = cmul(x[7], W3); x[11] = cmul(x[11], W6); x[15] = cmul(x[15], W9);
; #pragma unroll
;     for (int c = 0; c < 4; ++c) r4<INV>(x[4 * c], x[4 * c + 1], x[4 * c + 2], x[4 * c + 3]);
; }
; template <bool INV> __device__ __forceinline__ void bfly16(f32x2 (&x)[16], const LAS f32x2* TH, const LAS f32x2* TL, int tw) {
;     f32x2 W = tw32k(TH, TL, tw); if (INV) W.y = -W.y;
;     if (INV) { f32x2 p = W;
; #pragma unroll
;         for (int q = 1; q < 16; ++q) { x[q] = cmul(x[q], p); if (q < 15) p = cmul(p, W); } }
;     dft16<INV>(x);
;     if (!INV) { f32x2 p = W;
; #pragma unroll
;         for (int r = 1; r < 16; ++r) { x[4 * (r & 3) + (r >> 2)] = cmul(x[4 * (r & 3) + (r >> 2)], p); if (r < 15) p = cmul(p, W); } }
; }
; template <bool INV> __device__ __forceinline__ void bfly16_tab(f32x2 (&x)[16], const LAS f32x2* T, int tstride, int j) {
;     if (INV) {
; #pragma unroll
;         for (int q = 1; q < 16; ++q) { f32x2 p = T[q * tstride + j]; p.y = -p.y; x[q] = cmul(x[q], p); } }
;     dft16<INV>(x);
;     if (!INV) {
; #pragma unroll
;         for (int r = 1; r < 16; ++r) { const f32x2 p = T[r * tstride + j]; x[4 * (r & 3) + (r >> 2)] = cmul(x[4 * (r & 3) + (r >> 2)], p); } }
; }
	v_pk_add_f32 v[2:3], v[28:29], v[30:31]
	v_pk_add_f32 v[18:19], v[16:17], v[18:19] neg_lo:[0,1] neg_hi:[0,1]
	v_pk_add_f32 v[20:21], v[20:21], v[22:23] neg_lo:[0,1] neg_hi:[0,1]
	v_pk_add_f32 v[24:25], v[24:25], v[26:27] neg_lo:[0,1] neg_hi:[0,1]
	v_pk_add_f32 v[30:31], v[28:29], v[30:31] neg_lo:[0,1] neg_hi:[0,1]
	v_pk_add_f32 v[28:29], v[32:33], v[12:13]
	v_pk_add_f32 v[26:27], v[34:35], v[8:9]
	v_pk_add_f32 v[22:23], v[38:39], v[4:5]
	v_pk_add_f32 v[16:17], v[40:41], v[2:3]
	v_pk_add_f32 v[32:33], v[32:33], v[12:13] neg_lo:[0,1] neg_hi:[0,1]
	v_pk_add_f32 v[34:35], v[34:35], v[8:9] neg_lo:[0,1] neg_hi:[0,1]
	v_pk_add_f32 v[4:5], v[38:39], v[4:5] neg_lo:[0,1] neg_hi:[0,1]
	v_pk_add_f32 v[2:3], v[40:41], v[2:3] neg_lo:[0,1] neg_hi:[0,1]
	v_pk_add_f32 v[40:41], v[0:1], v[18:19] op_sel:[0,1] op_sel_hi:[1,0] neg_hi:[0,1]
	v_pk_add_f32 v[38:39], v[6:7], v[20:21] op_sel:[0,1] op_sel_hi:[1,0] neg_hi:[0,1]
	v_pk_add_f32 v[8:9], v[10:11], v[24:25] op_sel:[0,1] op_sel_hi:[1,0] neg_hi:[0,1]
	v_pk_add_f32 v[12:13], v[14:15], v[30:31] op_sel:[0,1] op_sel_hi:[1,0] neg_hi:[0,1]
	v_pk_add_f32 v[0:1], v[0:1], v[18:19] op_sel:[0,1] op_sel_hi:[1,0] neg_lo:[0,1]
	v_pk_add_f32 v[20:21], v[6:7], v[20:21] op_sel:[0,1] op_sel_hi:[1,0] neg_lo:[0,1]
	v_pk_add_f32 v[24:25], v[10:11], v[24:25] op_sel:[0,1] op_sel_hi:[1,0] neg_lo:[0,1]
	v_pk_add_f32 v[14:15], v[14:15], v[30:31] op_sel:[0,1] op_sel_hi:[1,0] neg_lo:[0,1]
	v_pk_mul_f32 v[30:31], v[38:39], s[70:71] op_sel_hi:[1,0]
	v_pk_mul_f32 v[10:11], v[34:35], s[72:73] op_sel_hi:[1,0]
	v_pk_mul_f32 v[6:7], v[20:21], s[64:65] op_sel_hi:[1,0]
	v_pk_mul_f32 v[18:19], v[8:9], s[72:73] op_sel_hi:[1,0]
	v_pk_mul_f32 v[42:43], v[24:25], s[72:73] op_sel_hi:[1,0]
	v_pk_mul_f32 v[44:45], v[12:13], s[64:65] op_sel_hi:[1,0]
	v_pk_mul_f32 v[46:47], v[2:3], s[72:73] op_sel_hi:[1,0]
	v_pk_mul_f32 v[48:49], v[14:15], s[82:83] op_sel_hi:[1,0]
	v_pk_fma_f32 v[38:39], v[38:39], s[44:45], v[30:31] op_sel:[0,0,1] op_sel_hi:[1,0,0] neg_lo:[0,0,1]
	v_pk_fma_f32 v[10:11], v[34:35], s[76:77], v[10:11] op_sel:[0,0,1] op_sel_hi:[1,0,0] neg_lo:[0,0,1]
	v_pk_fma_f32 v[6:7], v[20:21], s[82:83], v[6:7] op_sel:[0,0,1] op_sel_hi:[1,0,0] neg_lo:[0,0,1]
	v_pk_fma_f32 v[8:9], v[8:9], s[76:77], v[18:19] op_sel:[0,0,1] op_sel_hi:[1,0,0] neg_lo:[0,0,1]
	v_pk_fma_f32 v[42:43], v[24:25], s[72:73], v[42:43] op_sel:[0,0,1] op_sel_hi:[1,0,0] neg_lo:[0,0,1]
	v_pk_fma_f32 v[12:13], v[12:13], s[82:83], v[44:45] op_sel:[0,0,1] op_sel_hi:[1,0,0] neg_lo:[0,0,1]
	v_pk_fma_f32 v[2:3], v[2:3], s[72:73], v[46:47] op_sel:[0,0,1] op_sel_hi:[1,0,0] neg_lo:[0,0,1]
	v_pk_fma_f32 v[48:49], v[14:15], s[64:65], v[48:49] op_sel:[0,0,1] op_sel_hi:[1,0,0] neg_lo:[0,0,1]
	v_pk_add_f32 v[14:15], v[28:29], v[22:23]
	v_pk_add_f32 v[46:47], v[40:41], v[8:9]
	v_pk_add_f32 v[44:45], v[32:33], v[4:5] op_sel:[0,1] op_sel_hi:[1,0] neg_hi:[0,1]
	v_pk_add_f32 v[24:25], v[0:1], v[42:43]
	v_pk_add_f32 v[22:23], v[28:29], v[22:23] neg_lo:[0,1] neg_hi:[0,1]
	v_pk_add_f32 v[8:9], v[40:41], v[8:9] neg_lo:[0,1] neg_hi:[0,1]
	v_pk_add_f32 v[4:5], v[32:33], v[4:5] op_sel:[0,1] op_sel_hi:[1,0] neg_lo:[0,1]
	v_pk_add_f32 v[42:43], v[0:1], v[42:43] neg_lo:[0,1] neg_hi:[0,1]
	v_pk_add_f32 v[0:1], v[26:27], v[16:17]
	v_pk_add_f32 v[32:33], v[38:39], v[12:13]
	v_pk_add_f32 v[40:41], v[10:11], v[2:3]
	v_pk_add_f32 v[28:29], v[6:7], v[48:49]
	v_pk_add_f32 v[26:27], v[26:27], v[16:17] neg_lo:[0,1] neg_hi:[0,1]
	v_pk_add_f32 v[38:39], v[38:39], v[12:13] neg_lo:[0,1] neg_hi:[0,1]
	v_pk_add_f32 v[10:11], v[10:11], v[2:3] neg_lo:[0,1] neg_hi:[0,1]
	v_pk_add_f32 v[6:7], v[6:7], v[48:49] neg_lo:[0,1] neg_hi:[0,1]
	v_pk_add_f32 v[48:49], v[14:15], v[0:1]
	v_pk_add_f32 v[2:3], v[46:47], v[32:33]
	v_pk_add_f32 v[12:13], v[44:45], v[40:41]
	v_pk_add_f32 v[16:17], v[24:25], v[28:29]
	v_pk_add_f32 v[0:1], v[14:15], v[0:1] neg_lo:[0,1] neg_hi:[0,1]
	v_pk_add_f32 v[32:33], v[46:47], v[32:33] neg_lo:[0,1] neg_hi:[0,1]
	v_pk_add_f32 v[40:41], v[44:45], v[40:41] neg_lo:[0,1] neg_hi:[0,1]
	v_pk_add_f32 v[24:25], v[24:25], v[28:29] neg_lo:[0,1] neg_hi:[0,1]
	v_pk_add_f32 v[28:29], v[22:23], v[26:27] op_sel:[0,1] op_sel_hi:[1,0] neg_hi:[0,1]
	v_pk_add_f32 v[44:45], v[8:9], v[38:39] op_sel:[0,1] op_sel_hi:[1,0] neg_hi:[0,1]
	v_pk_add_f32 v[46:47], v[4:5], v[10:11] op_sel:[0,1] op_sel_hi:[1,0] neg_hi:[0,1]
	v_pk_add_f32 v[14:15], v[42:43], v[6:7] op_sel:[0,1] op_sel_hi:[1,0] neg_hi:[0,1]
	v_pk_add_f32 v[26:27], v[22:23], v[26:27] op_sel:[0,1] op_sel_hi:[1,0] neg_lo:[0,1]
	v_pk_add_f32 v[38:39], v[8:9], v[38:39] op_sel:[0,1] op_sel_hi:[1,0] neg_lo:[0,1]
	v_pk_add_f32 v[4:5], v[4:5], v[10:11] op_sel:[0,1] op_sel_hi:[1,0] neg_lo:[0,1]
	v_pk_add_f32 v[42:43], v[42:43], v[6:7] op_sel:[0,1] op_sel_hi:[1,0] neg_lo:[0,1]
	v_pk_mul_f32 v[6:7], v[2:3], v[208:209] op_sel:[0,1] op_sel_hi:[1,1]
	v_pk_mul_f32 v[10:11], v[12:13], v[210:211] op_sel:[0,1] op_sel_hi:[1,1]
	v_pk_fma_f32 v[2:3], v[2:3], v[208:209], v[6:7] op_sel:[0,0,1] op_sel_hi:[1,0,0] neg_lo:[0,0,1]
	v_pk_mul_f32 v[6:7], v[16:17], v[204:205] op_sel:[0,1] op_sel_hi:[1,1]
	v_pk_fma_f32 v[10:11], v[12:13], v[210:211], v[10:11] op_sel:[0,0,1] op_sel_hi:[1,0,0] neg_lo:[0,0,1]
	v_pk_mul_f32 v[12:13], v[28:29], v[206:207] op_sel:[0,1] op_sel_hi:[1,1]
	v_pk_fma_f32 v[6:7], v[16:17], v[204:205], v[6:7] op_sel:[0,0,1] op_sel_hi:[1,0,0] neg_lo:[0,0,1]
	v_pk_mul_f32 v[16:17], v[44:45], v[200:201] op_sel:[0,1] op_sel_hi:[1,1]
	v_pk_fma_f32 v[12:13], v[28:29], v[206:207], v[12:13] op_sel:[0,0,1] op_sel_hi:[1,0,0] neg_lo:[0,0,1]
	v_pk_mul_f32 v[28:29], v[46:47], v[202:203] op_sel:[0,1] op_sel_hi:[1,1]
	v_pk_fma_f32 v[16:17], v[44:45], v[200:201], v[16:17] op_sel:[0,0,1] op_sel_hi:[1,0,0] neg_lo:[0,0,1]
; #define LAS __attribute__((address_space(3)))
; __device__ __forceinline__ f32x2 cmul(f32x2 a, f32x2 b) { return (f32x2){a.x * b.x - a.y * b.y, a.x * b.y + a.y * b.x}; }
; template <bool INV> __device__ __forceinline__ void bfly16_tab(f32x2 (&x)[16], const LAS f32x2* T, int tstride, int j) {
;     if (INV) {
; #pragma unroll
;         for (int q = 1; q < 16; ++q) { f32x2 p = T[q * tstride + j]; p.y = -p.y; x[q] = cmul(x[q], p); } }
;     dft16<INV>(x);
;     if (!INV) {
; #pragma unroll
;         for (int r = 1; r < 16; ++r) { const f32x2 p = T[r * tstride + j]; x[4 * (r & 3) + (r >> 2)] = cmul(x[4 * (r & 3) + (r >> 2)], p); } }
; }
; template <bool INV> __device__ __forceinline__ void pass16_s64(LAS f32x2* X, const LAS f32x2* TH, int base, int j) {
;     f32x2 x[16];
; #pragma unroll
;     for (int q = 0; q < 16; ++q) x[q] = X[base + q * 68];
;     bfly16_tab<INV>(x, TH - 2048, 64, j);
; #pragma unroll
;     for (int c = 0; c < 4; ++c)
; #pragma unroll
;         for (int d = 0; d < 4; ++d) X[base + (c + 4 * d) * 68] = x[4 * c + d];
; }
; template <bool INV> __device__ __forceinline__ void pass16(LAS f32x2* X, const LAS f32x2* TH, const LAS f32x2* TL, int base, int stride, int tw) {
;     f32x2 x[16];
; #pragma unroll
;     for (int q = 0; q < 16; ++q) x[q] = X[base + q * stride];
;     bfly16<INV>(x, TH, TL, tw);
; #pragma unroll
;     for (int c = 0; c < 4; ++c)
; #pragma unroll
;         for (int d = 0; d < 4; ++d) X[base + (c + 4 * d) * stride] = x[4 * c + d];
; }
; template <bool INV> __device__ __forceinline__ void pass16_s4(LAS f32x2* X, const LAS f32x2* TH, const LAS f32x2* TL, int tid) {
; #pragma unroll 1
;     for (int s = 0; s < 2; ++s) {
;         const int b = tid + NTHR * s, blk = b >> 2, jj = b & 3;
;         LAS f32x2* P = X + blk * 68 + jj;
;         f32x2 x[16];
; #pragma unroll
;         for (int q = 0; q < 16; ++q) x[q] = P[4 * q];
;         bfly16_tab<INV>(x, TH - 1024, 4, jj);
; #pragma unroll
;         for (int c = 0; c < 4; ++c)
; #pragma unroll
;             for (int d = 0; d < 4; ++d) P[4 * (c + 4 * d)] = x[4 * c + d];
;     }
; }
	v_pk_mul_f32 v[44:45], v[14:15], v[196:197] op_sel:[0,1] op_sel_hi:[1,1]
	v_pk_fma_f32 v[28:29], v[46:47], v[202:203], v[28:29] op_sel:[0,0,1] op_sel_hi:[1,0,0] neg_lo:[0,0,1]
	v_pk_mul_f32 v[46:47], v[0:1], v[198:199] op_sel:[0,1] op_sel_hi:[1,1]
	v_pk_fma_f32 v[14:15], v[14:15], v[196:197], v[44:45] op_sel:[0,0,1] op_sel_hi:[1,0,0] neg_lo:[0,0,1]
	v_pk_mul_f32 v[44:45], v[32:33], v[192:193] op_sel:[0,1] op_sel_hi:[1,1]
	v_pk_fma_f32 v[46:47], v[0:1], v[198:199], v[46:47] op_sel:[0,0,1] op_sel_hi:[1,0,0] neg_lo:[0,0,1]
	v_pk_mul_f32 v[0:1], v[40:41], v[194:195] op_sel:[0,1] op_sel_hi:[1,1]
	v_pk_fma_f32 v[44:45], v[32:33], v[192:193], v[44:45] op_sel:[0,0,1] op_sel_hi:[1,0,0] neg_lo:[0,0,1]
	v_pk_mul_f32 v[32:33], v[24:25], v[188:189] op_sel:[0,1] op_sel_hi:[1,1]
	v_pk_fma_f32 v[0:1], v[40:41], v[194:195], v[0:1] op_sel:[0,0,1] op_sel_hi:[1,0,0] neg_lo:[0,0,1]
	v_pk_mul_f32 v[40:41], v[26:27], v[190:191] op_sel:[0,1] op_sel_hi:[1,1]
	v_pk_fma_f32 v[32:33], v[24:25], v[188:189], v[32:33] op_sel:[0,0,1] op_sel_hi:[1,0,0] neg_lo:[0,0,1]
	v_pk_mul_f32 v[24:25], v[38:39], v[184:185] op_sel:[0,1] op_sel_hi:[1,1]
	v_pk_fma_f32 v[40:41], v[26:27], v[190:191], v[40:41] op_sel:[0,0,1] op_sel_hi:[1,0,0] neg_lo:[0,0,1]
	v_pk_mul_f32 v[26:27], v[4:5], v[186:187] op_sel:[0,1] op_sel_hi:[1,1]
	v_pk_fma_f32 v[38:39], v[38:39], v[184:185], v[24:25] op_sel:[0,0,1] op_sel_hi:[1,0,0] neg_lo:[0,0,1]
	v_pk_mul_f32 v[24:25], v[42:43], v[232:233] op_sel:[0,1] op_sel_hi:[1,1]
	v_pk_fma_f32 v[26:27], v[4:5], v[186:187], v[26:27] op_sel:[0,0,1] op_sel_hi:[1,0,0] neg_lo:[0,0,1]
	v_pk_fma_f32 v[42:43], v[42:43], v[232:233], v[24:25] op_sel:[0,0,1] op_sel_hi:[1,0,0] neg_lo:[0,0,1]
	ds_write_b64 v176, v[48:49] offset:0
	ds_write_b64 v176, v[2:3] offset:544
	ds_write_b64 v176, v[10:11] offset:1088
	ds_write_b64 v176, v[6:7] offset:1632
	ds_write_b64 v176, v[12:13] offset:2176
	ds_write_b64 v176, v[16:17] offset:2720
	ds_write_b64 v176, v[28:29] offset:3264
	ds_write_b64 v176, v[14:15] offset:3808
	ds_write_b64 v176, v[46:47] offset:4352
	ds_write_b64 v176, v[44:45] offset:4896
	ds_write_b64 v176, v[0:1] offset:5440
	ds_write_b64 v176, v[32:33] offset:5984
	ds_write_b64 v176, v[40:41] offset:6528
	ds_write_b64 v176, v[38:39] offset:7072
	ds_write_b64 v176, v[26:27] offset:7616
	ds_write_b64 v176, v[42:43] offset:8160
	s_cbranch_scc1 .LBB0_946
	s_waitcnt lgkmcnt(0)
	s_barrier
	s_mov_b32 s0, 0
	s_mov_b64 s[8:9], -1
	ds_read2_b64 v[232:235], v141 offset0:4 offset1:8
	ds_read2_b64 v[208:211], v141 offset0:12 offset1:16
	ds_read2_b64 v[204:207], v141 offset0:20 offset1:24
	ds_read2_b64 v[200:203], v141 offset0:28 offset1:32
	ds_read2_b64 v[196:199], v141 offset0:36 offset1:40
	ds_read2_b64 v[192:195], v141 offset0:44 offset1:48
	ds_read2_b64 v[188:191], v141 offset0:52 offset1:56
	ds_read_b64 v[186:187], v141 offset:480
.LBB0_948:
	v_add_u32_e32 v37, s0, v140
	v_lshrrev_b32_e32 v138, 2, v37
	v_mad_u32_u24 v176, v138, s43, v144
	ds_read_b64 v[0:1], v176 offset:0
	ds_read_b64 v[2:3], v176 offset:256
	ds_read_b64 v[4:5], v176 offset:32
	ds_read_b64 v[6:7], v176 offset:288
	ds_read_b64 v[8:9], v176 offset:64
	ds_read_b64 v[10:11], v176 offset:320
	ds_read_b64 v[12:13], v176 offset:96
	ds_read_b64 v[14:15], v176 offset:352
	ds_read_b64 v[16:17], v176 offset:128
	ds_read_b64 v[18:19], v176 offset:384
	ds_read_b64 v[20:21], v176 offset:160
	ds_read_b64 v[22:23], v176 offset:416
	ds_read_b64 v[24:25], v176 offset:192
	ds_read_b64 v[26:27], v176 offset:448
	ds_read_b64 v[28:29], v176 offset:224
	ds_read_b64 v[30:31], v176 offset:480
	s_cmp_eq_u32 s0, 0
	s_movk_i32 s0, 0x200
	s_mov_b64 s[8:9], 0
	s_waitcnt lgkmcnt(14)
	v_pk_add_f32 v[32:33], v[0:1], v[2:3]
	s_waitcnt lgkmcnt(12)
	v_pk_add_f32 v[34:35], v[4:5], v[6:7]
	s_waitcnt lgkmcnt(10)
	v_pk_add_f32 v[38:39], v[8:9], v[10:11]
	s_waitcnt lgkmcnt(8)
	v_pk_add_f32 v[40:41], v[12:13], v[14:15]
	v_pk_add_f32 v[0:1], v[0:1], v[2:3] neg_lo:[0,1] neg_hi:[0,1]
	v_pk_add_f32 v[4:5], v[4:5], v[6:7] neg_lo:[0,1] neg_hi:[0,1]
	v_pk_add_f32 v[10:11], v[8:9], v[10:11] neg_lo:[0,1] neg_hi:[0,1]
	v_pk_add_f32 v[14:15], v[12:13], v[14:15] neg_lo:[0,1] neg_hi:[0,1]
	s_waitcnt lgkmcnt(6)
	v_pk_add_f32 v[12:13], v[16:17], v[18:19]
	s_waitcnt lgkmcnt(4)
	v_pk_add_f32 v[8:9], v[20:21], v[22:23]
	s_waitcnt lgkmcnt(2)
	v_pk_add_f32 v[6:7], v[24:25], v[26:27]
	s_waitcnt lgkmcnt(0)
; __device__ __forceinline__ f32x2 cmul(f32x2 a, f32x2 b) { return (f32x2){a.x * b.x - a.y * b.y, a.x * b.y + a.y * b.x}; }
; template <bool INV> __device__ __forceinline__ void dft16(f32x2 (&x)[16]) {
; #pragma unroll
;     for (int b = 0; b < 4; ++b) r4<INV>(x[b], x[4 + b], x[8 + b], x[12 + b]);
;     const float sg = INV ? -1.f : 1.f;
;     const f32x2 W1 = {0.92387953251f, -0.38268343236f * sg}, W2 = {0.70710678118f, -0.70710678118f * sg}, W3 = {0.38268343236f, -0.92387953251f * sg},
;                 W4 = {0.f, -1.f * sg}, W6 = {-0.70710678118f, -0.70710678118f * sg}, W9 = {-0.92387953251f, 0.38268343236f * sg};
;     x[5] = cmul(x[5], W1); x[9] = cmul(x[9], W2); x[13] = cmul(x[13], W3);
;     x[6] = cmul(x[6], W2); x[10] = cmul(x[10], W4); x[14] = cmul(x[14], W6);
;     x[7] = cmul(x[7], W3); x[11] = cmul(x[11], W6); x[15] = cmul(x[15], W9);
; #pragma unroll
;     for (int c = 0; c < 4; ++c) r4<INV>(x[4 * c], x[4 * c + 1], x[4 * c + 2], x[4 * c + 3]);
; }
	v_pk_add_f32 v[2:3], v[28:29], v[30:31]
	v_pk_add_f32 v[16:17], v[16:17], v[18:19] neg_lo:[0,1] neg_hi:[0,1]
	v_pk_add_f32 v[22:23], v[20:21], v[22:23] neg_lo:[0,1] neg_hi:[0,1]
	v_pk_add_f32 v[24:25], v[24:25], v[26:27] neg_lo:[0,1] neg_hi:[0,1]
	v_pk_add_f32 v[28:29], v[28:29], v[30:31] neg_lo:[0,1] neg_hi:[0,1]
	v_pk_add_f32 v[30:31], v[32:33], v[12:13]
	v_pk_add_f32 v[26:27], v[34:35], v[8:9]
	v_pk_add_f32 v[20:21], v[38:39], v[6:7]
	v_pk_add_f32 v[18:19], v[40:41], v[2:3]
	v_pk_add_f32 v[32:33], v[32:33], v[12:13] neg_lo:[0,1] neg_hi:[0,1]
	v_pk_add_f32 v[8:9], v[34:35], v[8:9] neg_lo:[0,1] neg_hi:[0,1]
	v_pk_add_f32 v[38:39], v[38:39], v[6:7] neg_lo:[0,1] neg_hi:[0,1]
	v_pk_add_f32 v[40:41], v[40:41], v[2:3] neg_lo:[0,1] neg_hi:[0,1]
	v_pk_add_f32 v[2:3], v[0:1], v[16:17] op_sel:[0,1] op_sel_hi:[1,0] neg_hi:[0,1]
	v_pk_add_f32 v[6:7], v[4:5], v[22:23] op_sel:[0,1] op_sel_hi:[1,0] neg_hi:[0,1]
	v_pk_add_f32 v[34:35], v[10:11], v[24:25] op_sel:[0,1] op_sel_hi:[1,0] neg_hi:[0,1]
	v_pk_add_f32 v[12:13], v[14:15], v[28:29] op_sel:[0,1] op_sel_hi:[1,0] neg_hi:[0,1]
	v_pk_add_f32 v[0:1], v[0:1], v[16:17] op_sel:[0,1] op_sel_hi:[1,0] neg_lo:[0,1]
	v_pk_add_f32 v[22:23], v[4:5], v[22:23] op_sel:[0,1] op_sel_hi:[1,0] neg_lo:[0,1]
	v_pk_add_f32 v[10:11], v[10:11], v[24:25] op_sel:[0,1] op_sel_hi:[1,0] neg_lo:[0,1]
	v_pk_add_f32 v[28:29], v[14:15], v[28:29] op_sel:[0,1] op_sel_hi:[1,0] neg_lo:[0,1]
	v_pk_mul_f32 v[14:15], v[6:7], s[70:71] op_sel_hi:[1,0]
	v_pk_mul_f32 v[24:25], v[8:9], s[72:73] op_sel_hi:[1,0]
	v_pk_mul_f32 v[4:5], v[22:23], s[64:65] op_sel_hi:[1,0]
	v_pk_mul_f32 v[16:17], v[34:35], s[72:73] op_sel_hi:[1,0]
	v_pk_mul_f32 v[42:43], v[10:11], s[72:73] op_sel_hi:[1,0]
	v_pk_mul_f32 v[44:45], v[12:13], s[64:65] op_sel_hi:[1,0]
	v_pk_mul_f32 v[46:47], v[40:41], s[72:73] op_sel_hi:[1,0]
	v_pk_mul_f32 v[48:49], v[28:29], s[82:83] op_sel_hi:[1,0]
	v_pk_fma_f32 v[14:15], v[6:7], s[44:45], v[14:15] op_sel:[0,0,1] op_sel_hi:[1,0,0] neg_lo:[0,0,1]
	v_pk_fma_f32 v[8:9], v[8:9], s[76:77], v[24:25] op_sel:[0,0,1] op_sel_hi:[1,0,0] neg_lo:[0,0,1]
	v_pk_fma_f32 v[4:5], v[22:23], s[82:83], v[4:5] op_sel:[0,0,1] op_sel_hi:[1,0,0] neg_lo:[0,0,1]
	v_pk_fma_f32 v[34:35], v[34:35], s[76:77], v[16:17] op_sel:[0,0,1] op_sel_hi:[1,0,0] neg_lo:[0,0,1]
	v_pk_fma_f32 v[42:43], v[10:11], s[72:73], v[42:43] op_sel:[0,0,1] op_sel_hi:[1,0,0] neg_lo:[0,0,1]
	v_pk_fma_f32 v[44:45], v[12:13], s[82:83], v[44:45] op_sel:[0,0,1] op_sel_hi:[1,0,0] neg_lo:[0,0,1]
	v_pk_fma_f32 v[46:47], v[40:41], s[72:73], v[46:47] op_sel:[0,0,1] op_sel_hi:[1,0,0] neg_lo:[0,0,1]
	v_pk_fma_f32 v[28:29], v[28:29], s[64:65], v[48:49] op_sel:[0,0,1] op_sel_hi:[1,0,0] neg_lo:[0,0,1]
	v_pk_add_f32 v[48:49], v[30:31], v[20:21]
	v_pk_add_f32 v[40:41], v[2:3], v[34:35]
	v_pk_add_f32 v[12:13], v[32:33], v[38:39] op_sel:[0,1] op_sel_hi:[1,0] neg_hi:[0,1]
	v_pk_add_f32 v[10:11], v[0:1], v[42:43]
	v_pk_add_f32 v[30:31], v[30:31], v[20:21] neg_lo:[0,1] neg_hi:[0,1]
	v_pk_add_f32 v[34:35], v[2:3], v[34:35] neg_lo:[0,1] neg_hi:[0,1]
	v_pk_add_f32 v[32:33], v[32:33], v[38:39] op_sel:[0,1] op_sel_hi:[1,0] neg_lo:[0,1]
	v_pk_add_f32 v[0:1], v[0:1], v[42:43] neg_lo:[0,1] neg_hi:[0,1]
	v_pk_add_f32 v[42:43], v[26:27], v[18:19]
	v_pk_add_f32 v[38:39], v[14:15], v[44:45]
	v_pk_add_f32 v[2:3], v[8:9], v[46:47]
	v_pk_add_f32 v[20:21], v[4:5], v[28:29]
	v_pk_add_f32 v[26:27], v[26:27], v[18:19] neg_lo:[0,1] neg_hi:[0,1]
	v_pk_add_f32 v[44:45], v[14:15], v[44:45] neg_lo:[0,1] neg_hi:[0,1]
	v_pk_add_f32 v[46:47], v[8:9], v[46:47] neg_lo:[0,1] neg_hi:[0,1]
	v_pk_add_f32 v[28:29], v[4:5], v[28:29] neg_lo:[0,1] neg_hi:[0,1]
	v_pk_add_f32 v[4:5], v[48:49], v[42:43]
	v_pk_add_f32 v[8:9], v[40:41], v[38:39]
	v_pk_add_f32 v[14:15], v[12:13], v[2:3]
	v_pk_add_f32 v[18:19], v[10:11], v[20:21]
	v_pk_add_f32 v[42:43], v[48:49], v[42:43] neg_lo:[0,1] neg_hi:[0,1]
	v_pk_add_f32 v[40:41], v[40:41], v[38:39] neg_lo:[0,1] neg_hi:[0,1]
	v_pk_add_f32 v[2:3], v[12:13], v[2:3] neg_lo:[0,1] neg_hi:[0,1]
	v_pk_add_f32 v[10:11], v[10:11], v[20:21] neg_lo:[0,1] neg_hi:[0,1]
; #define LAS __attribute__((address_space(3)))
; __device__ __forceinline__ f32x2 cmul(f32x2 a, f32x2 b) { return (f32x2){a.x * b.x - a.y * b.y, a.x * b.y + a.y * b.x}; }
; template <bool INV> __device__ __forceinline__ void bfly16_tab(f32x2 (&x)[16], const LAS f32x2* T, int tstride, int j) {
;     if (INV) {
; #pragma unroll
;         for (int q = 1; q < 16; ++q) { f32x2 p = T[q * tstride + j]; p.y = -p.y; x[q] = cmul(x[q], p); } }
;     dft16<INV>(x);
;     if (!INV) {
; #pragma unroll
;         for (int r = 1; r < 16; ++r) { const f32x2 p = T[r * tstride + j]; x[4 * (r & 3) + (r >> 2)] = cmul(x[4 * (r & 3) + (r >> 2)], p); } }
; }
; template <bool INV> __device__ __forceinline__ void pass16_s4(LAS f32x2* X, const LAS f32x2* TH, const LAS f32x2* TL, int tid) {
; #pragma unroll 1
;     for (int s = 0; s < 2; ++s) {
;         const int b = tid + NTHR * s, blk = b >> 2, jj = b & 3;
;         LAS f32x2* P = X + blk * 68 + jj;
;         f32x2 x[16];
; #pragma unroll
;         for (int q = 0; q < 16; ++q) x[q] = P[4 * q];
;         bfly16_tab<INV>(x, TH - 1024, 4, jj);
; #pragma unroll
;         for (int c = 0; c < 4; ++c)
; #pragma unroll
;             for (int d = 0; d < 4; ++d) P[4 * (c + 4 * d)] = x[4 * c + d];
;     }
; }
	v_pk_add_f32 v[20:21], v[30:31], v[26:27] op_sel:[0,1] op_sel_hi:[1,0] neg_hi:[0,1]
	v_pk_add_f32 v[12:13], v[34:35], v[44:45] op_sel:[0,1] op_sel_hi:[1,0] neg_hi:[0,1]
	v_pk_add_f32 v[38:39], v[32:33], v[46:47] op_sel:[0,1] op_sel_hi:[1,0] neg_hi:[0,1]
	v_pk_add_f32 v[48:49], v[0:1], v[28:29] op_sel:[0,1] op_sel_hi:[1,0] neg_hi:[0,1]
	v_pk_add_f32 v[30:31], v[30:31], v[26:27] op_sel:[0,1] op_sel_hi:[1,0] neg_lo:[0,1]
	v_pk_add_f32 v[34:35], v[34:35], v[44:45] op_sel:[0,1] op_sel_hi:[1,0] neg_lo:[0,1]
	v_pk_add_f32 v[46:47], v[32:33], v[46:47] op_sel:[0,1] op_sel_hi:[1,0] neg_lo:[0,1]
	v_pk_add_f32 v[28:29], v[0:1], v[28:29] op_sel:[0,1] op_sel_hi:[1,0] neg_lo:[0,1]
	v_pk_mul_f32 v[0:1], v[8:9], v[232:233] op_sel:[0,1] op_sel_hi:[1,1]
	v_pk_mul_f32 v[32:33], v[14:15], v[234:235] op_sel:[0,1] op_sel_hi:[1,1]
	v_pk_fma_f32 v[8:9], v[8:9], v[232:233], v[0:1] op_sel:[0,0,1] op_sel_hi:[1,0,0] neg_lo:[0,0,1]
	v_pk_mul_f32 v[0:1], v[18:19], v[208:209] op_sel:[0,1] op_sel_hi:[1,1]
	v_pk_fma_f32 v[32:33], v[14:15], v[234:235], v[32:33] op_sel:[0,0,1] op_sel_hi:[1,0,0] neg_lo:[0,0,1]
	v_pk_mul_f32 v[14:15], v[20:21], v[210:211] op_sel:[0,1] op_sel_hi:[1,1]
	v_pk_fma_f32 v[18:19], v[18:19], v[208:209], v[0:1] op_sel:[0,0,1] op_sel_hi:[1,0,0] neg_lo:[0,0,1]
	v_pk_mul_f32 v[0:1], v[12:13], v[204:205] op_sel:[0,1] op_sel_hi:[1,1]
	v_pk_fma_f32 v[14:15], v[20:21], v[210:211], v[14:15] op_sel:[0,0,1] op_sel_hi:[1,0,0] neg_lo:[0,0,1]
	v_pk_mul_f32 v[20:21], v[38:39], v[206:207] op_sel:[0,1] op_sel_hi:[1,1]
	v_pk_fma_f32 v[12:13], v[12:13], v[204:205], v[0:1] op_sel:[0,0,1] op_sel_hi:[1,0,0] neg_lo:[0,0,1]
	v_pk_mul_f32 v[0:1], v[48:49], v[200:201] op_sel:[0,1] op_sel_hi:[1,1]
	v_pk_fma_f32 v[38:39], v[38:39], v[206:207], v[20:21] op_sel:[0,0,1] op_sel_hi:[1,0,0] neg_lo:[0,0,1]
	v_pk_mul_f32 v[20:21], v[42:43], v[202:203] op_sel:[0,1] op_sel_hi:[1,1]
	v_pk_fma_f32 v[0:1], v[48:49], v[200:201], v[0:1] op_sel:[0,0,1] op_sel_hi:[1,0,0] neg_lo:[0,0,1]
	v_pk_mul_f32 v[48:49], v[40:41], v[196:197] op_sel:[0,1] op_sel_hi:[1,1]
	v_pk_fma_f32 v[20:21], v[42:43], v[202:203], v[20:21] op_sel:[0,0,1] op_sel_hi:[1,0,0] neg_lo:[0,0,1]
	v_pk_mul_f32 v[42:43], v[2:3], v[198:199] op_sel:[0,1] op_sel_hi:[1,1]
	v_pk_fma_f32 v[40:41], v[40:41], v[196:197], v[48:49] op_sel:[0,0,1] op_sel_hi:[1,0,0] neg_lo:[0,0,1]
	v_pk_mul_f32 v[48:49], v[10:11], v[192:193] op_sel:[0,1] op_sel_hi:[1,1]
	v_pk_fma_f32 v[42:43], v[2:3], v[198:199], v[42:43] op_sel:[0,0,1] op_sel_hi:[1,0,0] neg_lo:[0,0,1]
	v_pk_mul_f32 v[2:3], v[30:31], v[194:195] op_sel:[0,1] op_sel_hi:[1,1]
	v_pk_fma_f32 v[48:49], v[10:11], v[192:193], v[48:49] op_sel:[0,0,1] op_sel_hi:[1,0,0] neg_lo:[0,0,1]
	v_pk_mul_f32 v[10:11], v[34:35], v[188:189] op_sel:[0,1] op_sel_hi:[1,1]
	v_pk_fma_f32 v[30:31], v[30:31], v[194:195], v[2:3] op_sel:[0,0,1] op_sel_hi:[1,0,0] neg_lo:[0,0,1]
	v_pk_mul_f32 v[2:3], v[46:47], v[190:191] op_sel:[0,1] op_sel_hi:[1,1]
	v_pk_fma_f32 v[10:11], v[34:35], v[188:189], v[10:11] op_sel:[0,0,1] op_sel_hi:[1,0,0] neg_lo:[0,0,1]
	v_pk_mul_f32 v[34:35], v[28:29], v[186:187] op_sel:[0,1] op_sel_hi:[1,1]
	v_pk_fma_f32 v[46:47], v[46:47], v[190:191], v[2:3] op_sel:[0,0,1] op_sel_hi:[1,0,0] neg_lo:[0,0,1]
	v_pk_fma_f32 v[28:29], v[28:29], v[186:187], v[34:35] op_sel:[0,0,1] op_sel_hi:[1,0,0] neg_lo:[0,0,1]
	ds_write_b64 v176, v[4:5] offset:0
	ds_write_b64 v176, v[8:9] offset:32
	ds_write_b64 v176, v[32:33] offset:64
	ds_write_b64 v176, v[18:19] offset:96
	ds_write_b64 v176, v[14:15] offset:128
	ds_write_b64 v176, v[12:13] offset:160
	ds_write_b64 v176, v[38:39] offset:192
	ds_write_b64 v176, v[0:1] offset:224
	ds_write_b64 v176, v[20:21] offset:256
	ds_write_b64 v176, v[40:41] offset:288
	ds_write_b64 v176, v[42:43] offset:320
	ds_write_b64 v176, v[48:49] offset:352
	ds_write_b64 v176, v[30:31] offset:384
	ds_write_b64 v176, v[10:11] offset:416
	ds_write_b64 v176, v[46:47] offset:448
	ds_write_b64 v176, v[28:29] offset:480
	s_cbranch_scc1 .LBB0_948
	s_waitcnt lgkmcnt(0)
	s_barrier
	s_mov_b32 s0, 0
	v_mov_b32_e32 v0, v36
